# speedup vs baseline: 1.0049x; 1.0049x over previous
; #define STAGE(Pp, BASE, br, kt) do { const u16* _g = (BASE) + ((long)(br) * K + (long)(kt) * BK); \
;     __builtin_amdgcn_global_load_lds((const unsigned*)(_g + voff0), (unsigned*)((char*)(Pp) + tb16), 16, 0, 0); \
;     __builtin_amdgcn_global_load_lds((const unsigned*)(_g + voff1), (unsigned*)((char*)(Pp) + tb16 + 8192), 16, 0, 0); } while (0)
; #define LDA(dst, b, h) _Pragma("unroll") for (int m = 0; m < 4; ++m) _Pragma("unroll") for (int k = 0; k < 2; ++k) \
;     dst[m][k] = *reinterpret_cast<const bf16x8*>((const char*)shm + aB + (((b) * 2 + (h)) * 16384 + (m * 2 + k) * 1024))
; #define LDB(dst, b, h) _Pragma("unroll") for (int n = 0; n < 2; ++n) _Pragma("unroll") for (int k = 0; k < 2; ++k) \
;     dst[n][k] = *reinterpret_cast<const bf16x8*>((const char*)shm + bB + (((b) * 2 + (h)) * 16384 + (n * 2 + k) * 1024))
; #define WAIT_V(n) asm volatile("s_waitcnt vmcnt(" #n ")" ::: "memory")
; #define WAIT_L(n) asm volatile("s_waitcnt lgkmcnt(" #n ")" ::: "memory")
; #define BAR __builtin_amdgcn_s_barrier()
; #define SCHED __builtin_amdgcn_sched_barrier(0)
; template <int MODE> ...
;     ...
;     STAGE(SB(0, 0), Bt, bcol, 0); STAGE(SA(0, 0), A, brow, 0); STAGE(SB(0, 1), Bt, bcol + HALF, 0); STAGE(SA(0, 1), A, brow + HALF, 0);
;     STAGE(SB(1, 0), Bt, bcol, 1); STAGE(SA(1, 0), A, brow, 1); STAGE(SB(1, 1), Bt, bcol + HALF, 1);
;     WAIT_V(6);
;     if (wr == 1) BAR;
;     BAR;
;     for (int t = 0; t < nt - 2; t += 2) {
;       LDB(B0, 0, 0); LDB(B1, 0, 1); LDA(At, 0, 0); STAGE(SA(1, 1), A, brow + HALF, t + 1);
;       WAIT_L(0); BAR; MMA2(0, 0, 0, 1); BAR; SCHED;
;       LDA(At, 0, 1); STAGE(SB(0, 0), Bt, bcol, t + 2); STAGE(SB(0, 1), Bt, bcol + HALF, t + 2); STAGE(SA(0, 0), A, brow, t + 2);
;       WAIT_V(6); WAIT_L(0); BAR; MMA2(1, 0, 1, 1); BAR; SCHED;
.LBB0_154:
	v_readfirstlane_b32 s71, v167
	s_mov_b32 m0, s71
	ds_read_b128 v[170:173], v149
	ds_read_b128 v[174:177], v149 offset:1024
	ds_read_b128 v[178:181], v149 offset:2048
	ds_read_b128 v[182:185], v149 offset:3072
	ds_read_b128 v[186:189], v149 offset:16384
	ds_read_b128 v[190:193], v149 offset:17408
	ds_read_b128 v[194:197], v149 offset:18432
	ds_read_b128 v[198:201], v149 offset:19456
	ds_read_b128 v[202:205], v151
	ds_read_b128 v[206:209], v151 offset:1024
	ds_read_b128 v[210:213], v151 offset:2048
	ds_read_b128 v[214:217], v151 offset:3072
	ds_read_b128 v[218:221], v151 offset:4096
	ds_read_b128 v[222:225], v151 offset:5120
	ds_read_b128 v[226:229], v151 offset:6144
	ds_read_b128 v[230:233], v151 offset:7168
	s_add_u32 s88, s74, s40
	s_addc_u32 s89, s75, s41
	global_load_lds_dwordx4 v142, s[88:89]
	v_readfirstlane_b32 s71, v168
	s_mov_b32 m0, s71
	s_nop 0
	s_add_u32 s90, s74, s40
	s_addc_u32 s91, s75, s41
	global_load_lds_dwordx4 v144, s[90:91]
	s_waitcnt lgkmcnt(0)
	s_barrier
	s_setprio 1
	s_waitcnt lgkmcnt(0)
	v_mfma_f32_16x16x32_bf16 v[124:127], v[202:205], v[170:173], v[124:127]
	v_mfma_f32_16x16x32_bf16 v[120:123], v[202:205], v[178:181], v[120:123]
	v_mfma_f32_16x16x32_bf16 v[116:119], v[210:213], v[170:173], v[116:119]
	v_mfma_f32_16x16x32_bf16 v[112:115], v[210:213], v[178:181], v[112:115]
	v_mfma_f32_16x16x32_bf16 v[108:111], v[218:221], v[170:173], v[108:111]
	v_mfma_f32_16x16x32_bf16 v[104:107], v[218:221], v[178:181], v[104:107]
	v_mfma_f32_16x16x32_bf16 v[100:103], v[226:229], v[170:173], v[100:103]
	v_mfma_f32_16x16x32_bf16 v[96:99], v[226:229], v[178:181], v[96:99]
	v_mfma_f32_16x16x32_bf16 v[92:95], v[202:205], v[186:189], v[92:95]
	v_mfma_f32_16x16x32_bf16 v[88:91], v[202:205], v[194:197], v[88:91]
	v_mfma_f32_16x16x32_bf16 v[84:87], v[210:213], v[186:189], v[84:87]
	v_mfma_f32_16x16x32_bf16 v[80:83], v[210:213], v[194:197], v[80:83]
	v_mfma_f32_16x16x32_bf16 v[76:79], v[218:221], v[186:189], v[76:79]
	v_mfma_f32_16x16x32_bf16 v[72:75], v[218:221], v[194:197], v[72:75]
	v_mfma_f32_16x16x32_bf16 v[68:71], v[226:229], v[186:189], v[68:71]
	v_mfma_f32_16x16x32_bf16 v[64:67], v[226:229], v[194:197], v[64:67]
	v_mfma_f32_16x16x32_bf16 v[124:127], v[206:209], v[174:177], v[124:127]
	v_mfma_f32_16x16x32_bf16 v[120:123], v[206:209], v[182:185], v[120:123]
	v_mfma_f32_16x16x32_bf16 v[116:119], v[214:217], v[174:177], v[116:119]
	v_mfma_f32_16x16x32_bf16 v[112:115], v[214:217], v[182:185], v[112:115]
	v_mfma_f32_16x16x32_bf16 v[108:111], v[222:225], v[174:177], v[108:111]
	v_mfma_f32_16x16x32_bf16 v[104:107], v[222:225], v[182:185], v[104:107]
	v_mfma_f32_16x16x32_bf16 v[100:103], v[230:233], v[174:177], v[100:103]
	v_mfma_f32_16x16x32_bf16 v[96:99], v[230:233], v[182:185], v[96:99]
	v_mfma_f32_16x16x32_bf16 v[92:95], v[206:209], v[190:193], v[92:95]
	v_mfma_f32_16x16x32_bf16 v[88:91], v[206:209], v[198:201], v[88:91]
	v_mfma_f32_16x16x32_bf16 v[84:87], v[214:217], v[190:193], v[84:87]
	v_mfma_f32_16x16x32_bf16 v[80:83], v[214:217], v[198:201], v[80:83]
	v_mfma_f32_16x16x32_bf16 v[76:79], v[222:225], v[190:193], v[76:79]
	v_mfma_f32_16x16x32_bf16 v[72:75], v[222:225], v[198:201], v[72:75]
	v_mfma_f32_16x16x32_bf16 v[68:71], v[230:233], v[190:193], v[68:71]
	v_mfma_f32_16x16x32_bf16 v[64:67], v[230:233], v[198:201], v[64:67]
	s_setprio 0
	s_barrier
	v_readfirstlane_b32 s71, v153
	s_mov_b32 m0, s71
	ds_read_b128 v[202:205], v151 offset:16384
	ds_read_b128 v[206:209], v151 offset:17408
	ds_read_b128 v[210:213], v151 offset:18432
	ds_read_b128 v[214:217], v151 offset:19456
	ds_read_b128 v[218:221], v151 offset:20480
	ds_read_b128 v[222:225], v151 offset:21504
	ds_read_b128 v[226:229], v151 offset:22528
	ds_read_b128 v[230:233], v151 offset:23552
	s_add_u32 s92, s74, s42
	s_addc_u32 s93, s75, s43
	global_load_lds_dwordx4 v138, s[92:93]
	v_readfirstlane_b32 s71, v154
	s_mov_b32 m0, s71
	v_readfirstlane_b32 s71, v156
	s_add_u32 s96, s74, s42
	s_addc_u32 s97, s75, s43
	global_load_lds_dwordx4 v140, s[96:97]
	s_mov_b32 m0, s71
	v_readfirstlane_b32 s71, v157
	s_add_u32 s88, s74, s44
	s_addc_u32 s89, s75, s45
	global_load_lds_dwordx4 v138, s[88:89]
	s_mov_b32 m0, s71
	v_readfirstlane_b32 s71, v152
	s_add_u32 s90, s74, s44
	s_addc_u32 s91, s75, s45
	global_load_lds_dwordx4 v140, s[90:91]
	s_mov_b32 m0, s71
	v_readfirstlane_b32 s71, v155
	s_add_u32 s92, s74, s48
	s_addc_u32 s93, s75, s49
	global_load_lds_dwordx4 v142, s[92:93]
	s_mov_b32 m0, s71
	s_nop 0
	s_add_u32 s96, s74, s48
	s_addc_u32 s97, s75, s49
	global_load_lds_dwordx4 v144, s[96:97]
	s_waitcnt vmcnt(6)
	s_waitcnt lgkmcnt(0)
	s_barrier
; #define STAGE(Pp, BASE, br, kt) do { const u16* _g = (BASE) + ((long)(br) * K + (long)(kt) * BK); \
;     __builtin_amdgcn_global_load_lds((const unsigned*)(_g + voff0), (unsigned*)((char*)(Pp) + tb16), 16, 0, 0); \
;     __builtin_amdgcn_global_load_lds((const unsigned*)(_g + voff1), (unsigned*)((char*)(Pp) + tb16 + 8192), 16, 0, 0); } while (0)
; #define LDA(dst, b, h) _Pragma("unroll") for (int m = 0; m < 4; ++m) _Pragma("unroll") for (int k = 0; k < 2; ++k) \
;     dst[m][k] = *reinterpret_cast<const bf16x8*>((const char*)shm + aB + (((b) * 2 + (h)) * 16384 + (m * 2 + k) * 1024))
; #define LDB(dst, b, h) _Pragma("unroll") for (int n = 0; n < 2; ++n) _Pragma("unroll") for (int k = 0; k < 2; ++k) \
;     dst[n][k] = *reinterpret_cast<const bf16x8*>((const char*)shm + bB + (((b) * 2 + (h)) * 16384 + (n * 2 + k) * 1024))
; #define WAIT_V(n) asm volatile("s_waitcnt vmcnt(" #n ")" ::: "memory")
; #define WAIT_L(n) asm volatile("s_waitcnt lgkmcnt(" #n ")" ::: "memory")
; #define BAR __builtin_amdgcn_s_barrier()
; #define SCHED __builtin_amdgcn_sched_barrier(0)
; template <int MODE> ...
;     ...
;     STAGE(SB(0, 0), Bt, bcol, 0); STAGE(SA(0, 0), A, brow, 0); STAGE(SB(0, 1), Bt, bcol + HALF, 0); STAGE(SA(0, 1), A, brow + HALF, 0);
;     STAGE(SB(1, 0), Bt, bcol, 1); STAGE(SA(1, 0), A, brow, 1); STAGE(SB(1, 1), Bt, bcol + HALF, 1);
;     WAIT_V(6);
;     if (wr == 1) BAR;
;     BAR;
;     for (int t = 0; t < nt - 2; t += 2) {
;       LDB(B0, 0, 0); LDB(B1, 0, 1); LDA(At, 0, 0); STAGE(SA(1, 1), A, brow + HALF, t + 1);
;       WAIT_L(0); BAR; MMA2(0, 0, 0, 1); BAR; SCHED;
;       LDA(At, 0, 1); STAGE(SB(0, 0), Bt, bcol, t + 2); STAGE(SB(0, 1), Bt, bcol + HALF, t + 2); STAGE(SA(0, 0), A, brow, t + 2);
;       WAIT_V(6); WAIT_L(0); BAR; MMA2(1, 0, 1, 1); BAR; SCHED;
;       LDB(B0, 1, 0); LDB(B1, 1, 1); LDA(At, 1, 0); STAGE(SA(0, 1), A, brow + HALF, t + 2);
;       WAIT_L(0); BAR; MMA2(0, 0, 0, 1); BAR; SCHED;
	s_setprio 1
	s_waitcnt lgkmcnt(0)
	v_mfma_f32_16x16x32_bf16 v[60:63], v[202:205], v[170:173], v[60:63]
	v_mfma_f32_16x16x32_bf16 v[56:59], v[202:205], v[178:181], v[56:59]
	v_mfma_f32_16x16x32_bf16 v[52:55], v[210:213], v[170:173], v[52:55]
	v_mfma_f32_16x16x32_bf16 v[48:51], v[210:213], v[178:181], v[48:51]
	v_mfma_f32_16x16x32_bf16 v[44:47], v[218:221], v[170:173], v[44:47]
	v_mfma_f32_16x16x32_bf16 v[40:43], v[218:221], v[178:181], v[40:43]
	v_mfma_f32_16x16x32_bf16 v[36:39], v[226:229], v[170:173], v[36:39]
	v_mfma_f32_16x16x32_bf16 v[32:35], v[226:229], v[178:181], v[32:35]
	v_mfma_f32_16x16x32_bf16 v[28:31], v[202:205], v[186:189], v[28:31]
	v_mfma_f32_16x16x32_bf16 v[24:27], v[202:205], v[194:197], v[24:27]
	v_mfma_f32_16x16x32_bf16 v[20:23], v[210:213], v[186:189], v[20:23]
	v_mfma_f32_16x16x32_bf16 v[16:19], v[210:213], v[194:197], v[16:19]
	v_mfma_f32_16x16x32_bf16 v[12:15], v[218:221], v[186:189], v[12:15]
	v_mfma_f32_16x16x32_bf16 v[8:11], v[218:221], v[194:197], v[8:11]
	v_mfma_f32_16x16x32_bf16 v[4:7], v[226:229], v[186:189], v[4:7]
	v_mfma_f32_16x16x32_bf16 v[0:3], v[226:229], v[194:197], v[0:3]
	v_mfma_f32_16x16x32_bf16 v[60:63], v[206:209], v[174:177], v[60:63]
	v_mfma_f32_16x16x32_bf16 v[56:59], v[206:209], v[182:185], v[56:59]
	v_mfma_f32_16x16x32_bf16 v[52:55], v[214:217], v[174:177], v[52:55]
	v_mfma_f32_16x16x32_bf16 v[48:51], v[214:217], v[182:185], v[48:51]
	v_mfma_f32_16x16x32_bf16 v[44:47], v[222:225], v[174:177], v[44:47]
	v_mfma_f32_16x16x32_bf16 v[40:43], v[222:225], v[182:185], v[40:43]
	v_mfma_f32_16x16x32_bf16 v[36:39], v[230:233], v[174:177], v[36:39]
	v_mfma_f32_16x16x32_bf16 v[32:35], v[230:233], v[182:185], v[32:35]
	v_mfma_f32_16x16x32_bf16 v[28:31], v[206:209], v[190:193], v[28:31]
	v_mfma_f32_16x16x32_bf16 v[24:27], v[206:209], v[198:201], v[24:27]
	v_mfma_f32_16x16x32_bf16 v[20:23], v[214:217], v[190:193], v[20:23]
	v_mfma_f32_16x16x32_bf16 v[16:19], v[214:217], v[198:201], v[16:19]
	v_mfma_f32_16x16x32_bf16 v[12:15], v[222:225], v[190:193], v[12:15]
	v_mfma_f32_16x16x32_bf16 v[8:11], v[222:225], v[198:201], v[8:11]
	v_mfma_f32_16x16x32_bf16 v[4:7], v[230:233], v[190:193], v[4:7]
	v_mfma_f32_16x16x32_bf16 v[0:3], v[230:233], v[198:201], v[0:3]
	s_setprio 0
	s_barrier
	v_readfirstlane_b32 s71, v158
	s_mov_b32 m0, s71
	v_readfirstlane_b32 s71, v159
	ds_read_b128 v[170:173], v149 offset:32768
	ds_read_b128 v[174:177], v149 offset:33792
	ds_read_b128 v[178:181], v149 offset:34816
	ds_read_b128 v[182:185], v149 offset:35840
	ds_read_b128 v[186:189], v149 offset:49152
	ds_read_b128 v[190:193], v149 offset:50176
	ds_read_b128 v[194:197], v149 offset:51200
	ds_read_b128 v[198:201], v149 offset:52224
	ds_read_b128 v[202:205], v151 offset:32768
	ds_read_b128 v[206:209], v151 offset:33792
	ds_read_b128 v[210:213], v151 offset:34816
	ds_read_b128 v[214:217], v151 offset:35840
	ds_read_b128 v[218:221], v151 offset:36864
	ds_read_b128 v[222:225], v151 offset:37888
	ds_read_b128 v[226:229], v151 offset:38912
	ds_read_b128 v[230:233], v151 offset:39936
	s_add_u32 s88, s74, s50
	s_addc_u32 s89, s75, s51
	global_load_lds_dwordx4 v142, s[88:89]
	s_mov_b32 m0, s71
	s_nop 0
	s_add_u32 s90, s74, s50
	s_addc_u32 s91, s75, s51
	global_load_lds_dwordx4 v144, s[90:91]
	s_waitcnt lgkmcnt(0)
	s_barrier
	s_setprio 1
	s_waitcnt lgkmcnt(0)
	v_mfma_f32_16x16x32_bf16 v[124:127], v[202:205], v[170:173], v[124:127]
	v_mfma_f32_16x16x32_bf16 v[120:123], v[202:205], v[178:181], v[120:123]
	v_mfma_f32_16x16x32_bf16 v[116:119], v[210:213], v[170:173], v[116:119]
	v_mfma_f32_16x16x32_bf16 v[112:115], v[210:213], v[178:181], v[112:115]
	v_mfma_f32_16x16x32_bf16 v[108:111], v[218:221], v[170:173], v[108:111]
	v_mfma_f32_16x16x32_bf16 v[104:107], v[218:221], v[178:181], v[104:107]
	v_mfma_f32_16x16x32_bf16 v[100:103], v[226:229], v[170:173], v[100:103]
	v_mfma_f32_16x16x32_bf16 v[96:99], v[226:229], v[178:181], v[96:99]
	v_mfma_f32_16x16x32_bf16 v[92:95], v[202:205], v[186:189], v[92:95]
	v_mfma_f32_16x16x32_bf16 v[88:91], v[202:205], v[194:197], v[88:91]
	v_mfma_f32_16x16x32_bf16 v[84:87], v[210:213], v[186:189], v[84:87]
	v_mfma_f32_16x16x32_bf16 v[80:83], v[210:213], v[194:197], v[80:83]
	v_mfma_f32_16x16x32_bf16 v[76:79], v[218:221], v[186:189], v[76:79]
	v_mfma_f32_16x16x32_bf16 v[72:75], v[218:221], v[194:197], v[72:75]
	v_mfma_f32_16x16x32_bf16 v[68:71], v[226:229], v[186:189], v[68:71]
	v_mfma_f32_16x16x32_bf16 v[64:67], v[226:229], v[194:197], v[64:67]
	v_mfma_f32_16x16x32_bf16 v[124:127], v[206:209], v[174:177], v[124:127]
	v_mfma_f32_16x16x32_bf16 v[120:123], v[206:209], v[182:185], v[120:123]
	v_mfma_f32_16x16x32_bf16 v[116:119], v[214:217], v[174:177], v[116:119]
	v_mfma_f32_16x16x32_bf16 v[112:115], v[214:217], v[182:185], v[112:115]
	v_mfma_f32_16x16x32_bf16 v[108:111], v[222:225], v[174:177], v[108:111]
	v_mfma_f32_16x16x32_bf16 v[104:107], v[222:225], v[182:185], v[104:107]
	v_mfma_f32_16x16x32_bf16 v[100:103], v[230:233], v[174:177], v[100:103]
	v_mfma_f32_16x16x32_bf16 v[96:99], v[230:233], v[182:185], v[96:99]
	v_mfma_f32_16x16x32_bf16 v[92:95], v[206:209], v[190:193], v[92:95]
	v_mfma_f32_16x16x32_bf16 v[88:91], v[206:209], v[198:201], v[88:91]
	v_mfma_f32_16x16x32_bf16 v[84:87], v[214:217], v[190:193], v[84:87]
	v_mfma_f32_16x16x32_bf16 v[80:83], v[214:217], v[198:201], v[80:83]
	v_mfma_f32_16x16x32_bf16 v[76:79], v[222:225], v[190:193], v[76:79]
	v_mfma_f32_16x16x32_bf16 v[72:75], v[222:225], v[198:201], v[72:75]
	v_mfma_f32_16x16x32_bf16 v[68:71], v[230:233], v[190:193], v[68:71]
	v_mfma_f32_16x16x32_bf16 v[64:67], v[230:233], v[198:201], v[64:67]
	s_setprio 0
	s_barrier
; #define STAGE(Pp, BASE, br, kt) do { const u16* _g = (BASE) + ((long)(br) * K + (long)(kt) * BK); \
;     __builtin_amdgcn_global_load_lds((const unsigned*)(_g + voff0), (unsigned*)((char*)(Pp) + tb16), 16, 0, 0); \
;     __builtin_amdgcn_global_load_lds((const unsigned*)(_g + voff1), (unsigned*)((char*)(Pp) + tb16 + 8192), 16, 0, 0); } while (0)
; #define LDA(dst, b, h) _Pragma("unroll") for (int m = 0; m < 4; ++m) _Pragma("unroll") for (int k = 0; k < 2; ++k) \
;     dst[m][k] = *reinterpret_cast<const bf16x8*>((const char*)shm + aB + (((b) * 2 + (h)) * 16384 + (m * 2 + k) * 1024))
; #define LDB(dst, b, h) _Pragma("unroll") for (int n = 0; n < 2; ++n) _Pragma("unroll") for (int k = 0; k < 2; ++k) \
;     dst[n][k] = *reinterpret_cast<const bf16x8*>((const char*)shm + bB + (((b) * 2 + (h)) * 16384 + (n * 2 + k) * 1024))
; #define WAIT_V(n) asm volatile("s_waitcnt vmcnt(" #n ")" ::: "memory")
; #define WAIT_L(n) asm volatile("s_waitcnt lgkmcnt(" #n ")" ::: "memory")
; #define BAR __builtin_amdgcn_s_barrier()
; #define SCHED __builtin_amdgcn_sched_barrier(0)
; template <int MODE> ...
;     ...
;     STAGE(SB(0, 0), Bt, bcol, 0); STAGE(SA(0, 0), A, brow, 0); STAGE(SB(0, 1), Bt, bcol + HALF, 0); STAGE(SA(0, 1), A, brow + HALF, 0);
;     STAGE(SB(1, 0), Bt, bcol, 1); STAGE(SA(1, 0), A, brow, 1); STAGE(SB(1, 1), Bt, bcol + HALF, 1);
;     WAIT_V(6);
;     if (wr == 1) BAR;
;     BAR;
;     for (int t = 0; t < nt - 2; t += 2) {
;       LDB(B0, 0, 0); LDB(B1, 0, 1); LDA(At, 0, 0); STAGE(SA(1, 1), A, brow + HALF, t + 1);
;       WAIT_L(0); BAR; MMA2(0, 0, 0, 1); BAR; SCHED;
;       LDA(At, 0, 1); STAGE(SB(0, 0), Bt, bcol, t + 2); STAGE(SB(0, 1), Bt, bcol + HALF, t + 2); STAGE(SA(0, 0), A, brow, t + 2);
;       WAIT_V(6); WAIT_L(0); BAR; MMA2(1, 0, 1, 1); BAR; SCHED;
;       LDB(B0, 1, 0); LDB(B1, 1, 1); LDA(At, 1, 0); STAGE(SA(0, 1), A, brow + HALF, t + 2);
;       WAIT_L(0); BAR; MMA2(0, 0, 0, 1); BAR; SCHED;
;       LDA(At, 1, 1); STAGE(SB(1, 0), Bt, bcol, t + 3); STAGE(SB(1, 1), Bt, bcol + HALF, t + 3); STAGE(SA(1, 0), A, brow, t + 3);
;       WAIT_V(6); WAIT_L(0); BAR; MMA2(1, 0, 1, 1); BAR; SCHED;
;     }
;     {
;       LDB(B0, 0, 0); LDB(B1, 0, 1); LDA(At, 0, 0); STAGE(SA(1, 1), A, brow + HALF, nt - 1);
	v_readfirstlane_b32 s71, v160
	s_mov_b32 m0, s71
	v_readfirstlane_b32 s71, v161
	ds_read_b128 v[202:205], v151 offset:49152
	ds_read_b128 v[206:209], v151 offset:50176
	ds_read_b128 v[210:213], v151 offset:51200
	ds_read_b128 v[214:217], v151 offset:52224
	ds_read_b128 v[218:221], v151 offset:53248
	ds_read_b128 v[222:225], v151 offset:54272
	ds_read_b128 v[226:229], v151 offset:55296
	ds_read_b128 v[230:233], v151 offset:56320
	s_add_u32 s92, s74, s60
	s_addc_u32 s93, s75, s61
	global_load_lds_dwordx4 v138, s[92:93]
	s_mov_b32 m0, s71
	v_readfirstlane_b32 s71, v165
	s_add_u32 s96, s74, s60
	s_addc_u32 s97, s75, s61
	global_load_lds_dwordx4 v140, s[96:97]
	s_mov_b32 m0, s71
	v_readfirstlane_b32 s71, v166
	s_add_u32 s88, s74, s62
	s_addc_u32 s89, s75, s63
	global_load_lds_dwordx4 v138, s[88:89]
	s_mov_b32 m0, s71
	v_readfirstlane_b32 s71, v162
	s_add_u32 s90, s74, s62
	s_addc_u32 s91, s75, s63
	global_load_lds_dwordx4 v140, s[90:91]
	s_mov_b32 m0, s71
	v_readfirstlane_b32 s71, v163
	s_add_u32 s92, s74, s64
	s_addc_u32 s93, s75, s65
	global_load_lds_dwordx4 v142, s[92:93]
	s_mov_b32 m0, s71
	s_nop 0
	s_add_u32 s96, s74, s64
	s_addc_u32 s97, s75, s65
	global_load_lds_dwordx4 v144, s[96:97]
	s_waitcnt vmcnt(6)
	s_waitcnt lgkmcnt(0)
	s_barrier
	s_setprio 1
	s_waitcnt lgkmcnt(0)
	v_mfma_f32_16x16x32_bf16 v[60:63], v[202:205], v[170:173], v[60:63]
	v_mfma_f32_16x16x32_bf16 v[56:59], v[202:205], v[178:181], v[56:59]
	v_mfma_f32_16x16x32_bf16 v[52:55], v[210:213], v[170:173], v[52:55]
	v_mfma_f32_16x16x32_bf16 v[48:51], v[210:213], v[178:181], v[48:51]
	v_mfma_f32_16x16x32_bf16 v[44:47], v[218:221], v[170:173], v[44:47]
	v_mfma_f32_16x16x32_bf16 v[40:43], v[218:221], v[178:181], v[40:43]
	v_mfma_f32_16x16x32_bf16 v[36:39], v[226:229], v[170:173], v[36:39]
	v_mfma_f32_16x16x32_bf16 v[32:35], v[226:229], v[178:181], v[32:35]
	v_mfma_f32_16x16x32_bf16 v[28:31], v[202:205], v[186:189], v[28:31]
	v_mfma_f32_16x16x32_bf16 v[24:27], v[202:205], v[194:197], v[24:27]
	v_mfma_f32_16x16x32_bf16 v[20:23], v[210:213], v[186:189], v[20:23]
	v_mfma_f32_16x16x32_bf16 v[16:19], v[210:213], v[194:197], v[16:19]
	v_mfma_f32_16x16x32_bf16 v[12:15], v[218:221], v[186:189], v[12:15]
	v_mfma_f32_16x16x32_bf16 v[8:11], v[218:221], v[194:197], v[8:11]
	v_mfma_f32_16x16x32_bf16 v[4:7], v[226:229], v[186:189], v[4:7]
	v_mfma_f32_16x16x32_bf16 v[0:3], v[226:229], v[194:197], v[0:3]
	v_mfma_f32_16x16x32_bf16 v[60:63], v[206:209], v[174:177], v[60:63]
	v_mfma_f32_16x16x32_bf16 v[56:59], v[206:209], v[182:185], v[56:59]
	v_mfma_f32_16x16x32_bf16 v[52:55], v[214:217], v[174:177], v[52:55]
	v_mfma_f32_16x16x32_bf16 v[48:51], v[214:217], v[182:185], v[48:51]
	v_mfma_f32_16x16x32_bf16 v[44:47], v[222:225], v[174:177], v[44:47]
	v_mfma_f32_16x16x32_bf16 v[40:43], v[222:225], v[182:185], v[40:43]
	v_mfma_f32_16x16x32_bf16 v[36:39], v[230:233], v[174:177], v[36:39]
	v_mfma_f32_16x16x32_bf16 v[32:35], v[230:233], v[182:185], v[32:35]
	v_mfma_f32_16x16x32_bf16 v[28:31], v[206:209], v[190:193], v[28:31]
	v_mfma_f32_16x16x32_bf16 v[24:27], v[206:209], v[198:201], v[24:27]
	v_mfma_f32_16x16x32_bf16 v[20:23], v[214:217], v[190:193], v[20:23]
	v_mfma_f32_16x16x32_bf16 v[16:19], v[214:217], v[198:201], v[16:19]
	v_mfma_f32_16x16x32_bf16 v[12:15], v[222:225], v[190:193], v[12:15]
	v_mfma_f32_16x16x32_bf16 v[8:11], v[222:225], v[198:201], v[8:11]
	v_mfma_f32_16x16x32_bf16 v[4:7], v[230:233], v[190:193], v[4:7]
	v_mfma_f32_16x16x32_bf16 v[0:3], v[230:233], v[198:201], v[0:3]
	s_setprio 0
	s_barrier
	s_add_i32 s69, s69, 2
	s_add_u32 s74, s74, 0x100
	s_addc_u32 s75, s75, 0
	s_cmp_lt_u32 s69, 60
	s_cbranch_scc1 .LBB0_154
	s_add_u32 s72, s72, 0x1f80
	v_readfirstlane_b32 s69, v167
	s_addc_u32 s73, s73, 0
	s_mov_b32 m0, s69
	v_readfirstlane_b32 s69, v168
	ds_read_b128 v[138:141], v149
	ds_read_b128 v[142:145], v149 offset:1024
	ds_read_b128 v[170:173], v149 offset:2048
	ds_read_b128 v[174:177], v149 offset:3072
	ds_read_b128 v[178:181], v149 offset:16384
	ds_read_b128 v[182:185], v149 offset:17408
	ds_read_b128 v[186:189], v149 offset:18432
	ds_read_b128 v[190:193], v149 offset:19456
	ds_read_b128 v[194:197], v151
	ds_read_b128 v[198:201], v151 offset:1024
	ds_read_b128 v[202:205], v151 offset:2048
	ds_read_b128 v[206:209], v151 offset:3072
	ds_read_b128 v[210:213], v151 offset:4096
	ds_read_b128 v[214:217], v151 offset:5120
	ds_read_b128 v[218:221], v151 offset:6144
	ds_read_b128 v[222:225], v151 offset:7168
	global_load_lds_dwordx4 v134, s[72:73]
	s_mov_b32 m0, s69
	s_nop 0
	global_load_lds_dwordx4 v136, s[72:73]
	s_waitcnt lgkmcnt(0)
	s_barrier
; #define STAGE(Pp, BASE, br, kt) do { const u16* _g = (BASE) + ((long)(br) * K + (long)(kt) * BK); \
;     __builtin_amdgcn_global_load_lds((const unsigned*)(_g + voff0), (unsigned*)((char*)(Pp) + tb16), 16, 0, 0); \
;     __builtin_amdgcn_global_load_lds((const unsigned*)(_g + voff1), (unsigned*)((char*)(Pp) + tb16 + 8192), 16, 0, 0); } while (0)
; #define LDA(dst, b, h) _Pragma("unroll") for (int m = 0; m < 4; ++m) _Pragma("unroll") for (int k = 0; k < 2; ++k) \
;     dst[m][k] = *reinterpret_cast<const bf16x8*>((const char*)shm + aB + (((b) * 2 + (h)) * 16384 + (m * 2 + k) * 1024))
; #define LDB(dst, b, h) _Pragma("unroll") for (int n = 0; n < 2; ++n) _Pragma("unroll") for (int k = 0; k < 2; ++k) \
;     dst[n][k] = *reinterpret_cast<const bf16x8*>((const char*)shm + bB + (((b) * 2 + (h)) * 16384 + (n * 2 + k) * 1024))
; #define WAIT_V(n) asm volatile("s_waitcnt vmcnt(" #n ")" ::: "memory")
; #define WAIT_L(n) asm volatile("s_waitcnt lgkmcnt(" #n ")" ::: "memory")
; #define BAR __builtin_amdgcn_s_barrier()
; #define SCHED __builtin_amdgcn_sched_barrier(0)
; template <int MODE> ...
;     ...
;       LDB(B0, 0, 0); LDB(B1, 0, 1); LDA(At, 0, 0); STAGE(SA(1, 1), A, brow + HALF, nt - 1);
;       WAIT_L(0); BAR; MMA2(0, 0, 0, 1); BAR; SCHED;
;       LDA(At, 0, 1); WAIT_V(0); WAIT_L(0); BAR; MMA2(1, 0, 1, 1); BAR; SCHED;
;       LDB(B0, 1, 0); LDB(B1, 1, 1); LDA(At, 1, 0); WAIT_L(0); BAR; MMA2(0, 0, 0, 1); BAR; SCHED;
	s_setprio 1
	s_waitcnt lgkmcnt(0)
	v_mfma_f32_16x16x32_bf16 v[124:127], v[194:197], v[138:141], v[124:127]
	v_mfma_f32_16x16x32_bf16 v[120:123], v[194:197], v[170:173], v[120:123]
	v_mfma_f32_16x16x32_bf16 v[116:119], v[202:205], v[138:141], v[116:119]
	v_mfma_f32_16x16x32_bf16 v[112:115], v[202:205], v[170:173], v[112:115]
	v_mfma_f32_16x16x32_bf16 v[108:111], v[210:213], v[138:141], v[108:111]
	v_mfma_f32_16x16x32_bf16 v[104:107], v[210:213], v[170:173], v[104:107]
	v_mfma_f32_16x16x32_bf16 v[100:103], v[218:221], v[138:141], v[100:103]
	v_mfma_f32_16x16x32_bf16 v[96:99], v[218:221], v[170:173], v[96:99]
	v_mfma_f32_16x16x32_bf16 v[92:95], v[194:197], v[178:181], v[92:95]
	v_mfma_f32_16x16x32_bf16 v[88:91], v[194:197], v[186:189], v[88:91]
	v_mfma_f32_16x16x32_bf16 v[84:87], v[202:205], v[178:181], v[84:87]
	v_mfma_f32_16x16x32_bf16 v[80:83], v[202:205], v[186:189], v[80:83]
	v_mfma_f32_16x16x32_bf16 v[76:79], v[210:213], v[178:181], v[76:79]
	v_mfma_f32_16x16x32_bf16 v[72:75], v[210:213], v[186:189], v[72:75]
	v_mfma_f32_16x16x32_bf16 v[68:71], v[218:221], v[178:181], v[68:71]
	v_mfma_f32_16x16x32_bf16 v[64:67], v[218:221], v[186:189], v[64:67]
	v_mfma_f32_16x16x32_bf16 v[124:127], v[198:201], v[142:145], v[124:127]
	v_mfma_f32_16x16x32_bf16 v[120:123], v[198:201], v[174:177], v[120:123]
	v_mfma_f32_16x16x32_bf16 v[116:119], v[206:209], v[142:145], v[116:119]
	v_mfma_f32_16x16x32_bf16 v[112:115], v[206:209], v[174:177], v[112:115]
	v_mfma_f32_16x16x32_bf16 v[108:111], v[214:217], v[142:145], v[108:111]
	v_mfma_f32_16x16x32_bf16 v[104:107], v[214:217], v[174:177], v[104:107]
	v_mfma_f32_16x16x32_bf16 v[100:103], v[222:225], v[142:145], v[100:103]
	v_mfma_f32_16x16x32_bf16 v[96:99], v[222:225], v[174:177], v[96:99]
	v_mfma_f32_16x16x32_bf16 v[92:95], v[198:201], v[182:185], v[92:95]
	v_mfma_f32_16x16x32_bf16 v[88:91], v[198:201], v[190:193], v[88:91]
	v_mfma_f32_16x16x32_bf16 v[84:87], v[206:209], v[182:185], v[84:87]
	v_mfma_f32_16x16x32_bf16 v[80:83], v[206:209], v[190:193], v[80:83]
	v_mfma_f32_16x16x32_bf16 v[76:79], v[214:217], v[182:185], v[76:79]
	v_mfma_f32_16x16x32_bf16 v[72:75], v[214:217], v[190:193], v[72:75]
	v_mfma_f32_16x16x32_bf16 v[68:71], v[222:225], v[182:185], v[68:71]
	v_mfma_f32_16x16x32_bf16 v[64:67], v[222:225], v[190:193], v[64:67]
	s_setprio 0
	s_barrier
	ds_read_b128 v[194:197], v151 offset:16384
	ds_read_b128 v[198:201], v151 offset:17408
	ds_read_b128 v[202:205], v151 offset:18432
	ds_read_b128 v[206:209], v151 offset:19456
	ds_read_b128 v[210:213], v151 offset:20480
	ds_read_b128 v[214:217], v151 offset:21504
	ds_read_b128 v[218:221], v151 offset:22528
	ds_read_b128 v[222:225], v151 offset:23552
	s_waitcnt vmcnt(0)
	s_waitcnt lgkmcnt(0)
	s_barrier
	s_setprio 1
	s_waitcnt lgkmcnt(0)
	v_mfma_f32_16x16x32_bf16 v[56:59], v[194:197], v[170:173], v[56:59]
	v_mfma_f32_16x16x32_bf16 v[52:55], v[202:205], v[138:141], v[52:55]
	v_mfma_f32_16x16x32_bf16 v[48:51], v[202:205], v[170:173], v[48:51]
	v_mfma_f32_16x16x32_bf16 v[44:47], v[210:213], v[138:141], v[44:47]
	v_mfma_f32_16x16x32_bf16 v[40:43], v[210:213], v[170:173], v[40:43]
	v_mfma_f32_16x16x32_bf16 v[36:39], v[218:221], v[138:141], v[36:39]
	v_mfma_f32_16x16x32_bf16 v[32:35], v[218:221], v[170:173], v[32:35]
	v_mfma_f32_16x16x32_bf16 v[28:31], v[194:197], v[178:181], v[28:31]
	v_mfma_f32_16x16x32_bf16 v[24:27], v[194:197], v[186:189], v[24:27]
	v_mfma_f32_16x16x32_bf16 v[20:23], v[202:205], v[178:181], v[20:23]
	v_mfma_f32_16x16x32_bf16 v[16:19], v[202:205], v[186:189], v[16:19]
	v_mfma_f32_16x16x32_bf16 v[12:15], v[210:213], v[178:181], v[12:15]
	v_mfma_f32_16x16x32_bf16 v[8:11], v[210:213], v[186:189], v[8:11]
	v_mfma_f32_16x16x32_bf16 v[4:7], v[218:221], v[178:181], v[4:7]
	v_mfma_f32_16x16x32_bf16 v[0:3], v[218:221], v[186:189], v[0:3]
	v_mfma_f32_16x16x32_bf16 v[60:63], v[194:197], v[138:141], v[60:63]
	v_mfma_f32_16x16x32_bf16 v[56:59], v[198:201], v[174:177], v[56:59]
	v_mfma_f32_16x16x32_bf16 v[52:55], v[206:209], v[142:145], v[52:55]
	v_mfma_f32_16x16x32_bf16 v[48:51], v[206:209], v[174:177], v[48:51]
	v_mfma_f32_16x16x32_bf16 v[44:47], v[214:217], v[142:145], v[44:47]
	v_mfma_f32_16x16x32_bf16 v[40:43], v[214:217], v[174:177], v[40:43]
	v_mfma_f32_16x16x32_bf16 v[36:39], v[222:225], v[142:145], v[36:39]
	v_mfma_f32_16x16x32_bf16 v[32:35], v[222:225], v[174:177], v[32:35]
	v_mfma_f32_16x16x32_bf16 v[28:31], v[198:201], v[182:185], v[28:31]
	v_mfma_f32_16x16x32_bf16 v[24:27], v[198:201], v[190:193], v[24:27]
	v_mfma_f32_16x16x32_bf16 v[20:23], v[206:209], v[182:185], v[20:23]
	v_mfma_f32_16x16x32_bf16 v[16:19], v[206:209], v[190:193], v[16:19]
	v_mfma_f32_16x16x32_bf16 v[12:15], v[214:217], v[182:185], v[12:15]
	v_mfma_f32_16x16x32_bf16 v[8:11], v[214:217], v[190:193], v[8:11]
	v_mfma_f32_16x16x32_bf16 v[4:7], v[222:225], v[182:185], v[4:7]
	v_mfma_f32_16x16x32_bf16 v[0:3], v[222:225], v[190:193], v[0:3]
	v_mfma_f32_16x16x32_bf16 v[226:229], v[198:201], v[142:145], v[60:63]
	s_setprio 0
	s_barrier
	ds_read_b128 v[138:141], v149 offset:32768
	ds_read_b128 v[142:145], v149 offset:33792
	ds_read_b128 v[170:173], v149 offset:34816
	ds_read_b128 v[174:177], v149 offset:35840
	ds_read_b128 v[178:181], v149 offset:49152
	ds_read_b128 v[182:185], v149 offset:50176
	ds_read_b128 v[186:189], v149 offset:51200
	ds_read_b128 v[190:193], v149 offset:52224
	ds_read_b128 v[60:63], v151 offset:32768
	ds_read_b128 v[194:197], v151 offset:33792
	ds_read_b128 v[198:201], v151 offset:34816
	ds_read_b128 v[202:205], v151 offset:35840
	ds_read_b128 v[206:209], v151 offset:36864
	ds_read_b128 v[210:213], v151 offset:37888
	ds_read_b128 v[214:217], v151 offset:38912
	ds_read_b128 v[218:221], v151 offset:39936
	s_waitcnt lgkmcnt(0)
	s_barrier
; #define LDA(dst, b, h) _Pragma("unroll") for (int m = 0; m < 4; ++m) _Pragma("unroll") for (int k = 0; k < 2; ++k) \
;     dst[m][k] = *reinterpret_cast<const bf16x8*>((const char*)shm + aB + (((b) * 2 + (h)) * 16384 + (m * 2 + k) * 1024))
; #define LDB(dst, b, h) _Pragma("unroll") for (int n = 0; n < 2; ++n) _Pragma("unroll") for (int k = 0; k < 2; ++k) \
;     dst[n][k] = *reinterpret_cast<const bf16x8*>((const char*)shm + bB + (((b) * 2 + (h)) * 16384 + (n * 2 + k) * 1024))
; #define WAIT_L(n) asm volatile("s_waitcnt lgkmcnt(" #n ")" ::: "memory")
; #define BAR __builtin_amdgcn_s_barrier()
; #define SCHED __builtin_amdgcn_sched_barrier(0)
; template <int MODE> ...
;     ...
;       LDB(B0, 1, 0); LDB(B1, 1, 1); LDA(At, 1, 0); WAIT_L(0); BAR; MMA2(0, 0, 0, 1); BAR; SCHED;
;       LDA(At, 1, 1); WAIT_L(0); BAR; MMA2(1, 0, 1, 1); BAR; SCHED;
;     }
;     ...
;     if (wr == 0) BAR;
	s_setprio 1
	s_waitcnt lgkmcnt(0)
	v_mfma_f32_16x16x32_bf16 v[124:127], v[60:63], v[138:141], v[124:127]
	v_mfma_f32_16x16x32_bf16 v[120:123], v[60:63], v[170:173], v[120:123]
	v_mfma_f32_16x16x32_bf16 v[92:95], v[60:63], v[178:181], v[92:95]
	v_mfma_f32_16x16x32_bf16 v[60:63], v[60:63], v[186:189], v[88:91]
	v_mfma_f32_16x16x32_bf16 v[88:91], v[194:197], v[190:193], v[60:63]
	v_mfma_f32_16x16x32_bf16 v[60:63], v[198:201], v[178:181], v[84:87]
	v_mfma_f32_16x16x32_bf16 v[84:87], v[202:205], v[182:185], v[60:63]
	v_mfma_f32_16x16x32_bf16 v[60:63], v[198:201], v[186:189], v[80:83]
	v_mfma_f32_16x16x32_bf16 v[80:83], v[202:205], v[190:193], v[60:63]
	v_mfma_f32_16x16x32_bf16 v[60:63], v[206:209], v[178:181], v[76:79]
	v_mfma_f32_16x16x32_bf16 v[76:79], v[210:213], v[182:185], v[60:63]
	v_mfma_f32_16x16x32_bf16 v[60:63], v[206:209], v[186:189], v[72:75]
	v_mfma_f32_16x16x32_bf16 v[72:75], v[210:213], v[190:193], v[60:63]
	v_mfma_f32_16x16x32_bf16 v[60:63], v[214:217], v[178:181], v[68:71]
	v_mfma_f32_16x16x32_bf16 v[116:119], v[198:201], v[138:141], v[116:119]
	v_mfma_f32_16x16x32_bf16 v[112:115], v[198:201], v[170:173], v[112:115]
	v_mfma_f32_16x16x32_bf16 v[108:111], v[206:209], v[138:141], v[108:111]
	v_mfma_f32_16x16x32_bf16 v[104:107], v[206:209], v[170:173], v[104:107]
	v_mfma_f32_16x16x32_bf16 v[100:103], v[214:217], v[138:141], v[100:103]
	v_mfma_f32_16x16x32_bf16 v[96:99], v[214:217], v[170:173], v[96:99]
	v_mfma_f32_16x16x32_bf16 v[68:71], v[218:221], v[182:185], v[60:63]
	v_mfma_f32_16x16x32_bf16 v[60:63], v[214:217], v[186:189], v[64:67]
	v_mfma_f32_16x16x32_bf16 v[124:127], v[194:197], v[142:145], v[124:127]
	v_mfma_f32_16x16x32_bf16 v[120:123], v[194:197], v[174:177], v[120:123]
	v_mfma_f32_16x16x32_bf16 v[116:119], v[202:205], v[142:145], v[116:119]
	v_mfma_f32_16x16x32_bf16 v[112:115], v[202:205], v[174:177], v[112:115]
	v_mfma_f32_16x16x32_bf16 v[108:111], v[210:213], v[142:145], v[108:111]
	v_mfma_f32_16x16x32_bf16 v[104:107], v[210:213], v[174:177], v[104:107]
	v_mfma_f32_16x16x32_bf16 v[100:103], v[218:221], v[142:145], v[100:103]
	v_mfma_f32_16x16x32_bf16 v[96:99], v[218:221], v[174:177], v[96:99]
	v_mfma_f32_16x16x32_bf16 v[92:95], v[194:197], v[182:185], v[92:95]
	v_mfma_f32_16x16x32_bf16 v[60:63], v[218:221], v[190:193], v[60:63]
	s_setprio 0
	s_barrier
	ds_read_b128 v[194:197], v151 offset:49152
	ds_read_b128 v[198:201], v151 offset:50176
	ds_read_b128 v[202:205], v151 offset:51200
	ds_read_b128 v[206:209], v151 offset:52224
	ds_read_b128 v[210:213], v151 offset:53248
	ds_read_b128 v[214:217], v151 offset:54272
	ds_read_b128 v[218:221], v151 offset:55296
	ds_read_b128 v[222:225], v151 offset:56320
	s_waitcnt lgkmcnt(0)
	s_barrier
	s_setprio 1
	s_waitcnt lgkmcnt(0)
	v_mfma_f32_16x16x32_bf16 v[64:67], v[194:197], v[138:141], v[226:229]
	v_mfma_f32_16x16x32_bf16 v[56:59], v[194:197], v[170:173], v[56:59]
	v_mfma_f32_16x16x32_bf16 v[52:55], v[202:205], v[138:141], v[52:55]
	v_mfma_f32_16x16x32_bf16 v[48:51], v[202:205], v[170:173], v[48:51]
	v_mfma_f32_16x16x32_bf16 v[44:47], v[210:213], v[138:141], v[44:47]
	v_mfma_f32_16x16x32_bf16 v[40:43], v[210:213], v[170:173], v[40:43]
	v_mfma_f32_16x16x32_bf16 v[36:39], v[218:221], v[138:141], v[36:39]
	v_mfma_f32_16x16x32_bf16 v[32:35], v[218:221], v[170:173], v[32:35]
	v_mfma_f32_16x16x32_bf16 v[28:31], v[194:197], v[178:181], v[28:31]
	v_mfma_f32_16x16x32_bf16 v[24:27], v[194:197], v[186:189], v[24:27]
	v_mfma_f32_16x16x32_bf16 v[20:23], v[202:205], v[178:181], v[20:23]
	v_mfma_f32_16x16x32_bf16 v[16:19], v[202:205], v[186:189], v[16:19]
	v_mfma_f32_16x16x32_bf16 v[12:15], v[210:213], v[178:181], v[12:15]
	v_mfma_f32_16x16x32_bf16 v[8:11], v[210:213], v[186:189], v[8:11]
	v_mfma_f32_16x16x32_bf16 v[4:7], v[218:221], v[178:181], v[4:7]
	v_mfma_f32_16x16x32_bf16 v[0:3], v[218:221], v[186:189], v[0:3]
	v_mfma_f32_16x16x32_bf16 v[64:67], v[198:201], v[142:145], v[64:67]
	v_mfma_f32_16x16x32_bf16 v[56:59], v[198:201], v[174:177], v[56:59]
	v_mfma_f32_16x16x32_bf16 v[52:55], v[206:209], v[142:145], v[52:55]
	v_mfma_f32_16x16x32_bf16 v[48:51], v[206:209], v[174:177], v[48:51]
	v_mfma_f32_16x16x32_bf16 v[44:47], v[214:217], v[142:145], v[44:47]
	v_mfma_f32_16x16x32_bf16 v[40:43], v[214:217], v[174:177], v[40:43]
	v_mfma_f32_16x16x32_bf16 v[36:39], v[222:225], v[142:145], v[36:39]
	v_mfma_f32_16x16x32_bf16 v[32:35], v[222:225], v[174:177], v[32:35]
	v_mfma_f32_16x16x32_bf16 v[28:31], v[198:201], v[182:185], v[28:31]
	v_mfma_f32_16x16x32_bf16 v[24:27], v[198:201], v[190:193], v[24:27]
	v_mfma_f32_16x16x32_bf16 v[20:23], v[206:209], v[182:185], v[20:23]
	v_mfma_f32_16x16x32_bf16 v[16:19], v[206:209], v[190:193], v[16:19]
	v_mfma_f32_16x16x32_bf16 v[12:15], v[214:217], v[182:185], v[12:15]
	v_mfma_f32_16x16x32_bf16 v[8:11], v[214:217], v[190:193], v[8:11]
	v_mfma_f32_16x16x32_bf16 v[4:7], v[222:225], v[182:185], v[4:7]
	v_mfma_f32_16x16x32_bf16 v[0:3], v[222:225], v[190:193], v[0:3]
	s_setprio 0
	s_barrier
	s_and_saveexec_b64 s[72:73], s[6:7]
	s_cbranch_execz .LBB0_157
	s_barrier

; #define STAGE(Pp, BASE, br, kt) do { const u16* _g = (BASE) + ((long)(br) * K + (long)(kt) * BK); \
;     __builtin_amdgcn_global_load_lds((const unsigned*)(_g + voff0), (unsigned*)((char*)(Pp) + tb16), 16, 0, 0); \
;     __builtin_amdgcn_global_load_lds((const unsigned*)(_g + voff1), (unsigned*)((char*)(Pp) + tb16 + 8192), 16, 0, 0); } while (0)
; #define LDA(dst, b, h) _Pragma("unroll") for (int m = 0; m < 4; ++m) _Pragma("unroll") for (int k = 0; k < 2; ++k) \
;     dst[m][k] = *reinterpret_cast<const bf16x8*>((const char*)shm + aB + (((b) * 2 + (h)) * 16384 + (m * 2 + k) * 1024))
; #define LDB(dst, b, h) _Pragma("unroll") for (int n = 0; n < 2; ++n) _Pragma("unroll") for (int k = 0; k < 2; ++k) \
;     dst[n][k] = *reinterpret_cast<const bf16x8*>((const char*)shm + bB + (((b) * 2 + (h)) * 16384 + (n * 2 + k) * 1024))
; #define WAIT_V(n) asm volatile("s_waitcnt vmcnt(" #n ")" ::: "memory")
; #define WAIT_L(n) asm volatile("s_waitcnt lgkmcnt(" #n ")" ::: "memory")
; #define BAR __builtin_amdgcn_s_barrier()
; #define SCHED __builtin_amdgcn_sched_barrier(0)
; template <int MODE> ...
;     ...
;     STAGE(SB(0, 0), Bt, bcol, 0); STAGE(SA(0, 0), A, brow, 0); STAGE(SB(0, 1), Bt, bcol + HALF, 0); STAGE(SA(0, 1), A, brow + HALF, 0);
;     STAGE(SB(1, 0), Bt, bcol, 1); STAGE(SA(1, 0), A, brow, 1); STAGE(SB(1, 1), Bt, bcol + HALF, 1);
;     WAIT_V(6);
;     if (wr == 1) BAR;
;     BAR;
;     for (int t = 0; t < nt - 2; t += 2) {
;       LDB(B0, 0, 0); LDB(B1, 0, 1); LDA(At, 0, 0); STAGE(SA(1, 1), A, brow + HALF, t + 1);
;       WAIT_L(0); BAR; MMA2(0, 0, 0, 1); BAR; SCHED;
;       LDA(At, 0, 1); STAGE(SB(0, 0), Bt, bcol, t + 2); STAGE(SB(0, 1), Bt, bcol + HALF, t + 2); STAGE(SA(0, 0), A, brow, t + 2);
;       WAIT_V(6); WAIT_L(0); BAR; MMA2(1, 0, 1, 1); BAR; SCHED;
.LBB0_177:
	v_readfirstlane_b32 s71, v165
	s_mov_b32 m0, s71
	ds_read_b128 v[168:171], v148
	ds_read_b128 v[172:175], v148 offset:1024
	ds_read_b128 v[176:179], v148 offset:2048
	ds_read_b128 v[180:183], v148 offset:3072
	ds_read_b128 v[184:187], v148 offset:16384
	ds_read_b128 v[188:191], v148 offset:17408
	ds_read_b128 v[192:195], v148 offset:18432
	ds_read_b128 v[196:199], v148 offset:19456
	ds_read_b128 v[200:203], v147
	ds_read_b128 v[204:207], v147 offset:1024
	ds_read_b128 v[208:211], v147 offset:2048
	ds_read_b128 v[212:215], v147 offset:3072
	ds_read_b128 v[216:219], v147 offset:4096
	ds_read_b128 v[220:223], v147 offset:5120
	ds_read_b128 v[224:227], v147 offset:6144
	ds_read_b128 v[228:231], v147 offset:7168
	s_add_u32 s88, s68, s12
	s_addc_u32 s89, s69, s13
	global_load_lds_dwordx4 v142, s[88:89]
	v_readfirstlane_b32 s71, v166
	s_mov_b32 m0, s71
	s_nop 0
	s_add_u32 s90, s68, s12
	s_addc_u32 s91, s69, s13
	global_load_lds_dwordx4 v144, s[90:91]
	s_waitcnt lgkmcnt(0)
	s_barrier
	s_setprio 1
	s_waitcnt lgkmcnt(0)
	v_mfma_f32_16x16x32_bf16 v[124:127], v[200:203], v[168:171], v[124:127]
	v_mfma_f32_16x16x32_bf16 v[120:123], v[200:203], v[176:179], v[120:123]
	v_mfma_f32_16x16x32_bf16 v[116:119], v[208:211], v[168:171], v[116:119]
	v_mfma_f32_16x16x32_bf16 v[112:115], v[208:211], v[176:179], v[112:115]
	v_mfma_f32_16x16x32_bf16 v[108:111], v[216:219], v[168:171], v[108:111]
	v_mfma_f32_16x16x32_bf16 v[104:107], v[216:219], v[176:179], v[104:107]
	v_mfma_f32_16x16x32_bf16 v[100:103], v[224:227], v[168:171], v[100:103]
	v_mfma_f32_16x16x32_bf16 v[96:99], v[224:227], v[176:179], v[96:99]
	v_mfma_f32_16x16x32_bf16 v[92:95], v[200:203], v[184:187], v[92:95]
	v_mfma_f32_16x16x32_bf16 v[88:91], v[200:203], v[192:195], v[88:91]
	v_mfma_f32_16x16x32_bf16 v[84:87], v[208:211], v[184:187], v[84:87]
	v_mfma_f32_16x16x32_bf16 v[80:83], v[208:211], v[192:195], v[80:83]
	v_mfma_f32_16x16x32_bf16 v[76:79], v[216:219], v[184:187], v[76:79]
	v_mfma_f32_16x16x32_bf16 v[72:75], v[216:219], v[192:195], v[72:75]
	v_mfma_f32_16x16x32_bf16 v[68:71], v[224:227], v[184:187], v[68:71]
	v_mfma_f32_16x16x32_bf16 v[64:67], v[224:227], v[192:195], v[64:67]
	v_mfma_f32_16x16x32_bf16 v[124:127], v[204:207], v[172:175], v[124:127]
	v_mfma_f32_16x16x32_bf16 v[120:123], v[204:207], v[180:183], v[120:123]
	v_mfma_f32_16x16x32_bf16 v[116:119], v[212:215], v[172:175], v[116:119]
	v_mfma_f32_16x16x32_bf16 v[112:115], v[212:215], v[180:183], v[112:115]
	v_mfma_f32_16x16x32_bf16 v[108:111], v[220:223], v[172:175], v[108:111]
	v_mfma_f32_16x16x32_bf16 v[104:107], v[220:223], v[180:183], v[104:107]
	v_mfma_f32_16x16x32_bf16 v[100:103], v[228:231], v[172:175], v[100:103]
	v_mfma_f32_16x16x32_bf16 v[96:99], v[228:231], v[180:183], v[96:99]
	v_mfma_f32_16x16x32_bf16 v[92:95], v[204:207], v[188:191], v[92:95]
	v_mfma_f32_16x16x32_bf16 v[88:91], v[204:207], v[196:199], v[88:91]
	v_mfma_f32_16x16x32_bf16 v[84:87], v[212:215], v[188:191], v[84:87]
	v_mfma_f32_16x16x32_bf16 v[80:83], v[212:215], v[196:199], v[80:83]
	v_mfma_f32_16x16x32_bf16 v[76:79], v[220:223], v[188:191], v[76:79]
	v_mfma_f32_16x16x32_bf16 v[72:75], v[220:223], v[196:199], v[72:75]
	v_mfma_f32_16x16x32_bf16 v[68:71], v[228:231], v[188:191], v[68:71]
	v_mfma_f32_16x16x32_bf16 v[64:67], v[228:231], v[196:199], v[64:67]
	s_setprio 0
	s_barrier
	v_readfirstlane_b32 s71, v150
	s_mov_b32 m0, s71
	ds_read_b128 v[200:203], v147 offset:16384
	ds_read_b128 v[204:207], v147 offset:17408
	ds_read_b128 v[208:211], v147 offset:18432
	ds_read_b128 v[212:215], v147 offset:19456
	ds_read_b128 v[216:219], v147 offset:20480
	ds_read_b128 v[220:223], v147 offset:21504
	ds_read_b128 v[224:227], v147 offset:22528
	ds_read_b128 v[228:231], v147 offset:23552
	s_add_u32 s92, s68, s38
	s_addc_u32 s93, s69, s39
	global_load_lds_dwordx4 v138, s[92:93]
	v_readfirstlane_b32 s71, v152
	s_mov_b32 m0, s71
	v_readfirstlane_b32 s71, v154
	s_add_u32 s96, s68, s38
	s_addc_u32 s97, s69, s39
	global_load_lds_dwordx4 v140, s[96:97]
	s_mov_b32 m0, s71
	v_readfirstlane_b32 s71, v155
	s_add_u32 s88, s68, s40
	s_addc_u32 s89, s69, s41
	global_load_lds_dwordx4 v138, s[88:89]
	s_mov_b32 m0, s71
	v_readfirstlane_b32 s71, v151
	s_add_u32 s90, s68, s40
	s_addc_u32 s91, s69, s41
	global_load_lds_dwordx4 v140, s[90:91]
	s_mov_b32 m0, s71
	v_readfirstlane_b32 s71, v153
	s_add_u32 s92, s68, s42
	s_addc_u32 s93, s69, s43
	global_load_lds_dwordx4 v142, s[92:93]
	s_mov_b32 m0, s71
	s_nop 0
	s_add_u32 s96, s68, s42
	s_addc_u32 s97, s69, s43
	global_load_lds_dwordx4 v144, s[96:97]
	s_waitcnt vmcnt(6)
	s_waitcnt lgkmcnt(0)
	s_barrier
; #define STAGE(Pp, BASE, br, kt) do { const u16* _g = (BASE) + ((long)(br) * K + (long)(kt) * BK); \
;     __builtin_amdgcn_global_load_lds((const unsigned*)(_g + voff0), (unsigned*)((char*)(Pp) + tb16), 16, 0, 0); \
;     __builtin_amdgcn_global_load_lds((const unsigned*)(_g + voff1), (unsigned*)((char*)(Pp) + tb16 + 8192), 16, 0, 0); } while (0)
; #define LDA(dst, b, h) _Pragma("unroll") for (int m = 0; m < 4; ++m) _Pragma("unroll") for (int k = 0; k < 2; ++k) \
;     dst[m][k] = *reinterpret_cast<const bf16x8*>((const char*)shm + aB + (((b) * 2 + (h)) * 16384 + (m * 2 + k) * 1024))
; #define LDB(dst, b, h) _Pragma("unroll") for (int n = 0; n < 2; ++n) _Pragma("unroll") for (int k = 0; k < 2; ++k) \
;     dst[n][k] = *reinterpret_cast<const bf16x8*>((const char*)shm + bB + (((b) * 2 + (h)) * 16384 + (n * 2 + k) * 1024))
; #define WAIT_V(n) asm volatile("s_waitcnt vmcnt(" #n ")" ::: "memory")
; #define WAIT_L(n) asm volatile("s_waitcnt lgkmcnt(" #n ")" ::: "memory")
; #define BAR __builtin_amdgcn_s_barrier()
; #define SCHED __builtin_amdgcn_sched_barrier(0)
; template <int MODE> ...
;     ...
;     STAGE(SB(0, 0), Bt, bcol, 0); STAGE(SA(0, 0), A, brow, 0); STAGE(SB(0, 1), Bt, bcol + HALF, 0); STAGE(SA(0, 1), A, brow + HALF, 0);
;     STAGE(SB(1, 0), Bt, bcol, 1); STAGE(SA(1, 0), A, brow, 1); STAGE(SB(1, 1), Bt, bcol + HALF, 1);
;     WAIT_V(6);
;     if (wr == 1) BAR;
;     BAR;
;     for (int t = 0; t < nt - 2; t += 2) {
;       LDB(B0, 0, 0); LDB(B1, 0, 1); LDA(At, 0, 0); STAGE(SA(1, 1), A, brow + HALF, t + 1);
;       WAIT_L(0); BAR; MMA2(0, 0, 0, 1); BAR; SCHED;
;       LDA(At, 0, 1); STAGE(SB(0, 0), Bt, bcol, t + 2); STAGE(SB(0, 1), Bt, bcol + HALF, t + 2); STAGE(SA(0, 0), A, brow, t + 2);
;       WAIT_V(6); WAIT_L(0); BAR; MMA2(1, 0, 1, 1); BAR; SCHED;
;       LDB(B0, 1, 0); LDB(B1, 1, 1); LDA(At, 1, 0); STAGE(SA(0, 1), A, brow + HALF, t + 2);
;       WAIT_L(0); BAR; MMA2(0, 0, 0, 1); BAR; SCHED;
	s_setprio 1
	s_waitcnt lgkmcnt(0)
	v_mfma_f32_16x16x32_bf16 v[60:63], v[200:203], v[168:171], v[60:63]
	v_mfma_f32_16x16x32_bf16 v[56:59], v[200:203], v[176:179], v[56:59]
	v_mfma_f32_16x16x32_bf16 v[52:55], v[208:211], v[168:171], v[52:55]
	v_mfma_f32_16x16x32_bf16 v[48:51], v[208:211], v[176:179], v[48:51]
	v_mfma_f32_16x16x32_bf16 v[44:47], v[216:219], v[168:171], v[44:47]
	v_mfma_f32_16x16x32_bf16 v[40:43], v[216:219], v[176:179], v[40:43]
	v_mfma_f32_16x16x32_bf16 v[36:39], v[224:227], v[168:171], v[36:39]
	v_mfma_f32_16x16x32_bf16 v[32:35], v[224:227], v[176:179], v[32:35]
	v_mfma_f32_16x16x32_bf16 v[28:31], v[200:203], v[184:187], v[28:31]
	v_mfma_f32_16x16x32_bf16 v[24:27], v[200:203], v[192:195], v[24:27]
	v_mfma_f32_16x16x32_bf16 v[20:23], v[208:211], v[184:187], v[20:23]
	v_mfma_f32_16x16x32_bf16 v[16:19], v[208:211], v[192:195], v[16:19]
	v_mfma_f32_16x16x32_bf16 v[12:15], v[216:219], v[184:187], v[12:15]
	v_mfma_f32_16x16x32_bf16 v[8:11], v[216:219], v[192:195], v[8:11]
	v_mfma_f32_16x16x32_bf16 v[4:7], v[224:227], v[184:187], v[4:7]
	v_mfma_f32_16x16x32_bf16 v[0:3], v[224:227], v[192:195], v[0:3]
	v_mfma_f32_16x16x32_bf16 v[60:63], v[204:207], v[172:175], v[60:63]
	v_mfma_f32_16x16x32_bf16 v[56:59], v[204:207], v[180:183], v[56:59]
	v_mfma_f32_16x16x32_bf16 v[52:55], v[212:215], v[172:175], v[52:55]
	v_mfma_f32_16x16x32_bf16 v[48:51], v[212:215], v[180:183], v[48:51]
	v_mfma_f32_16x16x32_bf16 v[44:47], v[220:223], v[172:175], v[44:47]
	v_mfma_f32_16x16x32_bf16 v[40:43], v[220:223], v[180:183], v[40:43]
	v_mfma_f32_16x16x32_bf16 v[36:39], v[228:231], v[172:175], v[36:39]
	v_mfma_f32_16x16x32_bf16 v[32:35], v[228:231], v[180:183], v[32:35]
	v_mfma_f32_16x16x32_bf16 v[28:31], v[204:207], v[188:191], v[28:31]
	v_mfma_f32_16x16x32_bf16 v[24:27], v[204:207], v[196:199], v[24:27]
	v_mfma_f32_16x16x32_bf16 v[20:23], v[212:215], v[188:191], v[20:23]
	v_mfma_f32_16x16x32_bf16 v[16:19], v[212:215], v[196:199], v[16:19]
	v_mfma_f32_16x16x32_bf16 v[12:15], v[220:223], v[188:191], v[12:15]
	v_mfma_f32_16x16x32_bf16 v[8:11], v[220:223], v[196:199], v[8:11]
	v_mfma_f32_16x16x32_bf16 v[4:7], v[228:231], v[188:191], v[4:7]
	v_mfma_f32_16x16x32_bf16 v[0:3], v[228:231], v[196:199], v[0:3]
	s_setprio 0
	s_barrier
	v_readfirstlane_b32 s71, v156
	s_mov_b32 m0, s71
	v_readfirstlane_b32 s71, v157
	ds_read_b128 v[168:171], v148 offset:32768
	ds_read_b128 v[172:175], v148 offset:33792
	ds_read_b128 v[176:179], v148 offset:34816
	ds_read_b128 v[180:183], v148 offset:35840
	ds_read_b128 v[184:187], v148 offset:49152
	ds_read_b128 v[188:191], v148 offset:50176
	ds_read_b128 v[192:195], v148 offset:51200
	ds_read_b128 v[196:199], v148 offset:52224
	ds_read_b128 v[200:203], v147 offset:32768
	ds_read_b128 v[204:207], v147 offset:33792
	ds_read_b128 v[208:211], v147 offset:34816
	ds_read_b128 v[212:215], v147 offset:35840
	ds_read_b128 v[216:219], v147 offset:36864
	ds_read_b128 v[220:223], v147 offset:37888
	ds_read_b128 v[224:227], v147 offset:38912
	ds_read_b128 v[228:231], v147 offset:39936
	s_add_u32 s88, s68, s44
	s_addc_u32 s89, s69, s45
	global_load_lds_dwordx4 v142, s[88:89]
	s_mov_b32 m0, s71
	s_nop 0
	s_add_u32 s90, s68, s44
	s_addc_u32 s91, s69, s45
	global_load_lds_dwordx4 v144, s[90:91]
	s_waitcnt lgkmcnt(0)
	s_barrier
	s_setprio 1
	s_waitcnt lgkmcnt(0)
	v_mfma_f32_16x16x32_bf16 v[124:127], v[200:203], v[168:171], v[124:127]
	v_mfma_f32_16x16x32_bf16 v[120:123], v[200:203], v[176:179], v[120:123]
	v_mfma_f32_16x16x32_bf16 v[116:119], v[208:211], v[168:171], v[116:119]
	v_mfma_f32_16x16x32_bf16 v[112:115], v[208:211], v[176:179], v[112:115]
	v_mfma_f32_16x16x32_bf16 v[108:111], v[216:219], v[168:171], v[108:111]
	v_mfma_f32_16x16x32_bf16 v[104:107], v[216:219], v[176:179], v[104:107]
	v_mfma_f32_16x16x32_bf16 v[100:103], v[224:227], v[168:171], v[100:103]
	v_mfma_f32_16x16x32_bf16 v[96:99], v[224:227], v[176:179], v[96:99]
	v_mfma_f32_16x16x32_bf16 v[92:95], v[200:203], v[184:187], v[92:95]
	v_mfma_f32_16x16x32_bf16 v[88:91], v[200:203], v[192:195], v[88:91]
	v_mfma_f32_16x16x32_bf16 v[84:87], v[208:211], v[184:187], v[84:87]
	v_mfma_f32_16x16x32_bf16 v[80:83], v[208:211], v[192:195], v[80:83]
	v_mfma_f32_16x16x32_bf16 v[76:79], v[216:219], v[184:187], v[76:79]
	v_mfma_f32_16x16x32_bf16 v[72:75], v[216:219], v[192:195], v[72:75]
	v_mfma_f32_16x16x32_bf16 v[68:71], v[224:227], v[184:187], v[68:71]
	v_mfma_f32_16x16x32_bf16 v[64:67], v[224:227], v[192:195], v[64:67]
	v_mfma_f32_16x16x32_bf16 v[124:127], v[204:207], v[172:175], v[124:127]
	v_mfma_f32_16x16x32_bf16 v[120:123], v[204:207], v[180:183], v[120:123]
	v_mfma_f32_16x16x32_bf16 v[116:119], v[212:215], v[172:175], v[116:119]
	v_mfma_f32_16x16x32_bf16 v[112:115], v[212:215], v[180:183], v[112:115]
	v_mfma_f32_16x16x32_bf16 v[108:111], v[220:223], v[172:175], v[108:111]
	v_mfma_f32_16x16x32_bf16 v[104:107], v[220:223], v[180:183], v[104:107]
	v_mfma_f32_16x16x32_bf16 v[100:103], v[228:231], v[172:175], v[100:103]
	v_mfma_f32_16x16x32_bf16 v[96:99], v[228:231], v[180:183], v[96:99]
	v_mfma_f32_16x16x32_bf16 v[92:95], v[204:207], v[188:191], v[92:95]
	v_mfma_f32_16x16x32_bf16 v[88:91], v[204:207], v[196:199], v[88:91]
	v_mfma_f32_16x16x32_bf16 v[84:87], v[212:215], v[188:191], v[84:87]
	v_mfma_f32_16x16x32_bf16 v[80:83], v[212:215], v[196:199], v[80:83]
	v_mfma_f32_16x16x32_bf16 v[76:79], v[220:223], v[188:191], v[76:79]
	v_mfma_f32_16x16x32_bf16 v[72:75], v[220:223], v[196:199], v[72:75]
	v_mfma_f32_16x16x32_bf16 v[68:71], v[228:231], v[188:191], v[68:71]
	v_mfma_f32_16x16x32_bf16 v[64:67], v[228:231], v[196:199], v[64:67]
	s_setprio 0
	s_barrier
; #define STAGE(Pp, BASE, br, kt) do { const u16* _g = (BASE) + ((long)(br) * K + (long)(kt) * BK); \
;     __builtin_amdgcn_global_load_lds((const unsigned*)(_g + voff0), (unsigned*)((char*)(Pp) + tb16), 16, 0, 0); \
;     __builtin_amdgcn_global_load_lds((const unsigned*)(_g + voff1), (unsigned*)((char*)(Pp) + tb16 + 8192), 16, 0, 0); } while (0)
; #define LDA(dst, b, h) _Pragma("unroll") for (int m = 0; m < 4; ++m) _Pragma("unroll") for (int k = 0; k < 2; ++k) \
;     dst[m][k] = *reinterpret_cast<const bf16x8*>((const char*)shm + aB + (((b) * 2 + (h)) * 16384 + (m * 2 + k) * 1024))
; #define LDB(dst, b, h) _Pragma("unroll") for (int n = 0; n < 2; ++n) _Pragma("unroll") for (int k = 0; k < 2; ++k) \
;     dst[n][k] = *reinterpret_cast<const bf16x8*>((const char*)shm + bB + (((b) * 2 + (h)) * 16384 + (n * 2 + k) * 1024))
; #define WAIT_V(n) asm volatile("s_waitcnt vmcnt(" #n ")" ::: "memory")
; #define WAIT_L(n) asm volatile("s_waitcnt lgkmcnt(" #n ")" ::: "memory")
; #define BAR __builtin_amdgcn_s_barrier()
; #define SCHED __builtin_amdgcn_sched_barrier(0)
; template <int MODE> ...
;     ...
;     STAGE(SB(0, 0), Bt, bcol, 0); STAGE(SA(0, 0), A, brow, 0); STAGE(SB(0, 1), Bt, bcol + HALF, 0); STAGE(SA(0, 1), A, brow + HALF, 0);
;     STAGE(SB(1, 0), Bt, bcol, 1); STAGE(SA(1, 0), A, brow, 1); STAGE(SB(1, 1), Bt, bcol + HALF, 1);
;     WAIT_V(6);
;     if (wr == 1) BAR;
;     BAR;
;     for (int t = 0; t < nt - 2; t += 2) {
;       LDB(B0, 0, 0); LDB(B1, 0, 1); LDA(At, 0, 0); STAGE(SA(1, 1), A, brow + HALF, t + 1);
;       WAIT_L(0); BAR; MMA2(0, 0, 0, 1); BAR; SCHED;
;       LDA(At, 0, 1); STAGE(SB(0, 0), Bt, bcol, t + 2); STAGE(SB(0, 1), Bt, bcol + HALF, t + 2); STAGE(SA(0, 0), A, brow, t + 2);
;       WAIT_V(6); WAIT_L(0); BAR; MMA2(1, 0, 1, 1); BAR; SCHED;
;       LDB(B0, 1, 0); LDB(B1, 1, 1); LDA(At, 1, 0); STAGE(SA(0, 1), A, brow + HALF, t + 2);
;       WAIT_L(0); BAR; MMA2(0, 0, 0, 1); BAR; SCHED;
;       LDA(At, 1, 1); STAGE(SB(1, 0), Bt, bcol, t + 3); STAGE(SB(1, 1), Bt, bcol + HALF, t + 3); STAGE(SA(1, 0), A, brow, t + 3);
;       WAIT_V(6); WAIT_L(0); BAR; MMA2(1, 0, 1, 1); BAR; SCHED;
;     }
;     {
;       LDB(B0, 0, 0); LDB(B1, 0, 1); LDA(At, 0, 0); STAGE(SA(1, 1), A, brow + HALF, nt - 1);
	v_readfirstlane_b32 s71, v158
	s_mov_b32 m0, s71
	v_readfirstlane_b32 s71, v159
	ds_read_b128 v[200:203], v147 offset:49152
	ds_read_b128 v[204:207], v147 offset:50176
	ds_read_b128 v[208:211], v147 offset:51200
	ds_read_b128 v[212:215], v147 offset:52224
	ds_read_b128 v[216:219], v147 offset:53248
	ds_read_b128 v[220:223], v147 offset:54272
	ds_read_b128 v[224:227], v147 offset:55296
	ds_read_b128 v[228:231], v147 offset:56320
	s_add_u32 s92, s68, s48
	s_addc_u32 s93, s69, s49
	global_load_lds_dwordx4 v138, s[92:93]
	s_mov_b32 m0, s71
	v_readfirstlane_b32 s71, v162
	s_add_u32 s96, s68, s48
	s_addc_u32 s97, s69, s49
	global_load_lds_dwordx4 v140, s[96:97]
	s_mov_b32 m0, s71
	v_readfirstlane_b32 s71, v163
	s_add_u32 s88, s68, s50
	s_addc_u32 s89, s69, s51
	global_load_lds_dwordx4 v138, s[88:89]
	s_mov_b32 m0, s71
	v_readfirstlane_b32 s71, v160
	s_add_u32 s90, s68, s50
	s_addc_u32 s91, s69, s51
	global_load_lds_dwordx4 v140, s[90:91]
	s_mov_b32 m0, s71
	v_readfirstlane_b32 s71, v161
	s_add_u32 s92, s68, s60
	s_addc_u32 s93, s69, s61
	global_load_lds_dwordx4 v142, s[92:93]
	s_mov_b32 m0, s71
	s_nop 0
	s_add_u32 s96, s68, s60
	s_addc_u32 s97, s69, s61
	global_load_lds_dwordx4 v144, s[96:97]
	s_waitcnt vmcnt(6)
	s_waitcnt lgkmcnt(0)
	s_barrier
	s_setprio 1
	s_waitcnt lgkmcnt(0)
	v_mfma_f32_16x16x32_bf16 v[60:63], v[200:203], v[168:171], v[60:63]
	v_mfma_f32_16x16x32_bf16 v[56:59], v[200:203], v[176:179], v[56:59]
	v_mfma_f32_16x16x32_bf16 v[52:55], v[208:211], v[168:171], v[52:55]
	v_mfma_f32_16x16x32_bf16 v[48:51], v[208:211], v[176:179], v[48:51]
	v_mfma_f32_16x16x32_bf16 v[44:47], v[216:219], v[168:171], v[44:47]
	v_mfma_f32_16x16x32_bf16 v[40:43], v[216:219], v[176:179], v[40:43]
	v_mfma_f32_16x16x32_bf16 v[36:39], v[224:227], v[168:171], v[36:39]
	v_mfma_f32_16x16x32_bf16 v[32:35], v[224:227], v[176:179], v[32:35]
	v_mfma_f32_16x16x32_bf16 v[28:31], v[200:203], v[184:187], v[28:31]
	v_mfma_f32_16x16x32_bf16 v[24:27], v[200:203], v[192:195], v[24:27]
	v_mfma_f32_16x16x32_bf16 v[20:23], v[208:211], v[184:187], v[20:23]
	v_mfma_f32_16x16x32_bf16 v[16:19], v[208:211], v[192:195], v[16:19]
	v_mfma_f32_16x16x32_bf16 v[12:15], v[216:219], v[184:187], v[12:15]
	v_mfma_f32_16x16x32_bf16 v[8:11], v[216:219], v[192:195], v[8:11]
	v_mfma_f32_16x16x32_bf16 v[4:7], v[224:227], v[184:187], v[4:7]
	v_mfma_f32_16x16x32_bf16 v[0:3], v[224:227], v[192:195], v[0:3]
	v_mfma_f32_16x16x32_bf16 v[60:63], v[204:207], v[172:175], v[60:63]
	v_mfma_f32_16x16x32_bf16 v[56:59], v[204:207], v[180:183], v[56:59]
	v_mfma_f32_16x16x32_bf16 v[52:55], v[212:215], v[172:175], v[52:55]
	v_mfma_f32_16x16x32_bf16 v[48:51], v[212:215], v[180:183], v[48:51]
	v_mfma_f32_16x16x32_bf16 v[44:47], v[220:223], v[172:175], v[44:47]
	v_mfma_f32_16x16x32_bf16 v[40:43], v[220:223], v[180:183], v[40:43]
	v_mfma_f32_16x16x32_bf16 v[36:39], v[228:231], v[172:175], v[36:39]
	v_mfma_f32_16x16x32_bf16 v[32:35], v[228:231], v[180:183], v[32:35]
	v_mfma_f32_16x16x32_bf16 v[28:31], v[204:207], v[188:191], v[28:31]
	v_mfma_f32_16x16x32_bf16 v[24:27], v[204:207], v[196:199], v[24:27]
	v_mfma_f32_16x16x32_bf16 v[20:23], v[212:215], v[188:191], v[20:23]
	v_mfma_f32_16x16x32_bf16 v[16:19], v[212:215], v[196:199], v[16:19]
	v_mfma_f32_16x16x32_bf16 v[12:15], v[220:223], v[188:191], v[12:15]
	v_mfma_f32_16x16x32_bf16 v[8:11], v[220:223], v[196:199], v[8:11]
	v_mfma_f32_16x16x32_bf16 v[4:7], v[228:231], v[188:191], v[4:7]
	v_mfma_f32_16x16x32_bf16 v[0:3], v[228:231], v[196:199], v[0:3]
	s_setprio 0
	s_barrier
	s_add_i32 s70, s70, 2
	s_add_u32 s68, s68, 0x100
	s_addc_u32 s69, s69, 0
	s_cmp_lt_u32 s70, 60
	s_cbranch_scc1 .LBB0_177
	s_add_u32 s66, s66, 0x1f80
	v_readfirstlane_b32 s68, v165
	s_addc_u32 s67, s67, 0
	s_mov_b32 m0, s68
	v_readfirstlane_b32 s68, v166
	ds_read_b128 v[138:141], v148
	ds_read_b128 v[142:145], v148 offset:1024
	ds_read_b128 v[168:171], v148 offset:2048
	ds_read_b128 v[172:175], v148 offset:3072
	ds_read_b128 v[176:179], v148 offset:16384
	ds_read_b128 v[180:183], v148 offset:17408
	ds_read_b128 v[184:187], v148 offset:18432
	ds_read_b128 v[188:191], v148 offset:19456
	ds_read_b128 v[192:195], v147
	ds_read_b128 v[196:199], v147 offset:1024
	ds_read_b128 v[200:203], v147 offset:2048
	ds_read_b128 v[204:207], v147 offset:3072
	ds_read_b128 v[208:211], v147 offset:4096
	ds_read_b128 v[212:215], v147 offset:5120
	ds_read_b128 v[216:219], v147 offset:6144
	ds_read_b128 v[220:223], v147 offset:7168
	global_load_lds_dwordx4 v134, s[66:67]
	s_mov_b32 m0, s68
	s_nop 0
	global_load_lds_dwordx4 v136, s[66:67]
	s_waitcnt lgkmcnt(0)
	s_barrier
; #define STAGE(Pp, BASE, br, kt) do { const u16* _g = (BASE) + ((long)(br) * K + (long)(kt) * BK); \
;     __builtin_amdgcn_global_load_lds((const unsigned*)(_g + voff0), (unsigned*)((char*)(Pp) + tb16), 16, 0, 0); \
;     __builtin_amdgcn_global_load_lds((const unsigned*)(_g + voff1), (unsigned*)((char*)(Pp) + tb16 + 8192), 16, 0, 0); } while (0)
; #define LDA(dst, b, h) _Pragma("unroll") for (int m = 0; m < 4; ++m) _Pragma("unroll") for (int k = 0; k < 2; ++k) \
;     dst[m][k] = *reinterpret_cast<const bf16x8*>((const char*)shm + aB + (((b) * 2 + (h)) * 16384 + (m * 2 + k) * 1024))
; #define LDB(dst, b, h) _Pragma("unroll") for (int n = 0; n < 2; ++n) _Pragma("unroll") for (int k = 0; k < 2; ++k) \
;     dst[n][k] = *reinterpret_cast<const bf16x8*>((const char*)shm + bB + (((b) * 2 + (h)) * 16384 + (n * 2 + k) * 1024))
; #define WAIT_V(n) asm volatile("s_waitcnt vmcnt(" #n ")" ::: "memory")
; #define WAIT_L(n) asm volatile("s_waitcnt lgkmcnt(" #n ")" ::: "memory")
; #define BAR __builtin_amdgcn_s_barrier()
; #define SCHED __builtin_amdgcn_sched_barrier(0)
; template <int MODE> ...
;     ...
;       LDB(B0, 0, 0); LDB(B1, 0, 1); LDA(At, 0, 0); STAGE(SA(1, 1), A, brow + HALF, nt - 1);
;       WAIT_L(0); BAR; MMA2(0, 0, 0, 1); BAR; SCHED;
;       LDA(At, 0, 1); WAIT_V(0); WAIT_L(0); BAR; MMA2(1, 0, 1, 1); BAR; SCHED;
;       LDB(B0, 1, 0); LDB(B1, 1, 1); LDA(At, 1, 0); WAIT_L(0); BAR; MMA2(0, 0, 0, 1); BAR; SCHED;
	s_setprio 1
	s_waitcnt lgkmcnt(0)
	v_mfma_f32_16x16x32_bf16 v[124:127], v[192:195], v[138:141], v[124:127]
	v_mfma_f32_16x16x32_bf16 v[120:123], v[192:195], v[168:171], v[120:123]
	v_mfma_f32_16x16x32_bf16 v[116:119], v[200:203], v[138:141], v[116:119]
	v_mfma_f32_16x16x32_bf16 v[112:115], v[200:203], v[168:171], v[112:115]
	v_mfma_f32_16x16x32_bf16 v[108:111], v[208:211], v[138:141], v[108:111]
	v_mfma_f32_16x16x32_bf16 v[104:107], v[208:211], v[168:171], v[104:107]
	v_mfma_f32_16x16x32_bf16 v[100:103], v[216:219], v[138:141], v[100:103]
	v_mfma_f32_16x16x32_bf16 v[96:99], v[216:219], v[168:171], v[96:99]
	v_mfma_f32_16x16x32_bf16 v[92:95], v[192:195], v[176:179], v[92:95]
	v_mfma_f32_16x16x32_bf16 v[88:91], v[192:195], v[184:187], v[88:91]
	v_mfma_f32_16x16x32_bf16 v[84:87], v[200:203], v[176:179], v[84:87]
	v_mfma_f32_16x16x32_bf16 v[80:83], v[200:203], v[184:187], v[80:83]
	v_mfma_f32_16x16x32_bf16 v[76:79], v[208:211], v[176:179], v[76:79]
	v_mfma_f32_16x16x32_bf16 v[72:75], v[208:211], v[184:187], v[72:75]
	v_mfma_f32_16x16x32_bf16 v[68:71], v[216:219], v[176:179], v[68:71]
	v_mfma_f32_16x16x32_bf16 v[64:67], v[216:219], v[184:187], v[64:67]
	v_mfma_f32_16x16x32_bf16 v[124:127], v[196:199], v[142:145], v[124:127]
	v_mfma_f32_16x16x32_bf16 v[120:123], v[196:199], v[172:175], v[120:123]
	v_mfma_f32_16x16x32_bf16 v[116:119], v[204:207], v[142:145], v[116:119]
	v_mfma_f32_16x16x32_bf16 v[112:115], v[204:207], v[172:175], v[112:115]
	v_mfma_f32_16x16x32_bf16 v[108:111], v[212:215], v[142:145], v[108:111]
	v_mfma_f32_16x16x32_bf16 v[104:107], v[212:215], v[172:175], v[104:107]
	v_mfma_f32_16x16x32_bf16 v[100:103], v[220:223], v[142:145], v[100:103]
	v_mfma_f32_16x16x32_bf16 v[96:99], v[220:223], v[172:175], v[96:99]
	v_mfma_f32_16x16x32_bf16 v[92:95], v[196:199], v[180:183], v[92:95]
	v_mfma_f32_16x16x32_bf16 v[88:91], v[196:199], v[188:191], v[88:91]
	v_mfma_f32_16x16x32_bf16 v[84:87], v[204:207], v[180:183], v[84:87]
	v_mfma_f32_16x16x32_bf16 v[80:83], v[204:207], v[188:191], v[80:83]
	v_mfma_f32_16x16x32_bf16 v[76:79], v[212:215], v[180:183], v[76:79]
	v_mfma_f32_16x16x32_bf16 v[72:75], v[212:215], v[188:191], v[72:75]
	v_mfma_f32_16x16x32_bf16 v[68:71], v[220:223], v[180:183], v[68:71]
	v_mfma_f32_16x16x32_bf16 v[64:67], v[220:223], v[188:191], v[64:67]
	s_setprio 0
	s_barrier
	ds_read_b128 v[192:195], v147 offset:16384
	ds_read_b128 v[196:199], v147 offset:17408
	ds_read_b128 v[200:203], v147 offset:18432
	ds_read_b128 v[204:207], v147 offset:19456
	ds_read_b128 v[208:211], v147 offset:20480
	ds_read_b128 v[212:215], v147 offset:21504
	ds_read_b128 v[216:219], v147 offset:22528
	ds_read_b128 v[220:223], v147 offset:23552
	s_waitcnt vmcnt(0)
	s_waitcnt lgkmcnt(0)
	s_barrier
	s_setprio 1
	s_waitcnt lgkmcnt(0)
	v_mfma_f32_16x16x32_bf16 v[56:59], v[192:195], v[168:171], v[56:59]
	v_mfma_f32_16x16x32_bf16 v[52:55], v[200:203], v[138:141], v[52:55]
	v_mfma_f32_16x16x32_bf16 v[48:51], v[200:203], v[168:171], v[48:51]
	v_mfma_f32_16x16x32_bf16 v[44:47], v[208:211], v[138:141], v[44:47]
	v_mfma_f32_16x16x32_bf16 v[40:43], v[208:211], v[168:171], v[40:43]
	v_mfma_f32_16x16x32_bf16 v[36:39], v[216:219], v[138:141], v[36:39]
	v_mfma_f32_16x16x32_bf16 v[32:35], v[216:219], v[168:171], v[32:35]
	v_mfma_f32_16x16x32_bf16 v[28:31], v[192:195], v[176:179], v[28:31]
	v_mfma_f32_16x16x32_bf16 v[24:27], v[192:195], v[184:187], v[24:27]
	v_mfma_f32_16x16x32_bf16 v[20:23], v[200:203], v[176:179], v[20:23]
	v_mfma_f32_16x16x32_bf16 v[16:19], v[200:203], v[184:187], v[16:19]
	v_mfma_f32_16x16x32_bf16 v[12:15], v[208:211], v[176:179], v[12:15]
	v_mfma_f32_16x16x32_bf16 v[8:11], v[208:211], v[184:187], v[8:11]
	v_mfma_f32_16x16x32_bf16 v[4:7], v[216:219], v[176:179], v[4:7]
	v_mfma_f32_16x16x32_bf16 v[0:3], v[216:219], v[184:187], v[0:3]
	v_mfma_f32_16x16x32_bf16 v[60:63], v[192:195], v[138:141], v[60:63]
	v_mfma_f32_16x16x32_bf16 v[56:59], v[196:199], v[172:175], v[56:59]
	v_mfma_f32_16x16x32_bf16 v[52:55], v[204:207], v[142:145], v[52:55]
	v_mfma_f32_16x16x32_bf16 v[48:51], v[204:207], v[172:175], v[48:51]
	v_mfma_f32_16x16x32_bf16 v[44:47], v[212:215], v[142:145], v[44:47]
	v_mfma_f32_16x16x32_bf16 v[40:43], v[212:215], v[172:175], v[40:43]
	v_mfma_f32_16x16x32_bf16 v[36:39], v[220:223], v[142:145], v[36:39]
	v_mfma_f32_16x16x32_bf16 v[32:35], v[220:223], v[172:175], v[32:35]
	v_mfma_f32_16x16x32_bf16 v[28:31], v[196:199], v[180:183], v[28:31]
	v_mfma_f32_16x16x32_bf16 v[24:27], v[196:199], v[188:191], v[24:27]
	v_mfma_f32_16x16x32_bf16 v[20:23], v[204:207], v[180:183], v[20:23]
	v_mfma_f32_16x16x32_bf16 v[16:19], v[204:207], v[188:191], v[16:19]
	v_mfma_f32_16x16x32_bf16 v[12:15], v[212:215], v[180:183], v[12:15]
	v_mfma_f32_16x16x32_bf16 v[8:11], v[212:215], v[188:191], v[8:11]
	v_mfma_f32_16x16x32_bf16 v[4:7], v[220:223], v[180:183], v[4:7]
	v_mfma_f32_16x16x32_bf16 v[0:3], v[220:223], v[188:191], v[0:3]
	v_mfma_f32_16x16x32_bf16 v[224:227], v[196:199], v[142:145], v[60:63]
	s_setprio 0
	s_barrier
	ds_read_b128 v[138:141], v148 offset:32768
	ds_read_b128 v[142:145], v148 offset:33792
	ds_read_b128 v[168:171], v148 offset:34816
	ds_read_b128 v[172:175], v148 offset:35840
	ds_read_b128 v[176:179], v148 offset:49152
	ds_read_b128 v[180:183], v148 offset:50176
	ds_read_b128 v[184:187], v148 offset:51200
	ds_read_b128 v[188:191], v148 offset:52224
	ds_read_b128 v[60:63], v147 offset:32768
	ds_read_b128 v[192:195], v147 offset:33792
	ds_read_b128 v[196:199], v147 offset:34816
	ds_read_b128 v[200:203], v147 offset:35840
	ds_read_b128 v[204:207], v147 offset:36864
	ds_read_b128 v[208:211], v147 offset:37888
	ds_read_b128 v[212:215], v147 offset:38912
	ds_read_b128 v[216:219], v147 offset:39936
	s_waitcnt lgkmcnt(0)
	s_barrier
; #define LDA(dst, b, h) _Pragma("unroll") for (int m = 0; m < 4; ++m) _Pragma("unroll") for (int k = 0; k < 2; ++k) \
;     dst[m][k] = *reinterpret_cast<const bf16x8*>((const char*)shm + aB + (((b) * 2 + (h)) * 16384 + (m * 2 + k) * 1024))
; #define LDB(dst, b, h) _Pragma("unroll") for (int n = 0; n < 2; ++n) _Pragma("unroll") for (int k = 0; k < 2; ++k) \
;     dst[n][k] = *reinterpret_cast<const bf16x8*>((const char*)shm + bB + (((b) * 2 + (h)) * 16384 + (n * 2 + k) * 1024))
; #define WAIT_L(n) asm volatile("s_waitcnt lgkmcnt(" #n ")" ::: "memory")
; #define BAR __builtin_amdgcn_s_barrier()
; #define SCHED __builtin_amdgcn_sched_barrier(0)
; template <int MODE> ...
;     ...
;       LDB(B0, 1, 0); LDB(B1, 1, 1); LDA(At, 1, 0); WAIT_L(0); BAR; MMA2(0, 0, 0, 1); BAR; SCHED;
;       LDA(At, 1, 1); WAIT_L(0); BAR; MMA2(1, 0, 1, 1); BAR; SCHED;
;     }
;     ...
;     if (wr == 0) BAR;
	s_setprio 1
	s_waitcnt lgkmcnt(0)
	v_mfma_f32_16x16x32_bf16 v[124:127], v[60:63], v[138:141], v[124:127]
	v_mfma_f32_16x16x32_bf16 v[120:123], v[60:63], v[168:171], v[120:123]
	v_mfma_f32_16x16x32_bf16 v[92:95], v[60:63], v[176:179], v[92:95]
	v_mfma_f32_16x16x32_bf16 v[60:63], v[60:63], v[184:187], v[88:91]
	v_mfma_f32_16x16x32_bf16 v[88:91], v[192:195], v[188:191], v[60:63]
	v_mfma_f32_16x16x32_bf16 v[60:63], v[196:199], v[176:179], v[84:87]
	v_mfma_f32_16x16x32_bf16 v[84:87], v[200:203], v[180:183], v[60:63]
	v_mfma_f32_16x16x32_bf16 v[60:63], v[196:199], v[184:187], v[80:83]
	v_mfma_f32_16x16x32_bf16 v[80:83], v[200:203], v[188:191], v[60:63]
	v_mfma_f32_16x16x32_bf16 v[60:63], v[204:207], v[176:179], v[76:79]
	v_mfma_f32_16x16x32_bf16 v[76:79], v[208:211], v[180:183], v[60:63]
	v_mfma_f32_16x16x32_bf16 v[60:63], v[204:207], v[184:187], v[72:75]
	v_mfma_f32_16x16x32_bf16 v[72:75], v[208:211], v[188:191], v[60:63]
	v_mfma_f32_16x16x32_bf16 v[60:63], v[212:215], v[176:179], v[68:71]
	v_mfma_f32_16x16x32_bf16 v[116:119], v[196:199], v[138:141], v[116:119]
	v_mfma_f32_16x16x32_bf16 v[112:115], v[196:199], v[168:171], v[112:115]
	v_mfma_f32_16x16x32_bf16 v[108:111], v[204:207], v[138:141], v[108:111]
	v_mfma_f32_16x16x32_bf16 v[104:107], v[204:207], v[168:171], v[104:107]
	v_mfma_f32_16x16x32_bf16 v[100:103], v[212:215], v[138:141], v[100:103]
	v_mfma_f32_16x16x32_bf16 v[96:99], v[212:215], v[168:171], v[96:99]
	v_mfma_f32_16x16x32_bf16 v[68:71], v[216:219], v[180:183], v[60:63]
	v_mfma_f32_16x16x32_bf16 v[60:63], v[212:215], v[184:187], v[64:67]
	v_mfma_f32_16x16x32_bf16 v[124:127], v[192:195], v[142:145], v[124:127]
	v_mfma_f32_16x16x32_bf16 v[120:123], v[192:195], v[172:175], v[120:123]
	v_mfma_f32_16x16x32_bf16 v[116:119], v[200:203], v[142:145], v[116:119]
	v_mfma_f32_16x16x32_bf16 v[112:115], v[200:203], v[172:175], v[112:115]
	v_mfma_f32_16x16x32_bf16 v[108:111], v[208:211], v[142:145], v[108:111]
	v_mfma_f32_16x16x32_bf16 v[104:107], v[208:211], v[172:175], v[104:107]
	v_mfma_f32_16x16x32_bf16 v[100:103], v[216:219], v[142:145], v[100:103]
	v_mfma_f32_16x16x32_bf16 v[96:99], v[216:219], v[172:175], v[96:99]
	v_mfma_f32_16x16x32_bf16 v[92:95], v[192:195], v[180:183], v[92:95]
	v_mfma_f32_16x16x32_bf16 v[60:63], v[216:219], v[188:191], v[60:63]
	s_setprio 0
	s_barrier
	ds_read_b128 v[192:195], v147 offset:49152
	ds_read_b128 v[196:199], v147 offset:50176
	ds_read_b128 v[200:203], v147 offset:51200
	ds_read_b128 v[204:207], v147 offset:52224
	ds_read_b128 v[208:211], v147 offset:53248
	ds_read_b128 v[212:215], v147 offset:54272
	ds_read_b128 v[216:219], v147 offset:55296
	ds_read_b128 v[220:223], v147 offset:56320
	s_waitcnt lgkmcnt(0)
	s_barrier
	s_setprio 1
	s_waitcnt lgkmcnt(0)
	v_mfma_f32_16x16x32_bf16 v[64:67], v[192:195], v[138:141], v[224:227]
	v_mfma_f32_16x16x32_bf16 v[56:59], v[192:195], v[168:171], v[56:59]
	v_mfma_f32_16x16x32_bf16 v[52:55], v[200:203], v[138:141], v[52:55]
	v_mfma_f32_16x16x32_bf16 v[48:51], v[200:203], v[168:171], v[48:51]
	v_mfma_f32_16x16x32_bf16 v[44:47], v[208:211], v[138:141], v[44:47]
	v_mfma_f32_16x16x32_bf16 v[40:43], v[208:211], v[168:171], v[40:43]
	v_mfma_f32_16x16x32_bf16 v[36:39], v[216:219], v[138:141], v[36:39]
	v_mfma_f32_16x16x32_bf16 v[32:35], v[216:219], v[168:171], v[32:35]
	v_mfma_f32_16x16x32_bf16 v[28:31], v[192:195], v[176:179], v[28:31]
	v_mfma_f32_16x16x32_bf16 v[24:27], v[192:195], v[184:187], v[24:27]
	v_mfma_f32_16x16x32_bf16 v[20:23], v[200:203], v[176:179], v[20:23]
	v_mfma_f32_16x16x32_bf16 v[16:19], v[200:203], v[184:187], v[16:19]
	v_mfma_f32_16x16x32_bf16 v[12:15], v[208:211], v[176:179], v[12:15]
	v_mfma_f32_16x16x32_bf16 v[8:11], v[208:211], v[184:187], v[8:11]
	v_mfma_f32_16x16x32_bf16 v[4:7], v[216:219], v[176:179], v[4:7]
	v_mfma_f32_16x16x32_bf16 v[0:3], v[216:219], v[184:187], v[0:3]
	v_mfma_f32_16x16x32_bf16 v[64:67], v[196:199], v[142:145], v[64:67]
	v_mfma_f32_16x16x32_bf16 v[56:59], v[196:199], v[172:175], v[56:59]
	v_mfma_f32_16x16x32_bf16 v[52:55], v[204:207], v[142:145], v[52:55]
	v_mfma_f32_16x16x32_bf16 v[48:51], v[204:207], v[172:175], v[48:51]
	v_mfma_f32_16x16x32_bf16 v[44:47], v[212:215], v[142:145], v[44:47]
	v_mfma_f32_16x16x32_bf16 v[40:43], v[212:215], v[172:175], v[40:43]
	v_mfma_f32_16x16x32_bf16 v[36:39], v[220:223], v[142:145], v[36:39]
	v_mfma_f32_16x16x32_bf16 v[32:35], v[220:223], v[172:175], v[32:35]
	v_mfma_f32_16x16x32_bf16 v[28:31], v[196:199], v[180:183], v[28:31]
	v_mfma_f32_16x16x32_bf16 v[24:27], v[196:199], v[188:191], v[24:27]
	v_mfma_f32_16x16x32_bf16 v[20:23], v[204:207], v[180:183], v[20:23]
	v_mfma_f32_16x16x32_bf16 v[16:19], v[204:207], v[188:191], v[16:19]
	v_mfma_f32_16x16x32_bf16 v[12:15], v[212:215], v[180:183], v[12:15]
	v_mfma_f32_16x16x32_bf16 v[8:11], v[212:215], v[188:191], v[8:11]
	v_mfma_f32_16x16x32_bf16 v[4:7], v[220:223], v[180:183], v[4:7]
	v_mfma_f32_16x16x32_bf16 v[0:3], v[220:223], v[188:191], v[0:3]
	s_setprio 0
	s_barrier
	s_and_saveexec_b64 s[66:67], s[6:7]
	s_cbranch_execz .LBB0_180
	s_barrier

; #define STAGE(Pp, BASE, br, kt) do { const u16* _g = (BASE) + ((long)(br) * K + (long)(kt) * BK); \
;     __builtin_amdgcn_global_load_lds((const unsigned*)(_g + voff0), (unsigned*)((char*)(Pp) + tb16), 16, 0, 0); \
;     __builtin_amdgcn_global_load_lds((const unsigned*)(_g + voff1), (unsigned*)((char*)(Pp) + tb16 + 8192), 16, 0, 0); } while (0)
; #define LDA(dst, b, h) _Pragma("unroll") for (int m = 0; m < 4; ++m) _Pragma("unroll") for (int k = 0; k < 2; ++k) \
;     dst[m][k] = *reinterpret_cast<const bf16x8*>((const char*)shm + aB + (((b) * 2 + (h)) * 16384 + (m * 2 + k) * 1024))
; #define LDB(dst, b, h) _Pragma("unroll") for (int n = 0; n < 2; ++n) _Pragma("unroll") for (int k = 0; k < 2; ++k) \
;     dst[n][k] = *reinterpret_cast<const bf16x8*>((const char*)shm + bB + (((b) * 2 + (h)) * 16384 + (n * 2 + k) * 1024))
; #define WAIT_V(n) asm volatile("s_waitcnt vmcnt(" #n ")" ::: "memory")
; #define WAIT_L(n) asm volatile("s_waitcnt lgkmcnt(" #n ")" ::: "memory")
; #define BAR __builtin_amdgcn_s_barrier()
; #define SCHED __builtin_amdgcn_sched_barrier(0)
; template <int MODE> ...
;     ...
;     STAGE(SB(0, 0), Bt, bcol, 0); STAGE(SA(0, 0), A, brow, 0); STAGE(SB(0, 1), Bt, bcol + HALF, 0); STAGE(SA(0, 1), A, brow + HALF, 0);
;     STAGE(SB(1, 0), Bt, bcol, 1); STAGE(SA(1, 0), A, brow, 1); STAGE(SB(1, 1), Bt, bcol + HALF, 1);
;     WAIT_V(6);
;     if (wr == 1) BAR;
;     BAR;
;     for (int t = 0; t < nt - 2; t += 2) {
;       LDB(B0, 0, 0); LDB(B1, 0, 1); LDA(At, 0, 0); STAGE(SA(1, 1), A, brow + HALF, t + 1);
;       WAIT_L(0); BAR; MMA2(0, 0, 0, 1); BAR; SCHED;
;       LDA(At, 0, 1); STAGE(SB(0, 0), Bt, bcol, t + 2); STAGE(SB(0, 1), Bt, bcol + HALF, t + 2); STAGE(SA(0, 0), A, brow, t + 2);
;       WAIT_V(6); WAIT_L(0); BAR; MMA2(1, 0, 1, 1); BAR; SCHED;
.LBB0_486:
	v_readfirstlane_b32 s74, v160
	s_mov_b32 m0, s74
	ds_read_b128 v[166:169], v145
	ds_read_b128 v[170:173], v145 offset:1024
	ds_read_b128 v[174:177], v145 offset:2048
	ds_read_b128 v[178:181], v145 offset:3072
	ds_read_b128 v[182:185], v145 offset:16384
	ds_read_b128 v[186:189], v145 offset:17408
	ds_read_b128 v[190:193], v145 offset:18432
	ds_read_b128 v[194:197], v145 offset:19456
	ds_read_b128 v[198:201], v144
	ds_read_b128 v[202:205], v144 offset:1024
	ds_read_b128 v[206:209], v144 offset:2048
	ds_read_b128 v[210:213], v144 offset:3072
	ds_read_b128 v[214:217], v144 offset:4096
	ds_read_b128 v[218:221], v144 offset:5120
	ds_read_b128 v[222:225], v144 offset:6144
	ds_read_b128 v[226:229], v144 offset:7168
	s_add_u32 s88, s72, s16
	s_addc_u32 s89, s73, s17
	global_load_lds_dwordx4 v140, s[88:89]
	v_readfirstlane_b32 s74, v161
	s_mov_b32 m0, s74
	s_nop 0
	s_add_u32 s90, s72, s16
	s_addc_u32 s91, s73, s17
	global_load_lds_dwordx4 v142, s[90:91]
	s_waitcnt lgkmcnt(0)
	s_barrier
	s_setprio 1
	s_waitcnt lgkmcnt(0)
	v_mfma_f32_16x16x32_bf16 v[124:127], v[198:201], v[166:169], v[124:127]
	v_mfma_f32_16x16x32_bf16 v[120:123], v[198:201], v[174:177], v[120:123]
	v_mfma_f32_16x16x32_bf16 v[116:119], v[206:209], v[166:169], v[116:119]
	v_mfma_f32_16x16x32_bf16 v[112:115], v[206:209], v[174:177], v[112:115]
	v_mfma_f32_16x16x32_bf16 v[108:111], v[214:217], v[166:169], v[108:111]
	v_mfma_f32_16x16x32_bf16 v[104:107], v[214:217], v[174:177], v[104:107]
	v_mfma_f32_16x16x32_bf16 v[100:103], v[222:225], v[166:169], v[100:103]
	v_mfma_f32_16x16x32_bf16 v[96:99], v[222:225], v[174:177], v[96:99]
	v_mfma_f32_16x16x32_bf16 v[92:95], v[198:201], v[182:185], v[92:95]
	v_mfma_f32_16x16x32_bf16 v[88:91], v[198:201], v[190:193], v[88:91]
	v_mfma_f32_16x16x32_bf16 v[84:87], v[206:209], v[182:185], v[84:87]
	v_mfma_f32_16x16x32_bf16 v[80:83], v[206:209], v[190:193], v[80:83]
	v_mfma_f32_16x16x32_bf16 v[76:79], v[214:217], v[182:185], v[76:79]
	v_mfma_f32_16x16x32_bf16 v[72:75], v[214:217], v[190:193], v[72:75]
	v_mfma_f32_16x16x32_bf16 v[68:71], v[222:225], v[182:185], v[68:71]
	v_mfma_f32_16x16x32_bf16 v[64:67], v[222:225], v[190:193], v[64:67]
	v_mfma_f32_16x16x32_bf16 v[124:127], v[202:205], v[170:173], v[124:127]
	v_mfma_f32_16x16x32_bf16 v[120:123], v[202:205], v[178:181], v[120:123]
	v_mfma_f32_16x16x32_bf16 v[116:119], v[210:213], v[170:173], v[116:119]
	v_mfma_f32_16x16x32_bf16 v[112:115], v[210:213], v[178:181], v[112:115]
	v_mfma_f32_16x16x32_bf16 v[108:111], v[218:221], v[170:173], v[108:111]
	v_mfma_f32_16x16x32_bf16 v[104:107], v[218:221], v[178:181], v[104:107]
	v_mfma_f32_16x16x32_bf16 v[100:103], v[226:229], v[170:173], v[100:103]
	v_mfma_f32_16x16x32_bf16 v[96:99], v[226:229], v[178:181], v[96:99]
	v_mfma_f32_16x16x32_bf16 v[92:95], v[202:205], v[186:189], v[92:95]
	v_mfma_f32_16x16x32_bf16 v[88:91], v[202:205], v[194:197], v[88:91]
	v_mfma_f32_16x16x32_bf16 v[84:87], v[210:213], v[186:189], v[84:87]
	v_mfma_f32_16x16x32_bf16 v[80:83], v[210:213], v[194:197], v[80:83]
	v_mfma_f32_16x16x32_bf16 v[76:79], v[218:221], v[186:189], v[76:79]
	v_mfma_f32_16x16x32_bf16 v[72:75], v[218:221], v[194:197], v[72:75]
	v_mfma_f32_16x16x32_bf16 v[68:71], v[226:229], v[186:189], v[68:71]
	v_mfma_f32_16x16x32_bf16 v[64:67], v[226:229], v[194:197], v[64:67]
	s_setprio 0
	s_barrier
	v_readfirstlane_b32 s74, v147
	s_mov_b32 m0, s74
	ds_read_b128 v[198:201], v144 offset:16384
	ds_read_b128 v[202:205], v144 offset:17408
	ds_read_b128 v[206:209], v144 offset:18432
	ds_read_b128 v[210:213], v144 offset:19456
	ds_read_b128 v[214:217], v144 offset:20480
	ds_read_b128 v[218:221], v144 offset:21504
	ds_read_b128 v[222:225], v144 offset:22528
	ds_read_b128 v[226:229], v144 offset:23552
	s_add_u32 s92, s72, s38
	s_addc_u32 s93, s73, s39
	global_load_lds_dwordx4 v136, s[92:93]
	v_readfirstlane_b32 s74, v148
	s_mov_b32 m0, s74
	v_readfirstlane_b32 s74, v150
	s_add_u32 s96, s72, s38
	s_addc_u32 s97, s73, s39
	global_load_lds_dwordx4 v138, s[96:97]
	s_mov_b32 m0, s74
	v_readfirstlane_b32 s74, v151
	s_add_u32 s88, s72, s40
	s_addc_u32 s89, s73, s41
	global_load_lds_dwordx4 v136, s[88:89]
	s_mov_b32 m0, s74
	v_readfirstlane_b32 s74, v146
	s_add_u32 s90, s72, s40
	s_addc_u32 s91, s73, s41
	global_load_lds_dwordx4 v138, s[90:91]
	s_mov_b32 m0, s74
	v_readfirstlane_b32 s74, v149
	s_add_u32 s92, s72, s42
	s_addc_u32 s93, s73, s43
	global_load_lds_dwordx4 v140, s[92:93]
	s_mov_b32 m0, s74
	s_nop 0
	s_add_u32 s96, s72, s42
	s_addc_u32 s97, s73, s43
	global_load_lds_dwordx4 v142, s[96:97]
	s_waitcnt vmcnt(6)
	s_waitcnt lgkmcnt(0)
	s_barrier
; #define STAGE(Pp, BASE, br, kt) do { const u16* _g = (BASE) + ((long)(br) * K + (long)(kt) * BK); \
;     __builtin_amdgcn_global_load_lds((const unsigned*)(_g + voff0), (unsigned*)((char*)(Pp) + tb16), 16, 0, 0); \
;     __builtin_amdgcn_global_load_lds((const unsigned*)(_g + voff1), (unsigned*)((char*)(Pp) + tb16 + 8192), 16, 0, 0); } while (0)
; #define LDA(dst, b, h) _Pragma("unroll") for (int m = 0; m < 4; ++m) _Pragma("unroll") for (int k = 0; k < 2; ++k) \
;     dst[m][k] = *reinterpret_cast<const bf16x8*>((const char*)shm + aB + (((b) * 2 + (h)) * 16384 + (m * 2 + k) * 1024))
; #define LDB(dst, b, h) _Pragma("unroll") for (int n = 0; n < 2; ++n) _Pragma("unroll") for (int k = 0; k < 2; ++k) \
;     dst[n][k] = *reinterpret_cast<const bf16x8*>((const char*)shm + bB + (((b) * 2 + (h)) * 16384 + (n * 2 + k) * 1024))
; #define WAIT_V(n) asm volatile("s_waitcnt vmcnt(" #n ")" ::: "memory")
; #define WAIT_L(n) asm volatile("s_waitcnt lgkmcnt(" #n ")" ::: "memory")
; #define BAR __builtin_amdgcn_s_barrier()
; #define SCHED __builtin_amdgcn_sched_barrier(0)
; template <int MODE> ...
;     ...
;     STAGE(SB(0, 0), Bt, bcol, 0); STAGE(SA(0, 0), A, brow, 0); STAGE(SB(0, 1), Bt, bcol + HALF, 0); STAGE(SA(0, 1), A, brow + HALF, 0);
;     STAGE(SB(1, 0), Bt, bcol, 1); STAGE(SA(1, 0), A, brow, 1); STAGE(SB(1, 1), Bt, bcol + HALF, 1);
;     WAIT_V(6);
;     if (wr == 1) BAR;
;     BAR;
;     for (int t = 0; t < nt - 2; t += 2) {
;       LDB(B0, 0, 0); LDB(B1, 0, 1); LDA(At, 0, 0); STAGE(SA(1, 1), A, brow + HALF, t + 1);
;       WAIT_L(0); BAR; MMA2(0, 0, 0, 1); BAR; SCHED;
;       LDA(At, 0, 1); STAGE(SB(0, 0), Bt, bcol, t + 2); STAGE(SB(0, 1), Bt, bcol + HALF, t + 2); STAGE(SA(0, 0), A, brow, t + 2);
;       WAIT_V(6); WAIT_L(0); BAR; MMA2(1, 0, 1, 1); BAR; SCHED;
;       LDB(B0, 1, 0); LDB(B1, 1, 1); LDA(At, 1, 0); STAGE(SA(0, 1), A, brow + HALF, t + 2);
;       WAIT_L(0); BAR; MMA2(0, 0, 0, 1); BAR; SCHED;
	s_setprio 1
	s_waitcnt lgkmcnt(0)
	v_mfma_f32_16x16x32_bf16 v[60:63], v[198:201], v[166:169], v[60:63]
	v_mfma_f32_16x16x32_bf16 v[56:59], v[198:201], v[174:177], v[56:59]
	v_mfma_f32_16x16x32_bf16 v[52:55], v[206:209], v[166:169], v[52:55]
	v_mfma_f32_16x16x32_bf16 v[48:51], v[206:209], v[174:177], v[48:51]
	v_mfma_f32_16x16x32_bf16 v[44:47], v[214:217], v[166:169], v[44:47]
	v_mfma_f32_16x16x32_bf16 v[40:43], v[214:217], v[174:177], v[40:43]
	v_mfma_f32_16x16x32_bf16 v[36:39], v[222:225], v[166:169], v[36:39]
	v_mfma_f32_16x16x32_bf16 v[32:35], v[222:225], v[174:177], v[32:35]
	v_mfma_f32_16x16x32_bf16 v[28:31], v[198:201], v[182:185], v[28:31]
	v_mfma_f32_16x16x32_bf16 v[24:27], v[198:201], v[190:193], v[24:27]
	v_mfma_f32_16x16x32_bf16 v[20:23], v[206:209], v[182:185], v[20:23]
	v_mfma_f32_16x16x32_bf16 v[16:19], v[206:209], v[190:193], v[16:19]
	v_mfma_f32_16x16x32_bf16 v[12:15], v[214:217], v[182:185], v[12:15]
	v_mfma_f32_16x16x32_bf16 v[8:11], v[214:217], v[190:193], v[8:11]
	v_mfma_f32_16x16x32_bf16 v[4:7], v[222:225], v[182:185], v[4:7]
	v_mfma_f32_16x16x32_bf16 v[0:3], v[222:225], v[190:193], v[0:3]
	v_mfma_f32_16x16x32_bf16 v[60:63], v[202:205], v[170:173], v[60:63]
	v_mfma_f32_16x16x32_bf16 v[56:59], v[202:205], v[178:181], v[56:59]
	v_mfma_f32_16x16x32_bf16 v[52:55], v[210:213], v[170:173], v[52:55]
	v_mfma_f32_16x16x32_bf16 v[48:51], v[210:213], v[178:181], v[48:51]
	v_mfma_f32_16x16x32_bf16 v[44:47], v[218:221], v[170:173], v[44:47]
	v_mfma_f32_16x16x32_bf16 v[40:43], v[218:221], v[178:181], v[40:43]
	v_mfma_f32_16x16x32_bf16 v[36:39], v[226:229], v[170:173], v[36:39]
	v_mfma_f32_16x16x32_bf16 v[32:35], v[226:229], v[178:181], v[32:35]
	v_mfma_f32_16x16x32_bf16 v[28:31], v[202:205], v[186:189], v[28:31]
	v_mfma_f32_16x16x32_bf16 v[24:27], v[202:205], v[194:197], v[24:27]
	v_mfma_f32_16x16x32_bf16 v[20:23], v[210:213], v[186:189], v[20:23]
	v_mfma_f32_16x16x32_bf16 v[16:19], v[210:213], v[194:197], v[16:19]
	v_mfma_f32_16x16x32_bf16 v[12:15], v[218:221], v[186:189], v[12:15]
	v_mfma_f32_16x16x32_bf16 v[8:11], v[218:221], v[194:197], v[8:11]
	v_mfma_f32_16x16x32_bf16 v[4:7], v[226:229], v[186:189], v[4:7]
	v_mfma_f32_16x16x32_bf16 v[0:3], v[226:229], v[194:197], v[0:3]
	s_setprio 0
	s_barrier
	v_readfirstlane_b32 s74, v152
	s_mov_b32 m0, s74
	v_readfirstlane_b32 s74, v153
	ds_read_b128 v[166:169], v145 offset:32768
	ds_read_b128 v[170:173], v145 offset:33792
	ds_read_b128 v[174:177], v145 offset:34816
	ds_read_b128 v[178:181], v145 offset:35840
	ds_read_b128 v[182:185], v145 offset:49152
	ds_read_b128 v[186:189], v145 offset:50176
	ds_read_b128 v[190:193], v145 offset:51200
	ds_read_b128 v[194:197], v145 offset:52224
	ds_read_b128 v[198:201], v144 offset:32768
	ds_read_b128 v[202:205], v144 offset:33792
	ds_read_b128 v[206:209], v144 offset:34816
	ds_read_b128 v[210:213], v144 offset:35840
	ds_read_b128 v[214:217], v144 offset:36864
	ds_read_b128 v[218:221], v144 offset:37888
	ds_read_b128 v[222:225], v144 offset:38912
	ds_read_b128 v[226:229], v144 offset:39936
	s_add_u32 s88, s72, s44
	s_addc_u32 s89, s73, s45
	global_load_lds_dwordx4 v140, s[88:89]
	s_mov_b32 m0, s74
	s_nop 0
	s_add_u32 s90, s72, s44
	s_addc_u32 s91, s73, s45
	global_load_lds_dwordx4 v142, s[90:91]
	s_waitcnt lgkmcnt(0)
	s_barrier
	s_setprio 1
	s_waitcnt lgkmcnt(0)
	v_mfma_f32_16x16x32_bf16 v[124:127], v[198:201], v[166:169], v[124:127]
	v_mfma_f32_16x16x32_bf16 v[120:123], v[198:201], v[174:177], v[120:123]
	v_mfma_f32_16x16x32_bf16 v[116:119], v[206:209], v[166:169], v[116:119]
	v_mfma_f32_16x16x32_bf16 v[112:115], v[206:209], v[174:177], v[112:115]
	v_mfma_f32_16x16x32_bf16 v[108:111], v[214:217], v[166:169], v[108:111]
	v_mfma_f32_16x16x32_bf16 v[104:107], v[214:217], v[174:177], v[104:107]
	v_mfma_f32_16x16x32_bf16 v[100:103], v[222:225], v[166:169], v[100:103]
	v_mfma_f32_16x16x32_bf16 v[96:99], v[222:225], v[174:177], v[96:99]
	v_mfma_f32_16x16x32_bf16 v[92:95], v[198:201], v[182:185], v[92:95]
	v_mfma_f32_16x16x32_bf16 v[88:91], v[198:201], v[190:193], v[88:91]
	v_mfma_f32_16x16x32_bf16 v[84:87], v[206:209], v[182:185], v[84:87]
	v_mfma_f32_16x16x32_bf16 v[80:83], v[206:209], v[190:193], v[80:83]
	v_mfma_f32_16x16x32_bf16 v[76:79], v[214:217], v[182:185], v[76:79]
	v_mfma_f32_16x16x32_bf16 v[72:75], v[214:217], v[190:193], v[72:75]
	v_mfma_f32_16x16x32_bf16 v[68:71], v[222:225], v[182:185], v[68:71]
	v_mfma_f32_16x16x32_bf16 v[64:67], v[222:225], v[190:193], v[64:67]
	v_mfma_f32_16x16x32_bf16 v[124:127], v[202:205], v[170:173], v[124:127]
	v_mfma_f32_16x16x32_bf16 v[120:123], v[202:205], v[178:181], v[120:123]
	v_mfma_f32_16x16x32_bf16 v[116:119], v[210:213], v[170:173], v[116:119]
	v_mfma_f32_16x16x32_bf16 v[112:115], v[210:213], v[178:181], v[112:115]
	v_mfma_f32_16x16x32_bf16 v[108:111], v[218:221], v[170:173], v[108:111]
	v_mfma_f32_16x16x32_bf16 v[104:107], v[218:221], v[178:181], v[104:107]
	v_mfma_f32_16x16x32_bf16 v[100:103], v[226:229], v[170:173], v[100:103]
	v_mfma_f32_16x16x32_bf16 v[96:99], v[226:229], v[178:181], v[96:99]
	v_mfma_f32_16x16x32_bf16 v[92:95], v[202:205], v[186:189], v[92:95]
	v_mfma_f32_16x16x32_bf16 v[88:91], v[202:205], v[194:197], v[88:91]
	v_mfma_f32_16x16x32_bf16 v[84:87], v[210:213], v[186:189], v[84:87]
	v_mfma_f32_16x16x32_bf16 v[80:83], v[210:213], v[194:197], v[80:83]
	v_mfma_f32_16x16x32_bf16 v[76:79], v[218:221], v[186:189], v[76:79]
	v_mfma_f32_16x16x32_bf16 v[72:75], v[218:221], v[194:197], v[72:75]
	v_mfma_f32_16x16x32_bf16 v[68:71], v[226:229], v[186:189], v[68:71]
	v_mfma_f32_16x16x32_bf16 v[64:67], v[226:229], v[194:197], v[64:67]
	s_setprio 0
	s_barrier
; #define STAGE(Pp, BASE, br, kt) do { const u16* _g = (BASE) + ((long)(br) * K + (long)(kt) * BK); \
;     __builtin_amdgcn_global_load_lds((const unsigned*)(_g + voff0), (unsigned*)((char*)(Pp) + tb16), 16, 0, 0); \
;     __builtin_amdgcn_global_load_lds((const unsigned*)(_g + voff1), (unsigned*)((char*)(Pp) + tb16 + 8192), 16, 0, 0); } while (0)
; #define LDA(dst, b, h) _Pragma("unroll") for (int m = 0; m < 4; ++m) _Pragma("unroll") for (int k = 0; k < 2; ++k) \
;     dst[m][k] = *reinterpret_cast<const bf16x8*>((const char*)shm + aB + (((b) * 2 + (h)) * 16384 + (m * 2 + k) * 1024))
; #define LDB(dst, b, h) _Pragma("unroll") for (int n = 0; n < 2; ++n) _Pragma("unroll") for (int k = 0; k < 2; ++k) \
;     dst[n][k] = *reinterpret_cast<const bf16x8*>((const char*)shm + bB + (((b) * 2 + (h)) * 16384 + (n * 2 + k) * 1024))
; #define WAIT_V(n) asm volatile("s_waitcnt vmcnt(" #n ")" ::: "memory")
; #define WAIT_L(n) asm volatile("s_waitcnt lgkmcnt(" #n ")" ::: "memory")
; #define BAR __builtin_amdgcn_s_barrier()
; #define SCHED __builtin_amdgcn_sched_barrier(0)
; template <int MODE> ...
;     ...
;     STAGE(SB(0, 0), Bt, bcol, 0); STAGE(SA(0, 0), A, brow, 0); STAGE(SB(0, 1), Bt, bcol + HALF, 0); STAGE(SA(0, 1), A, brow + HALF, 0);
;     STAGE(SB(1, 0), Bt, bcol, 1); STAGE(SA(1, 0), A, brow, 1); STAGE(SB(1, 1), Bt, bcol + HALF, 1);
;     WAIT_V(6);
;     if (wr == 1) BAR;
;     BAR;
;     for (int t = 0; t < nt - 2; t += 2) {
;       LDB(B0, 0, 0); LDB(B1, 0, 1); LDA(At, 0, 0); STAGE(SA(1, 1), A, brow + HALF, t + 1);
;       WAIT_L(0); BAR; MMA2(0, 0, 0, 1); BAR; SCHED;
;       LDA(At, 0, 1); STAGE(SB(0, 0), Bt, bcol, t + 2); STAGE(SB(0, 1), Bt, bcol + HALF, t + 2); STAGE(SA(0, 0), A, brow, t + 2);
;       WAIT_V(6); WAIT_L(0); BAR; MMA2(1, 0, 1, 1); BAR; SCHED;
;       LDB(B0, 1, 0); LDB(B1, 1, 1); LDA(At, 1, 0); STAGE(SA(0, 1), A, brow + HALF, t + 2);
;       WAIT_L(0); BAR; MMA2(0, 0, 0, 1); BAR; SCHED;
;       LDA(At, 1, 1); STAGE(SB(1, 0), Bt, bcol, t + 3); STAGE(SB(1, 1), Bt, bcol + HALF, t + 3); STAGE(SA(1, 0), A, brow, t + 3);
;       WAIT_V(6); WAIT_L(0); BAR; MMA2(1, 0, 1, 1); BAR; SCHED;
;     }
;     {
;       LDB(B0, 0, 0); LDB(B1, 0, 1); LDA(At, 0, 0); STAGE(SA(1, 1), A, brow + HALF, nt - 1);
	v_readfirstlane_b32 s74, v154
	s_mov_b32 m0, s74
	v_readfirstlane_b32 s74, v155
	ds_read_b128 v[198:201], v144 offset:49152
	ds_read_b128 v[202:205], v144 offset:50176
	ds_read_b128 v[206:209], v144 offset:51200
	ds_read_b128 v[210:213], v144 offset:52224
	ds_read_b128 v[214:217], v144 offset:53248
	ds_read_b128 v[218:221], v144 offset:54272
	ds_read_b128 v[222:225], v144 offset:55296
	ds_read_b128 v[226:229], v144 offset:56320
	s_add_u32 s92, s72, s48
	s_addc_u32 s93, s73, s49
	global_load_lds_dwordx4 v136, s[92:93]
	s_mov_b32 m0, s74
	v_readfirstlane_b32 s74, v158
	s_add_u32 s96, s72, s48
	s_addc_u32 s97, s73, s49
	global_load_lds_dwordx4 v138, s[96:97]
	s_mov_b32 m0, s74
	v_readfirstlane_b32 s74, v159
	s_add_u32 s88, s72, s50
	s_addc_u32 s89, s73, s51
	global_load_lds_dwordx4 v136, s[88:89]
	s_mov_b32 m0, s74
	v_readfirstlane_b32 s74, v156
	s_add_u32 s90, s72, s50
	s_addc_u32 s91, s73, s51
	global_load_lds_dwordx4 v138, s[90:91]
	s_mov_b32 m0, s74
	v_readfirstlane_b32 s74, v157
	s_add_u32 s92, s72, s60
	s_addc_u32 s93, s73, s61
	global_load_lds_dwordx4 v140, s[92:93]
	s_mov_b32 m0, s74
	s_nop 0
	s_add_u32 s96, s72, s60
	s_addc_u32 s97, s73, s61
	global_load_lds_dwordx4 v142, s[96:97]
	s_waitcnt vmcnt(6)
	s_waitcnt lgkmcnt(0)
	s_barrier
	s_setprio 1
	s_waitcnt lgkmcnt(0)
	v_mfma_f32_16x16x32_bf16 v[60:63], v[198:201], v[166:169], v[60:63]
	v_mfma_f32_16x16x32_bf16 v[56:59], v[198:201], v[174:177], v[56:59]
	v_mfma_f32_16x16x32_bf16 v[52:55], v[206:209], v[166:169], v[52:55]
	v_mfma_f32_16x16x32_bf16 v[48:51], v[206:209], v[174:177], v[48:51]
	v_mfma_f32_16x16x32_bf16 v[44:47], v[214:217], v[166:169], v[44:47]
	v_mfma_f32_16x16x32_bf16 v[40:43], v[214:217], v[174:177], v[40:43]
	v_mfma_f32_16x16x32_bf16 v[36:39], v[222:225], v[166:169], v[36:39]
	v_mfma_f32_16x16x32_bf16 v[32:35], v[222:225], v[174:177], v[32:35]
	v_mfma_f32_16x16x32_bf16 v[28:31], v[198:201], v[182:185], v[28:31]
	v_mfma_f32_16x16x32_bf16 v[24:27], v[198:201], v[190:193], v[24:27]
	v_mfma_f32_16x16x32_bf16 v[20:23], v[206:209], v[182:185], v[20:23]
	v_mfma_f32_16x16x32_bf16 v[16:19], v[206:209], v[190:193], v[16:19]
	v_mfma_f32_16x16x32_bf16 v[12:15], v[214:217], v[182:185], v[12:15]
	v_mfma_f32_16x16x32_bf16 v[8:11], v[214:217], v[190:193], v[8:11]
	v_mfma_f32_16x16x32_bf16 v[4:7], v[222:225], v[182:185], v[4:7]
	v_mfma_f32_16x16x32_bf16 v[0:3], v[222:225], v[190:193], v[0:3]
	v_mfma_f32_16x16x32_bf16 v[60:63], v[202:205], v[170:173], v[60:63]
	v_mfma_f32_16x16x32_bf16 v[56:59], v[202:205], v[178:181], v[56:59]
	v_mfma_f32_16x16x32_bf16 v[52:55], v[210:213], v[170:173], v[52:55]
	v_mfma_f32_16x16x32_bf16 v[48:51], v[210:213], v[178:181], v[48:51]
	v_mfma_f32_16x16x32_bf16 v[44:47], v[218:221], v[170:173], v[44:47]
	v_mfma_f32_16x16x32_bf16 v[40:43], v[218:221], v[178:181], v[40:43]
	v_mfma_f32_16x16x32_bf16 v[36:39], v[226:229], v[170:173], v[36:39]
	v_mfma_f32_16x16x32_bf16 v[32:35], v[226:229], v[178:181], v[32:35]
	v_mfma_f32_16x16x32_bf16 v[28:31], v[202:205], v[186:189], v[28:31]
	v_mfma_f32_16x16x32_bf16 v[24:27], v[202:205], v[194:197], v[24:27]
	v_mfma_f32_16x16x32_bf16 v[20:23], v[210:213], v[186:189], v[20:23]
	v_mfma_f32_16x16x32_bf16 v[16:19], v[210:213], v[194:197], v[16:19]
	v_mfma_f32_16x16x32_bf16 v[12:15], v[218:221], v[186:189], v[12:15]
	v_mfma_f32_16x16x32_bf16 v[8:11], v[218:221], v[194:197], v[8:11]
	v_mfma_f32_16x16x32_bf16 v[4:7], v[226:229], v[186:189], v[4:7]
	v_mfma_f32_16x16x32_bf16 v[0:3], v[226:229], v[194:197], v[0:3]
	s_setprio 0
	s_barrier
	s_add_i32 s63, s63, 2
	s_add_u32 s72, s72, 0x100
	s_addc_u32 s73, s73, 0
	s_cmp_lt_u32 s63, 60
	s_cbranch_scc1 .LBB0_486
	s_add_u32 s70, s70, 0x1f80
	v_readfirstlane_b32 s63, v160
	s_addc_u32 s71, s71, 0
	s_mov_b32 m0, s63
	v_readfirstlane_b32 s63, v161
	ds_read_b128 v[136:139], v145
	ds_read_b128 v[140:143], v145 offset:1024
	ds_read_b128 v[166:169], v145 offset:2048
	ds_read_b128 v[170:173], v145 offset:3072
	ds_read_b128 v[174:177], v145 offset:16384
	ds_read_b128 v[178:181], v145 offset:17408
	ds_read_b128 v[182:185], v145 offset:18432
	ds_read_b128 v[186:189], v145 offset:19456
	ds_read_b128 v[190:193], v144
	ds_read_b128 v[194:197], v144 offset:1024
	ds_read_b128 v[198:201], v144 offset:2048
	ds_read_b128 v[202:205], v144 offset:3072
	ds_read_b128 v[206:209], v144 offset:4096
	ds_read_b128 v[210:213], v144 offset:5120
	ds_read_b128 v[214:217], v144 offset:6144
	ds_read_b128 v[218:221], v144 offset:7168
	global_load_lds_dwordx4 v132, s[70:71]
	s_mov_b32 m0, s63
	s_nop 0
	global_load_lds_dwordx4 v134, s[70:71]
	s_waitcnt lgkmcnt(0)
	s_barrier
; #define STAGE(Pp, BASE, br, kt) do { const u16* _g = (BASE) + ((long)(br) * K + (long)(kt) * BK); \
;     __builtin_amdgcn_global_load_lds((const unsigned*)(_g + voff0), (unsigned*)((char*)(Pp) + tb16), 16, 0, 0); \
;     __builtin_amdgcn_global_load_lds((const unsigned*)(_g + voff1), (unsigned*)((char*)(Pp) + tb16 + 8192), 16, 0, 0); } while (0)
; #define LDA(dst, b, h) _Pragma("unroll") for (int m = 0; m < 4; ++m) _Pragma("unroll") for (int k = 0; k < 2; ++k) \
;     dst[m][k] = *reinterpret_cast<const bf16x8*>((const char*)shm + aB + (((b) * 2 + (h)) * 16384 + (m * 2 + k) * 1024))
; #define LDB(dst, b, h) _Pragma("unroll") for (int n = 0; n < 2; ++n) _Pragma("unroll") for (int k = 0; k < 2; ++k) \
;     dst[n][k] = *reinterpret_cast<const bf16x8*>((const char*)shm + bB + (((b) * 2 + (h)) * 16384 + (n * 2 + k) * 1024))
; #define WAIT_V(n) asm volatile("s_waitcnt vmcnt(" #n ")" ::: "memory")
; #define WAIT_L(n) asm volatile("s_waitcnt lgkmcnt(" #n ")" ::: "memory")
; #define BAR __builtin_amdgcn_s_barrier()
; #define SCHED __builtin_amdgcn_sched_barrier(0)
; template <int MODE> ...
;     ...
;       LDB(B0, 0, 0); LDB(B1, 0, 1); LDA(At, 0, 0); STAGE(SA(1, 1), A, brow + HALF, nt - 1);
;       WAIT_L(0); BAR; MMA2(0, 0, 0, 1); BAR; SCHED;
;       LDA(At, 0, 1); WAIT_V(0); WAIT_L(0); BAR; MMA2(1, 0, 1, 1); BAR; SCHED;
;       LDB(B0, 1, 0); LDB(B1, 1, 1); LDA(At, 1, 0); WAIT_L(0); BAR; MMA2(0, 0, 0, 1); BAR; SCHED;
	s_setprio 1
	s_waitcnt lgkmcnt(0)
	v_mfma_f32_16x16x32_bf16 v[124:127], v[190:193], v[136:139], v[124:127]
	v_mfma_f32_16x16x32_bf16 v[116:119], v[198:201], v[136:139], v[116:119]
	v_mfma_f32_16x16x32_bf16 v[108:111], v[206:209], v[136:139], v[108:111]
	v_mfma_f32_16x16x32_bf16 v[100:103], v[214:217], v[136:139], v[100:103]
	v_mfma_f32_16x16x32_bf16 v[96:99], v[214:217], v[166:169], v[96:99]
	v_mfma_f32_16x16x32_bf16 v[92:95], v[190:193], v[174:177], v[92:95]
	v_mfma_f32_16x16x32_bf16 v[88:91], v[190:193], v[182:185], v[88:91]
	v_mfma_f32_16x16x32_bf16 v[80:83], v[198:201], v[182:185], v[80:83]
	v_mfma_f32_16x16x32_bf16 v[76:79], v[206:209], v[174:177], v[76:79]
	v_mfma_f32_16x16x32_bf16 v[124:127], v[194:197], v[140:143], v[124:127]
	v_mfma_f32_16x16x32_bf16 v[120:123], v[190:193], v[166:169], v[120:123]
	v_mfma_f32_16x16x32_bf16 v[116:119], v[202:205], v[140:143], v[116:119]
	v_mfma_f32_16x16x32_bf16 v[112:115], v[198:201], v[166:169], v[112:115]
	v_mfma_f32_16x16x32_bf16 v[108:111], v[210:213], v[140:143], v[108:111]
	v_mfma_f32_16x16x32_bf16 v[104:107], v[206:209], v[166:169], v[104:107]
	v_mfma_f32_16x16x32_bf16 v[100:103], v[218:221], v[140:143], v[100:103]
	v_mfma_f32_16x16x32_bf16 v[96:99], v[218:221], v[170:173], v[96:99]
	v_mfma_f32_16x16x32_bf16 v[92:95], v[194:197], v[178:181], v[92:95]
	v_mfma_f32_16x16x32_bf16 v[88:91], v[194:197], v[186:189], v[88:91]
	v_mfma_f32_16x16x32_bf16 v[84:87], v[198:201], v[174:177], v[84:87]
	v_mfma_f32_16x16x32_bf16 v[80:83], v[202:205], v[186:189], v[80:83]
	v_mfma_f32_16x16x32_bf16 v[76:79], v[210:213], v[178:181], v[76:79]
	v_mfma_f32_16x16x32_bf16 v[72:75], v[206:209], v[182:185], v[72:75]
	v_mfma_f32_16x16x32_bf16 v[68:71], v[214:217], v[174:177], v[68:71]
	v_mfma_f32_16x16x32_bf16 v[64:67], v[214:217], v[182:185], v[64:67]
	v_mfma_f32_16x16x32_bf16 v[222:225], v[194:197], v[170:173], v[120:123]
	v_mfma_f32_16x16x32_bf16 v[226:229], v[202:205], v[170:173], v[112:115]
	v_mfma_f32_16x16x32_bf16 v[230:233], v[210:213], v[170:173], v[104:107]
	v_mfma_f32_16x16x32_bf16 v[190:193], v[202:205], v[178:181], v[84:87]
	v_mfma_f32_16x16x32_bf16 v[194:197], v[210:213], v[186:189], v[72:75]
	v_mfma_f32_16x16x32_bf16 v[198:201], v[218:221], v[178:181], v[68:71]
	v_mfma_f32_16x16x32_bf16 v[202:205], v[218:221], v[186:189], v[64:67]
	s_setprio 0
	s_barrier
	s_nop 0
	ds_read_b128 v[64:67], v144 offset:16384
	ds_read_b128 v[68:71], v144 offset:17408
	ds_read_b128 v[72:75], v144 offset:18432
	ds_read_b128 v[84:87], v144 offset:19456
	ds_read_b128 v[104:107], v144 offset:20480
	ds_read_b128 v[112:115], v144 offset:21504
	ds_read_b128 v[120:123], v144 offset:22528
	ds_read_b128 v[206:209], v144 offset:23552
	s_waitcnt vmcnt(0)
	s_waitcnt lgkmcnt(0)
	s_barrier
	s_setprio 1
	s_waitcnt lgkmcnt(0)
	v_mfma_f32_16x16x32_bf16 v[60:63], v[64:67], v[136:139], v[60:63]
	v_mfma_f32_16x16x32_bf16 v[56:59], v[64:67], v[166:169], v[56:59]
	v_mfma_f32_16x16x32_bf16 v[52:55], v[72:75], v[136:139], v[52:55]
	v_mfma_f32_16x16x32_bf16 v[48:51], v[72:75], v[166:169], v[48:51]
	v_mfma_f32_16x16x32_bf16 v[44:47], v[104:107], v[136:139], v[44:47]
	v_mfma_f32_16x16x32_bf16 v[40:43], v[104:107], v[166:169], v[40:43]
	v_mfma_f32_16x16x32_bf16 v[28:31], v[64:67], v[174:177], v[28:31]
	v_mfma_f32_16x16x32_bf16 v[24:27], v[64:67], v[182:185], v[24:27]
	v_mfma_f32_16x16x32_bf16 v[20:23], v[72:75], v[174:177], v[20:23]
	v_mfma_f32_16x16x32_bf16 v[60:63], v[68:71], v[140:143], v[60:63]
	v_mfma_f32_16x16x32_bf16 v[56:59], v[68:71], v[170:173], v[56:59]
	v_mfma_f32_16x16x32_bf16 v[52:55], v[84:87], v[140:143], v[52:55]
	v_mfma_f32_16x16x32_bf16 v[48:51], v[84:87], v[170:173], v[48:51]
	v_mfma_f32_16x16x32_bf16 v[44:47], v[112:115], v[140:143], v[44:47]
	v_mfma_f32_16x16x32_bf16 v[40:43], v[112:115], v[170:173], v[40:43]
	v_mfma_f32_16x16x32_bf16 v[36:39], v[120:123], v[136:139], v[36:39]
	v_mfma_f32_16x16x32_bf16 v[32:35], v[120:123], v[166:169], v[32:35]
	v_mfma_f32_16x16x32_bf16 v[28:31], v[68:71], v[178:181], v[28:31]
	v_mfma_f32_16x16x32_bf16 v[24:27], v[68:71], v[186:189], v[24:27]
	v_mfma_f32_16x16x32_bf16 v[20:23], v[84:87], v[178:181], v[20:23]
	v_mfma_f32_16x16x32_bf16 v[16:19], v[72:75], v[182:185], v[16:19]
	v_mfma_f32_16x16x32_bf16 v[12:15], v[104:107], v[174:177], v[12:15]
	v_mfma_f32_16x16x32_bf16 v[8:11], v[104:107], v[182:185], v[8:11]
	v_mfma_f32_16x16x32_bf16 v[4:7], v[120:123], v[174:177], v[4:7]
	v_mfma_f32_16x16x32_bf16 v[0:3], v[120:123], v[182:185], v[0:3]
	v_mfma_f32_16x16x32_bf16 v[136:139], v[206:209], v[140:143], v[36:39]
	v_mfma_f32_16x16x32_bf16 v[140:143], v[206:209], v[170:173], v[32:35]
	v_mfma_f32_16x16x32_bf16 v[166:169], v[84:87], v[186:189], v[16:19]
	v_mfma_f32_16x16x32_bf16 v[170:173], v[112:115], v[178:181], v[12:15]
	v_mfma_f32_16x16x32_bf16 v[210:213], v[112:115], v[186:189], v[8:11]
	v_mfma_f32_16x16x32_bf16 v[174:177], v[206:209], v[178:181], v[4:7]
	v_mfma_f32_16x16x32_bf16 v[178:181], v[206:209], v[186:189], v[0:3]
	s_setprio 0
	s_barrier
; #define LDA(dst, b, h) _Pragma("unroll") for (int m = 0; m < 4; ++m) _Pragma("unroll") for (int k = 0; k < 2; ++k) \
;     dst[m][k] = *reinterpret_cast<const bf16x8*>((const char*)shm + aB + (((b) * 2 + (h)) * 16384 + (m * 2 + k) * 1024))
; #define LDB(dst, b, h) _Pragma("unroll") for (int n = 0; n < 2; ++n) _Pragma("unroll") for (int k = 0; k < 2; ++k) \
;     dst[n][k] = *reinterpret_cast<const bf16x8*>((const char*)shm + bB + (((b) * 2 + (h)) * 16384 + (n * 2 + k) * 1024))
; #define WAIT_L(n) asm volatile("s_waitcnt lgkmcnt(" #n ")" ::: "memory")
; #define BAR __builtin_amdgcn_s_barrier()
; #define SCHED __builtin_amdgcn_sched_barrier(0)
; template <int MODE> ...
;     ...
;       LDB(B0, 1, 0); LDB(B1, 1, 1); LDA(At, 1, 0); WAIT_L(0); BAR; MMA2(0, 0, 0, 1); BAR; SCHED;
;       LDA(At, 1, 1); WAIT_L(0); BAR; MMA2(1, 0, 1, 1); BAR; SCHED;
;     }
;     ...
;     if (wr == 0) BAR;
	ds_read_b128 v[12:15], v145 offset:32768
	ds_read_b128 v[16:19], v145 offset:33792
	ds_read_b128 v[182:185], v145 offset:34816
	ds_read_b128 v[186:189], v145 offset:35840
	ds_read_b128 v[206:209], v145 offset:49152
	ds_read_b128 v[214:217], v145 offset:50176
	ds_read_b128 v[218:221], v145 offset:51200
	ds_read_b128 v[234:237], v145 offset:52224
	ds_read_b128 v[0:3], v144 offset:32768
	ds_read_b128 v[4:7], v144 offset:33792
	ds_read_b128 v[8:11], v144 offset:34816
	ds_read_b128 v[32:35], v144 offset:35840
	ds_read_b128 v[36:39], v144 offset:36864
	ds_read_b128 v[238:241], v144 offset:37888
	ds_read_b128 v[242:245], v144 offset:38912
	ds_read_b128 v[246:249], v144 offset:39936
	s_waitcnt lgkmcnt(0)
	s_barrier
	s_setprio 1
	s_waitcnt lgkmcnt(0)
	v_mfma_f32_16x16x32_bf16 v[64:67], v[0:3], v[12:15], v[124:127]
	v_mfma_f32_16x16x32_bf16 v[68:71], v[242:245], v[182:185], v[96:99]
	v_mfma_f32_16x16x32_bf16 v[120:123], v[4:7], v[16:19], v[64:67]
	v_mfma_f32_16x16x32_bf16 v[64:67], v[0:3], v[182:185], v[222:225]
	v_mfma_f32_16x16x32_bf16 v[84:87], v[246:249], v[186:189], v[68:71]
	v_mfma_f32_16x16x32_bf16 v[68:71], v[0:3], v[206:209], v[92:95]
	v_mfma_f32_16x16x32_bf16 v[0:3], v[0:3], v[218:221], v[88:91]
	v_mfma_f32_16x16x32_bf16 v[88:91], v[4:7], v[234:237], v[0:3]
	v_mfma_f32_16x16x32_bf16 v[0:3], v[8:11], v[206:209], v[190:193]
	v_mfma_f32_16x16x32_bf16 v[124:127], v[4:7], v[186:189], v[64:67]
	v_mfma_f32_16x16x32_bf16 v[64:67], v[8:11], v[12:15], v[116:119]
	v_mfma_f32_16x16x32_bf16 v[72:75], v[32:35], v[214:217], v[0:3]
	v_mfma_f32_16x16x32_bf16 v[0:3], v[8:11], v[218:221], v[80:83]
	v_mfma_f32_16x16x32_bf16 v[112:115], v[32:35], v[16:19], v[64:67]
	v_mfma_f32_16x16x32_bf16 v[64:67], v[8:11], v[182:185], v[226:229]
	v_mfma_f32_16x16x32_bf16 v[92:95], v[32:35], v[234:237], v[0:3]
	v_mfma_f32_16x16x32_bf16 v[0:3], v[36:39], v[206:209], v[76:79]
	v_mfma_f32_16x16x32_bf16 v[116:119], v[32:35], v[186:189], v[64:67]
	v_mfma_f32_16x16x32_bf16 v[64:67], v[36:39], v[12:15], v[108:111]
	v_mfma_f32_16x16x32_bf16 v[76:79], v[238:241], v[214:217], v[0:3]
	v_mfma_f32_16x16x32_bf16 v[0:3], v[36:39], v[218:221], v[194:197]
	v_mfma_f32_16x16x32_bf16 v[104:107], v[238:241], v[16:19], v[64:67]
	v_mfma_f32_16x16x32_bf16 v[64:67], v[36:39], v[182:185], v[230:233]
	v_mfma_f32_16x16x32_bf16 v[96:99], v[238:241], v[234:237], v[0:3]
	v_mfma_f32_16x16x32_bf16 v[0:3], v[242:245], v[206:209], v[198:201]
	v_mfma_f32_16x16x32_bf16 v[108:111], v[238:241], v[186:189], v[64:67]
	v_mfma_f32_16x16x32_bf16 v[64:67], v[242:245], v[12:15], v[100:103]
	v_mfma_f32_16x16x32_bf16 v[80:83], v[246:249], v[214:217], v[0:3]
	v_mfma_f32_16x16x32_bf16 v[0:3], v[242:245], v[218:221], v[202:205]
	v_mfma_f32_16x16x32_bf16 v[64:67], v[246:249], v[16:19], v[64:67]
	v_mfma_f32_16x16x32_bf16 v[68:71], v[4:7], v[214:217], v[68:71]
	v_mfma_f32_16x16x32_bf16 v[100:103], v[246:249], v[234:237], v[0:3]
	s_setprio 0
	s_barrier
	ds_read_b128 v[190:193], v144 offset:49152
	ds_read_b128 v[194:197], v144 offset:50176
	ds_read_b128 v[198:201], v144 offset:51200
	ds_read_b128 v[202:205], v144 offset:52224
	ds_read_b128 v[222:225], v144 offset:53248
	ds_read_b128 v[226:229], v144 offset:54272
	ds_read_b128 v[230:233], v144 offset:55296
	ds_read_b128 v[238:241], v144 offset:56320
	s_waitcnt lgkmcnt(0)
	s_barrier
	s_setprio 1
	s_waitcnt lgkmcnt(0)
	v_mfma_f32_16x16x32_bf16 v[4:7], v[190:193], v[182:185], v[56:59]
	v_mfma_f32_16x16x32_bf16 v[8:11], v[198:201], v[182:185], v[48:51]
	v_mfma_f32_16x16x32_bf16 v[0:3], v[190:193], v[12:15], v[60:63]
	v_mfma_f32_16x16x32_bf16 v[32:35], v[194:197], v[186:189], v[4:7]
	v_mfma_f32_16x16x32_bf16 v[4:7], v[198:201], v[12:15], v[52:55]
	v_mfma_f32_16x16x32_bf16 v[36:39], v[202:205], v[186:189], v[8:11]
	v_mfma_f32_16x16x32_bf16 v[8:11], v[222:225], v[12:15], v[44:47]
	v_mfma_f32_16x16x32_bf16 v[12:15], v[230:233], v[12:15], v[136:139]
	v_mfma_f32_16x16x32_bf16 v[0:3], v[194:197], v[16:19], v[0:3]
	v_mfma_f32_16x16x32_bf16 v[4:7], v[202:205], v[16:19], v[4:7]
	v_mfma_f32_16x16x32_bf16 v[8:11], v[226:229], v[16:19], v[8:11]
	v_mfma_f32_16x16x32_bf16 v[12:15], v[238:241], v[16:19], v[12:15]
	v_mfma_f32_16x16x32_bf16 v[16:19], v[230:233], v[182:185], v[140:143]
	v_mfma_f32_16x16x32_bf16 v[24:27], v[190:193], v[218:221], v[24:27]
	v_mfma_f32_16x16x32_bf16 v[44:47], v[238:241], v[186:189], v[16:19]
	v_mfma_f32_16x16x32_bf16 v[16:19], v[190:193], v[206:209], v[28:31]
	v_mfma_f32_16x16x32_bf16 v[48:51], v[194:197], v[234:237], v[24:27]
	v_mfma_f32_16x16x32_bf16 v[24:27], v[198:201], v[218:221], v[166:169]
	v_mfma_f32_16x16x32_bf16 v[28:31], v[222:225], v[218:221], v[210:213]
	v_mfma_f32_16x16x32_bf16 v[40:43], v[222:225], v[182:185], v[40:43]
	v_mfma_f32_16x16x32_bf16 v[20:23], v[198:201], v[206:209], v[20:23]
	v_mfma_f32_16x16x32_bf16 v[52:55], v[202:205], v[234:237], v[24:27]
	v_mfma_f32_16x16x32_bf16 v[24:27], v[222:225], v[206:209], v[170:173]
	v_mfma_f32_16x16x32_bf16 v[56:59], v[226:229], v[234:237], v[28:31]
	v_mfma_f32_16x16x32_bf16 v[28:31], v[230:233], v[206:209], v[174:177]
	v_mfma_f32_16x16x32_bf16 v[60:63], v[230:233], v[218:221], v[178:181]
	v_mfma_f32_16x16x32_bf16 v[40:43], v[226:229], v[186:189], v[40:43]
	v_mfma_f32_16x16x32_bf16 v[16:19], v[194:197], v[214:217], v[16:19]
	v_mfma_f32_16x16x32_bf16 v[20:23], v[202:205], v[214:217], v[20:23]
	v_mfma_f32_16x16x32_bf16 v[24:27], v[226:229], v[214:217], v[24:27]
	v_mfma_f32_16x16x32_bf16 v[28:31], v[238:241], v[214:217], v[28:31]
	v_mfma_f32_16x16x32_bf16 v[60:63], v[238:241], v[234:237], v[60:63]
	s_setprio 0
	s_barrier
	s_and_saveexec_b64 s[70:71], s[6:7]
	s_cbranch_execz .LBB0_489
	s_barrier

; #define STAGE(Pp, BASE, br, kt) do { const u16* _g = (BASE) + ((long)(br) * K + (long)(kt) * BK); \
;     __builtin_amdgcn_global_load_lds((const unsigned*)(_g + voff0), (unsigned*)((char*)(Pp) + tb16), 16, 0, 0); \
;     __builtin_amdgcn_global_load_lds((const unsigned*)(_g + voff1), (unsigned*)((char*)(Pp) + tb16 + 8192), 16, 0, 0); } while (0)
; #define LDA(dst, b, h) _Pragma("unroll") for (int m = 0; m < 4; ++m) _Pragma("unroll") for (int k = 0; k < 2; ++k) \
;     dst[m][k] = *reinterpret_cast<const bf16x8*>((const char*)shm + aB + (((b) * 2 + (h)) * 16384 + (m * 2 + k) * 1024))
; #define LDB(dst, b, h) _Pragma("unroll") for (int n = 0; n < 2; ++n) _Pragma("unroll") for (int k = 0; k < 2; ++k) \
;     dst[n][k] = *reinterpret_cast<const bf16x8*>((const char*)shm + bB + (((b) * 2 + (h)) * 16384 + (n * 2 + k) * 1024))
; #define WAIT_V(n) asm volatile("s_waitcnt vmcnt(" #n ")" ::: "memory")
; #define WAIT_L(n) asm volatile("s_waitcnt lgkmcnt(" #n ")" ::: "memory")
; #define BAR __builtin_amdgcn_s_barrier()
; #define SCHED __builtin_amdgcn_sched_barrier(0)
; template <int MODE> ...
;     ...
;     STAGE(SB(0, 0), Bt, bcol, 0); STAGE(SA(0, 0), A, brow, 0); STAGE(SB(0, 1), Bt, bcol + HALF, 0); STAGE(SA(0, 1), A, brow + HALF, 0);
;     STAGE(SB(1, 0), Bt, bcol, 1); STAGE(SA(1, 0), A, brow, 1); STAGE(SB(1, 1), Bt, bcol + HALF, 1);
;     WAIT_V(6);
;     if (wr == 1) BAR;
;     BAR;
;     for (int t = 0; t < nt - 2; t += 2) {
;       LDB(B0, 0, 0); LDB(B1, 0, 1); LDA(At, 0, 0); STAGE(SA(1, 1), A, brow + HALF, t + 1);
;       WAIT_L(0); BAR; MMA2(0, 0, 0, 1); BAR; SCHED;
;       LDA(At, 0, 1); STAGE(SB(0, 0), Bt, bcol, t + 2); STAGE(SB(0, 1), Bt, bcol + HALF, t + 2); STAGE(SA(0, 0), A, brow, t + 2);
;       WAIT_V(6); WAIT_L(0); BAR; MMA2(1, 0, 1, 1); BAR; SCHED;
.LBB0_591:
	v_readfirstlane_b32 s65, v165
	s_mov_b32 m0, s65
	ds_read_b128 v[168:171], v149
	ds_read_b128 v[172:175], v149 offset:1024
	ds_read_b128 v[176:179], v149 offset:2048
	ds_read_b128 v[180:183], v149 offset:3072
	ds_read_b128 v[184:187], v149 offset:16384
	ds_read_b128 v[188:191], v149 offset:17408
	ds_read_b128 v[192:195], v149 offset:18432
	ds_read_b128 v[196:199], v149 offset:19456
	ds_read_b128 v[200:203], v148
	ds_read_b128 v[204:207], v148 offset:1024
	ds_read_b128 v[208:211], v148 offset:2048
	ds_read_b128 v[212:215], v148 offset:3072
	ds_read_b128 v[216:219], v148 offset:4096
	ds_read_b128 v[220:223], v148 offset:5120
	ds_read_b128 v[224:227], v148 offset:6144
	ds_read_b128 v[228:231], v148 offset:7168
	s_add_u32 s88, s10, s38
	s_addc_u32 s89, s11, s39
	global_load_lds_dwordx4 v142, s[88:89]
	v_readfirstlane_b32 s65, v166
	s_mov_b32 m0, s65
	s_nop 0
	s_add_u32 s90, s10, s38
	s_addc_u32 s91, s11, s39
	global_load_lds_dwordx4 v144, s[90:91]
	s_waitcnt lgkmcnt(0)
	s_barrier
	s_setprio 1
	s_waitcnt lgkmcnt(0)
	v_mfma_f32_16x16x32_bf16 v[124:127], v[200:203], v[168:171], v[124:127]
	v_mfma_f32_16x16x32_bf16 v[120:123], v[200:203], v[176:179], v[120:123]
	v_mfma_f32_16x16x32_bf16 v[116:119], v[208:211], v[168:171], v[116:119]
	v_mfma_f32_16x16x32_bf16 v[112:115], v[208:211], v[176:179], v[112:115]
	v_mfma_f32_16x16x32_bf16 v[108:111], v[216:219], v[168:171], v[108:111]
	v_mfma_f32_16x16x32_bf16 v[104:107], v[216:219], v[176:179], v[104:107]
	v_mfma_f32_16x16x32_bf16 v[100:103], v[224:227], v[168:171], v[100:103]
	v_mfma_f32_16x16x32_bf16 v[96:99], v[224:227], v[176:179], v[96:99]
	v_mfma_f32_16x16x32_bf16 v[88:91], v[200:203], v[184:187], v[88:91]
	v_mfma_f32_16x16x32_bf16 v[72:75], v[200:203], v[192:195], v[72:75]
	v_mfma_f32_16x16x32_bf16 v[56:59], v[208:211], v[184:187], v[56:59]
	v_mfma_f32_16x16x32_bf16 v[48:51], v[208:211], v[192:195], v[48:51]
	v_mfma_f32_16x16x32_bf16 v[44:47], v[216:219], v[184:187], v[44:47]
	v_mfma_f32_16x16x32_bf16 v[40:43], v[216:219], v[192:195], v[40:43]
	v_mfma_f32_16x16x32_bf16 v[36:39], v[224:227], v[184:187], v[36:39]
	v_mfma_f32_16x16x32_bf16 v[32:35], v[224:227], v[192:195], v[32:35]
	v_mfma_f32_16x16x32_bf16 v[124:127], v[204:207], v[172:175], v[124:127]
	v_mfma_f32_16x16x32_bf16 v[120:123], v[204:207], v[180:183], v[120:123]
	v_mfma_f32_16x16x32_bf16 v[116:119], v[212:215], v[172:175], v[116:119]
	v_mfma_f32_16x16x32_bf16 v[112:115], v[212:215], v[180:183], v[112:115]
	v_mfma_f32_16x16x32_bf16 v[108:111], v[220:223], v[172:175], v[108:111]
	v_mfma_f32_16x16x32_bf16 v[104:107], v[220:223], v[180:183], v[104:107]
	v_mfma_f32_16x16x32_bf16 v[100:103], v[228:231], v[172:175], v[100:103]
	v_mfma_f32_16x16x32_bf16 v[96:99], v[228:231], v[180:183], v[96:99]
	v_mfma_f32_16x16x32_bf16 v[88:91], v[204:207], v[188:191], v[88:91]
	v_mfma_f32_16x16x32_bf16 v[72:75], v[204:207], v[196:199], v[72:75]
	v_mfma_f32_16x16x32_bf16 v[56:59], v[212:215], v[188:191], v[56:59]
	v_mfma_f32_16x16x32_bf16 v[48:51], v[212:215], v[196:199], v[48:51]
	v_mfma_f32_16x16x32_bf16 v[44:47], v[220:223], v[188:191], v[44:47]
	v_mfma_f32_16x16x32_bf16 v[40:43], v[220:223], v[196:199], v[40:43]
	v_mfma_f32_16x16x32_bf16 v[36:39], v[228:231], v[188:191], v[36:39]
	v_mfma_f32_16x16x32_bf16 v[32:35], v[228:231], v[196:199], v[32:35]
	s_setprio 0
	s_barrier
	v_readfirstlane_b32 s65, v151
	s_mov_b32 m0, s65
	ds_read_b128 v[200:203], v148 offset:16384
	ds_read_b128 v[204:207], v148 offset:17408
	ds_read_b128 v[208:211], v148 offset:18432
	ds_read_b128 v[212:215], v148 offset:19456
	ds_read_b128 v[216:219], v148 offset:20480
	ds_read_b128 v[220:223], v148 offset:21504
	ds_read_b128 v[224:227], v148 offset:22528
	ds_read_b128 v[228:231], v148 offset:23552
	s_add_u32 s92, s10, s40
	s_addc_u32 s93, s11, s41
	global_load_lds_dwordx4 v138, s[92:93]
	v_readfirstlane_b32 s65, v152
	s_mov_b32 m0, s65
	v_readfirstlane_b32 s65, v154
	s_add_u32 s96, s10, s40
	s_addc_u32 s97, s11, s41
	global_load_lds_dwordx4 v140, s[96:97]
	s_mov_b32 m0, s65
	v_readfirstlane_b32 s65, v155
	s_add_u32 s88, s10, s42
	s_addc_u32 s89, s11, s43
	global_load_lds_dwordx4 v138, s[88:89]
	s_mov_b32 m0, s65
	v_readfirstlane_b32 s65, v150
	s_add_u32 s90, s10, s42
	s_addc_u32 s91, s11, s43
	global_load_lds_dwordx4 v140, s[90:91]
	s_mov_b32 m0, s65
	v_readfirstlane_b32 s65, v153
	s_add_u32 s92, s10, s44
	s_addc_u32 s93, s11, s45
	global_load_lds_dwordx4 v142, s[92:93]
	s_mov_b32 m0, s65
	s_nop 0
	s_add_u32 s96, s10, s44
	s_addc_u32 s97, s11, s45
	global_load_lds_dwordx4 v144, s[96:97]
	s_waitcnt vmcnt(6)
	s_waitcnt lgkmcnt(0)
	s_barrier
; #define STAGE(Pp, BASE, br, kt) do { const u16* _g = (BASE) + ((long)(br) * K + (long)(kt) * BK); \
;     __builtin_amdgcn_global_load_lds((const unsigned*)(_g + voff0), (unsigned*)((char*)(Pp) + tb16), 16, 0, 0); \
;     __builtin_amdgcn_global_load_lds((const unsigned*)(_g + voff1), (unsigned*)((char*)(Pp) + tb16 + 8192), 16, 0, 0); } while (0)
; #define LDA(dst, b, h) _Pragma("unroll") for (int m = 0; m < 4; ++m) _Pragma("unroll") for (int k = 0; k < 2; ++k) \
;     dst[m][k] = *reinterpret_cast<const bf16x8*>((const char*)shm + aB + (((b) * 2 + (h)) * 16384 + (m * 2 + k) * 1024))
; #define LDB(dst, b, h) _Pragma("unroll") for (int n = 0; n < 2; ++n) _Pragma("unroll") for (int k = 0; k < 2; ++k) \
;     dst[n][k] = *reinterpret_cast<const bf16x8*>((const char*)shm + bB + (((b) * 2 + (h)) * 16384 + (n * 2 + k) * 1024))
; #define WAIT_V(n) asm volatile("s_waitcnt vmcnt(" #n ")" ::: "memory")
; #define WAIT_L(n) asm volatile("s_waitcnt lgkmcnt(" #n ")" ::: "memory")
; #define BAR __builtin_amdgcn_s_barrier()
; #define SCHED __builtin_amdgcn_sched_barrier(0)
; template <int MODE> ...
;     ...
;     STAGE(SB(0, 0), Bt, bcol, 0); STAGE(SA(0, 0), A, brow, 0); STAGE(SB(0, 1), Bt, bcol + HALF, 0); STAGE(SA(0, 1), A, brow + HALF, 0);
;     STAGE(SB(1, 0), Bt, bcol, 1); STAGE(SA(1, 0), A, brow, 1); STAGE(SB(1, 1), Bt, bcol + HALF, 1);
;     WAIT_V(6);
;     if (wr == 1) BAR;
;     BAR;
;     for (int t = 0; t < nt - 2; t += 2) {
;       LDB(B0, 0, 0); LDB(B1, 0, 1); LDA(At, 0, 0); STAGE(SA(1, 1), A, brow + HALF, t + 1);
;       WAIT_L(0); BAR; MMA2(0, 0, 0, 1); BAR; SCHED;
;       LDA(At, 0, 1); STAGE(SB(0, 0), Bt, bcol, t + 2); STAGE(SB(0, 1), Bt, bcol + HALF, t + 2); STAGE(SA(0, 0), A, brow, t + 2);
;       WAIT_V(6); WAIT_L(0); BAR; MMA2(1, 0, 1, 1); BAR; SCHED;
;       LDB(B0, 1, 0); LDB(B1, 1, 1); LDA(At, 1, 0); STAGE(SA(0, 1), A, brow + HALF, t + 2);
;       WAIT_L(0); BAR; MMA2(0, 0, 0, 1); BAR; SCHED;
	s_setprio 1
	s_waitcnt lgkmcnt(0)
	v_mfma_f32_16x16x32_bf16 v[28:31], v[200:203], v[168:171], v[28:31]
	v_mfma_f32_16x16x32_bf16 v[24:27], v[200:203], v[176:179], v[24:27]
	v_mfma_f32_16x16x32_bf16 v[20:23], v[208:211], v[168:171], v[20:23]
	v_mfma_f32_16x16x32_bf16 v[16:19], v[208:211], v[176:179], v[16:19]
	v_mfma_f32_16x16x32_bf16 v[12:15], v[216:219], v[168:171], v[12:15]
	v_mfma_f32_16x16x32_bf16 v[8:11], v[216:219], v[176:179], v[8:11]
	v_mfma_f32_16x16x32_bf16 v[4:7], v[224:227], v[168:171], v[4:7]
	v_mfma_f32_16x16x32_bf16 v[0:3], v[224:227], v[176:179], v[0:3]
	v_mfma_f32_16x16x32_bf16 v[52:55], v[200:203], v[184:187], v[52:55]
	v_mfma_f32_16x16x32_bf16 v[60:63], v[200:203], v[192:195], v[60:63]
	v_mfma_f32_16x16x32_bf16 v[64:67], v[208:211], v[184:187], v[64:67]
	v_mfma_f32_16x16x32_bf16 v[68:71], v[208:211], v[192:195], v[68:71]
	v_mfma_f32_16x16x32_bf16 v[76:79], v[216:219], v[184:187], v[76:79]
	v_mfma_f32_16x16x32_bf16 v[80:83], v[216:219], v[192:195], v[80:83]
	v_mfma_f32_16x16x32_bf16 v[84:87], v[224:227], v[184:187], v[84:87]
	v_mfma_f32_16x16x32_bf16 v[92:95], v[224:227], v[192:195], v[92:95]
	v_mfma_f32_16x16x32_bf16 v[28:31], v[204:207], v[172:175], v[28:31]
	v_mfma_f32_16x16x32_bf16 v[24:27], v[204:207], v[180:183], v[24:27]
	v_mfma_f32_16x16x32_bf16 v[20:23], v[212:215], v[172:175], v[20:23]
	v_mfma_f32_16x16x32_bf16 v[16:19], v[212:215], v[180:183], v[16:19]
	v_mfma_f32_16x16x32_bf16 v[12:15], v[220:223], v[172:175], v[12:15]
	v_mfma_f32_16x16x32_bf16 v[8:11], v[220:223], v[180:183], v[8:11]
	v_mfma_f32_16x16x32_bf16 v[4:7], v[228:231], v[172:175], v[4:7]
	v_mfma_f32_16x16x32_bf16 v[0:3], v[228:231], v[180:183], v[0:3]
	v_mfma_f32_16x16x32_bf16 v[52:55], v[204:207], v[188:191], v[52:55]
	v_mfma_f32_16x16x32_bf16 v[60:63], v[204:207], v[196:199], v[60:63]
	v_mfma_f32_16x16x32_bf16 v[64:67], v[212:215], v[188:191], v[64:67]
	v_mfma_f32_16x16x32_bf16 v[68:71], v[212:215], v[196:199], v[68:71]
	v_mfma_f32_16x16x32_bf16 v[76:79], v[220:223], v[188:191], v[76:79]
	v_mfma_f32_16x16x32_bf16 v[80:83], v[220:223], v[196:199], v[80:83]
	v_mfma_f32_16x16x32_bf16 v[84:87], v[228:231], v[188:191], v[84:87]
	v_mfma_f32_16x16x32_bf16 v[92:95], v[228:231], v[196:199], v[92:95]
	s_setprio 0
	s_barrier
	v_readfirstlane_b32 s65, v156
	s_mov_b32 m0, s65
	v_readfirstlane_b32 s65, v157
	ds_read_b128 v[168:171], v149 offset:32768
	ds_read_b128 v[172:175], v149 offset:33792
	ds_read_b128 v[176:179], v149 offset:34816
	ds_read_b128 v[180:183], v149 offset:35840
	ds_read_b128 v[184:187], v149 offset:49152
	ds_read_b128 v[188:191], v149 offset:50176
	ds_read_b128 v[192:195], v149 offset:51200
	ds_read_b128 v[196:199], v149 offset:52224
	ds_read_b128 v[200:203], v148 offset:32768
	ds_read_b128 v[204:207], v148 offset:33792
	ds_read_b128 v[208:211], v148 offset:34816
	ds_read_b128 v[212:215], v148 offset:35840
	ds_read_b128 v[216:219], v148 offset:36864
	ds_read_b128 v[220:223], v148 offset:37888
	ds_read_b128 v[224:227], v148 offset:38912
	ds_read_b128 v[228:231], v148 offset:39936
	s_add_u32 s88, s10, s48
	s_addc_u32 s89, s11, s49
	global_load_lds_dwordx4 v142, s[88:89]
	s_mov_b32 m0, s65
	s_nop 0
	s_add_u32 s90, s10, s48
	s_addc_u32 s91, s11, s49
	global_load_lds_dwordx4 v144, s[90:91]
	s_waitcnt lgkmcnt(0)
	s_barrier
	s_setprio 1
	s_waitcnt lgkmcnt(0)
	v_mfma_f32_16x16x32_bf16 v[124:127], v[200:203], v[168:171], v[124:127]
	v_mfma_f32_16x16x32_bf16 v[120:123], v[200:203], v[176:179], v[120:123]
	v_mfma_f32_16x16x32_bf16 v[116:119], v[208:211], v[168:171], v[116:119]
	v_mfma_f32_16x16x32_bf16 v[112:115], v[208:211], v[176:179], v[112:115]
	v_mfma_f32_16x16x32_bf16 v[108:111], v[216:219], v[168:171], v[108:111]
	v_mfma_f32_16x16x32_bf16 v[104:107], v[216:219], v[176:179], v[104:107]
	v_mfma_f32_16x16x32_bf16 v[100:103], v[224:227], v[168:171], v[100:103]
	v_mfma_f32_16x16x32_bf16 v[96:99], v[224:227], v[176:179], v[96:99]
	v_mfma_f32_16x16x32_bf16 v[88:91], v[200:203], v[184:187], v[88:91]
	v_mfma_f32_16x16x32_bf16 v[72:75], v[200:203], v[192:195], v[72:75]
	v_mfma_f32_16x16x32_bf16 v[56:59], v[208:211], v[184:187], v[56:59]
	v_mfma_f32_16x16x32_bf16 v[48:51], v[208:211], v[192:195], v[48:51]
	v_mfma_f32_16x16x32_bf16 v[44:47], v[216:219], v[184:187], v[44:47]
	v_mfma_f32_16x16x32_bf16 v[40:43], v[216:219], v[192:195], v[40:43]
	v_mfma_f32_16x16x32_bf16 v[36:39], v[224:227], v[184:187], v[36:39]
	v_mfma_f32_16x16x32_bf16 v[32:35], v[224:227], v[192:195], v[32:35]
	v_mfma_f32_16x16x32_bf16 v[124:127], v[204:207], v[172:175], v[124:127]
	v_mfma_f32_16x16x32_bf16 v[120:123], v[204:207], v[180:183], v[120:123]
	v_mfma_f32_16x16x32_bf16 v[116:119], v[212:215], v[172:175], v[116:119]
	v_mfma_f32_16x16x32_bf16 v[112:115], v[212:215], v[180:183], v[112:115]
	v_mfma_f32_16x16x32_bf16 v[108:111], v[220:223], v[172:175], v[108:111]
	v_mfma_f32_16x16x32_bf16 v[104:107], v[220:223], v[180:183], v[104:107]
	v_mfma_f32_16x16x32_bf16 v[100:103], v[228:231], v[172:175], v[100:103]
	v_mfma_f32_16x16x32_bf16 v[96:99], v[228:231], v[180:183], v[96:99]
	v_mfma_f32_16x16x32_bf16 v[88:91], v[204:207], v[188:191], v[88:91]
	v_mfma_f32_16x16x32_bf16 v[72:75], v[204:207], v[196:199], v[72:75]
	v_mfma_f32_16x16x32_bf16 v[56:59], v[212:215], v[188:191], v[56:59]
	v_mfma_f32_16x16x32_bf16 v[48:51], v[212:215], v[196:199], v[48:51]
	v_mfma_f32_16x16x32_bf16 v[44:47], v[220:223], v[188:191], v[44:47]
	v_mfma_f32_16x16x32_bf16 v[40:43], v[220:223], v[196:199], v[40:43]
	v_mfma_f32_16x16x32_bf16 v[36:39], v[228:231], v[188:191], v[36:39]
	v_mfma_f32_16x16x32_bf16 v[32:35], v[228:231], v[196:199], v[32:35]
	s_setprio 0
	s_barrier
; #define STAGE(Pp, BASE, br, kt) do { const u16* _g = (BASE) + ((long)(br) * K + (long)(kt) * BK); \
;     __builtin_amdgcn_global_load_lds((const unsigned*)(_g + voff0), (unsigned*)((char*)(Pp) + tb16), 16, 0, 0); \
;     __builtin_amdgcn_global_load_lds((const unsigned*)(_g + voff1), (unsigned*)((char*)(Pp) + tb16 + 8192), 16, 0, 0); } while (0)
; #define LDA(dst, b, h) _Pragma("unroll") for (int m = 0; m < 4; ++m) _Pragma("unroll") for (int k = 0; k < 2; ++k) \
;     dst[m][k] = *reinterpret_cast<const bf16x8*>((const char*)shm + aB + (((b) * 2 + (h)) * 16384 + (m * 2 + k) * 1024))
; #define LDB(dst, b, h) _Pragma("unroll") for (int n = 0; n < 2; ++n) _Pragma("unroll") for (int k = 0; k < 2; ++k) \
;     dst[n][k] = *reinterpret_cast<const bf16x8*>((const char*)shm + bB + (((b) * 2 + (h)) * 16384 + (n * 2 + k) * 1024))
; #define WAIT_V(n) asm volatile("s_waitcnt vmcnt(" #n ")" ::: "memory")
; #define WAIT_L(n) asm volatile("s_waitcnt lgkmcnt(" #n ")" ::: "memory")
; #define BAR __builtin_amdgcn_s_barrier()
; #define SCHED __builtin_amdgcn_sched_barrier(0)
; template <int MODE> ...
;     ...
;     STAGE(SB(0, 0), Bt, bcol, 0); STAGE(SA(0, 0), A, brow, 0); STAGE(SB(0, 1), Bt, bcol + HALF, 0); STAGE(SA(0, 1), A, brow + HALF, 0);
;     STAGE(SB(1, 0), Bt, bcol, 1); STAGE(SA(1, 0), A, brow, 1); STAGE(SB(1, 1), Bt, bcol + HALF, 1);
;     WAIT_V(6);
;     if (wr == 1) BAR;
;     BAR;
;     for (int t = 0; t < nt - 2; t += 2) {
;       LDB(B0, 0, 0); LDB(B1, 0, 1); LDA(At, 0, 0); STAGE(SA(1, 1), A, brow + HALF, t + 1);
;       WAIT_L(0); BAR; MMA2(0, 0, 0, 1); BAR; SCHED;
;       LDA(At, 0, 1); STAGE(SB(0, 0), Bt, bcol, t + 2); STAGE(SB(0, 1), Bt, bcol + HALF, t + 2); STAGE(SA(0, 0), A, brow, t + 2);
;       WAIT_V(6); WAIT_L(0); BAR; MMA2(1, 0, 1, 1); BAR; SCHED;
;       LDB(B0, 1, 0); LDB(B1, 1, 1); LDA(At, 1, 0); STAGE(SA(0, 1), A, brow + HALF, t + 2);
;       WAIT_L(0); BAR; MMA2(0, 0, 0, 1); BAR; SCHED;
;       LDA(At, 1, 1); STAGE(SB(1, 0), Bt, bcol, t + 3); STAGE(SB(1, 1), Bt, bcol + HALF, t + 3); STAGE(SA(1, 0), A, brow, t + 3);
;       WAIT_V(6); WAIT_L(0); BAR; MMA2(1, 0, 1, 1); BAR; SCHED;
;     }
;     {
;       LDB(B0, 0, 0); LDB(B1, 0, 1); LDA(At, 0, 0); STAGE(SA(1, 1), A, brow + HALF, nt - 1);
	v_readfirstlane_b32 s65, v158
	s_mov_b32 m0, s65
	v_readfirstlane_b32 s65, v159
	ds_read_b128 v[200:203], v148 offset:49152
	ds_read_b128 v[204:207], v148 offset:50176
	ds_read_b128 v[208:211], v148 offset:51200
	ds_read_b128 v[212:215], v148 offset:52224
	ds_read_b128 v[216:219], v148 offset:53248
	ds_read_b128 v[220:223], v148 offset:54272
	ds_read_b128 v[224:227], v148 offset:55296
	ds_read_b128 v[228:231], v148 offset:56320
	s_add_u32 s92, s10, s50
	s_addc_u32 s93, s11, s51
	global_load_lds_dwordx4 v138, s[92:93]
	s_mov_b32 m0, s65
	v_readfirstlane_b32 s65, v162
	s_add_u32 s96, s10, s50
	s_addc_u32 s97, s11, s51
	global_load_lds_dwordx4 v140, s[96:97]
	s_mov_b32 m0, s65
	v_readfirstlane_b32 s65, v163
	s_add_u32 s88, s10, s60
	s_addc_u32 s89, s11, s61
	global_load_lds_dwordx4 v138, s[88:89]
	s_mov_b32 m0, s65
	v_readfirstlane_b32 s65, v160
	s_add_u32 s90, s10, s60
	s_addc_u32 s91, s11, s61
	global_load_lds_dwordx4 v140, s[90:91]
	s_mov_b32 m0, s65
	v_readfirstlane_b32 s65, v161
	s_add_u32 s92, s10, s62
	s_addc_u32 s93, s11, s63
	global_load_lds_dwordx4 v142, s[92:93]
	s_mov_b32 m0, s65
	s_nop 0
	s_add_u32 s96, s10, s62
	s_addc_u32 s97, s11, s63
	global_load_lds_dwordx4 v144, s[96:97]
	s_waitcnt vmcnt(6)
	s_waitcnt lgkmcnt(0)
	s_barrier
	s_setprio 1
	s_waitcnt lgkmcnt(0)
	v_mfma_f32_16x16x32_bf16 v[28:31], v[200:203], v[168:171], v[28:31]
	v_mfma_f32_16x16x32_bf16 v[24:27], v[200:203], v[176:179], v[24:27]
	v_mfma_f32_16x16x32_bf16 v[20:23], v[208:211], v[168:171], v[20:23]
	v_mfma_f32_16x16x32_bf16 v[16:19], v[208:211], v[176:179], v[16:19]
	v_mfma_f32_16x16x32_bf16 v[12:15], v[216:219], v[168:171], v[12:15]
	v_mfma_f32_16x16x32_bf16 v[8:11], v[216:219], v[176:179], v[8:11]
	v_mfma_f32_16x16x32_bf16 v[4:7], v[224:227], v[168:171], v[4:7]
	v_mfma_f32_16x16x32_bf16 v[0:3], v[224:227], v[176:179], v[0:3]
	v_mfma_f32_16x16x32_bf16 v[52:55], v[200:203], v[184:187], v[52:55]
	v_mfma_f32_16x16x32_bf16 v[60:63], v[200:203], v[192:195], v[60:63]
	v_mfma_f32_16x16x32_bf16 v[64:67], v[208:211], v[184:187], v[64:67]
	v_mfma_f32_16x16x32_bf16 v[68:71], v[208:211], v[192:195], v[68:71]
	v_mfma_f32_16x16x32_bf16 v[76:79], v[216:219], v[184:187], v[76:79]
	v_mfma_f32_16x16x32_bf16 v[80:83], v[216:219], v[192:195], v[80:83]
	v_mfma_f32_16x16x32_bf16 v[84:87], v[224:227], v[184:187], v[84:87]
	v_mfma_f32_16x16x32_bf16 v[92:95], v[224:227], v[192:195], v[92:95]
	v_mfma_f32_16x16x32_bf16 v[28:31], v[204:207], v[172:175], v[28:31]
	v_mfma_f32_16x16x32_bf16 v[24:27], v[204:207], v[180:183], v[24:27]
	v_mfma_f32_16x16x32_bf16 v[20:23], v[212:215], v[172:175], v[20:23]
	v_mfma_f32_16x16x32_bf16 v[16:19], v[212:215], v[180:183], v[16:19]
	v_mfma_f32_16x16x32_bf16 v[12:15], v[220:223], v[172:175], v[12:15]
	v_mfma_f32_16x16x32_bf16 v[8:11], v[220:223], v[180:183], v[8:11]
	v_mfma_f32_16x16x32_bf16 v[4:7], v[228:231], v[172:175], v[4:7]
	v_mfma_f32_16x16x32_bf16 v[0:3], v[228:231], v[180:183], v[0:3]
	v_mfma_f32_16x16x32_bf16 v[52:55], v[204:207], v[188:191], v[52:55]
	v_mfma_f32_16x16x32_bf16 v[60:63], v[204:207], v[196:199], v[60:63]
	v_mfma_f32_16x16x32_bf16 v[64:67], v[212:215], v[188:191], v[64:67]
	v_mfma_f32_16x16x32_bf16 v[68:71], v[212:215], v[196:199], v[68:71]
	v_mfma_f32_16x16x32_bf16 v[76:79], v[220:223], v[188:191], v[76:79]
	v_mfma_f32_16x16x32_bf16 v[80:83], v[220:223], v[196:199], v[80:83]
	v_mfma_f32_16x16x32_bf16 v[84:87], v[228:231], v[188:191], v[84:87]
	v_mfma_f32_16x16x32_bf16 v[92:95], v[228:231], v[196:199], v[92:95]
	s_setprio 0
	s_barrier
	s_add_i32 s35, s35, 2
	s_add_u32 s10, s10, 0x100
	s_addc_u32 s11, s11, 0
	s_cmp_lt_u32 s35, 60
	s_cbranch_scc1 .LBB0_591
	s_add_u32 s8, s8, 0x1f80
	v_readfirstlane_b32 s10, v165
	s_addc_u32 s9, s9, 0
	s_mov_b32 m0, s10
	v_readfirstlane_b32 s10, v166
	ds_read_b128 v[138:141], v149
	ds_read_b128 v[142:145], v149 offset:1024
	ds_read_b128 v[168:171], v149 offset:2048
	ds_read_b128 v[172:175], v149 offset:3072
	ds_read_b128 v[176:179], v149 offset:16384
	ds_read_b128 v[180:183], v149 offset:17408
	ds_read_b128 v[184:187], v149 offset:18432
	ds_read_b128 v[188:191], v149 offset:19456
	ds_read_b128 v[192:195], v148
	ds_read_b128 v[196:199], v148 offset:1024
	ds_read_b128 v[200:203], v148 offset:2048
	ds_read_b128 v[204:207], v148 offset:3072
	ds_read_b128 v[208:211], v148 offset:4096
	ds_read_b128 v[212:215], v148 offset:5120
	ds_read_b128 v[216:219], v148 offset:6144
	ds_read_b128 v[220:223], v148 offset:7168
	global_load_lds_dwordx4 v134, s[8:9]
	s_mov_b32 m0, s10
	s_nop 0
	global_load_lds_dwordx4 v136, s[8:9]
	s_waitcnt lgkmcnt(0)
	s_barrier
; #define STAGE(Pp, BASE, br, kt) do { const u16* _g = (BASE) + ((long)(br) * K + (long)(kt) * BK); \
;     __builtin_amdgcn_global_load_lds((const unsigned*)(_g + voff0), (unsigned*)((char*)(Pp) + tb16), 16, 0, 0); \
;     __builtin_amdgcn_global_load_lds((const unsigned*)(_g + voff1), (unsigned*)((char*)(Pp) + tb16 + 8192), 16, 0, 0); } while (0)
; #define LDA(dst, b, h) _Pragma("unroll") for (int m = 0; m < 4; ++m) _Pragma("unroll") for (int k = 0; k < 2; ++k) \
;     dst[m][k] = *reinterpret_cast<const bf16x8*>((const char*)shm + aB + (((b) * 2 + (h)) * 16384 + (m * 2 + k) * 1024))
; #define LDB(dst, b, h) _Pragma("unroll") for (int n = 0; n < 2; ++n) _Pragma("unroll") for (int k = 0; k < 2; ++k) \
;     dst[n][k] = *reinterpret_cast<const bf16x8*>((const char*)shm + bB + (((b) * 2 + (h)) * 16384 + (n * 2 + k) * 1024))
; #define WAIT_V(n) asm volatile("s_waitcnt vmcnt(" #n ")" ::: "memory")
; #define WAIT_L(n) asm volatile("s_waitcnt lgkmcnt(" #n ")" ::: "memory")
; #define BAR __builtin_amdgcn_s_barrier()
; #define SCHED __builtin_amdgcn_sched_barrier(0)
; template <int MODE> ...
;     ...
;       LDB(B0, 0, 0); LDB(B1, 0, 1); LDA(At, 0, 0); STAGE(SA(1, 1), A, brow + HALF, nt - 1);
;       WAIT_L(0); BAR; MMA2(0, 0, 0, 1); BAR; SCHED;
;       LDA(At, 0, 1); WAIT_V(0); WAIT_L(0); BAR; MMA2(1, 0, 1, 1); BAR; SCHED;
;       LDB(B0, 1, 0); LDB(B1, 1, 1); LDA(At, 1, 0); WAIT_L(0); BAR; MMA2(0, 0, 0, 1); BAR; SCHED;
	s_setprio 1
	s_waitcnt lgkmcnt(0)
	v_mfma_f32_16x16x32_bf16 v[124:127], v[192:195], v[138:141], v[124:127]
	v_mfma_f32_16x16x32_bf16 v[120:123], v[192:195], v[168:171], v[120:123]
	v_mfma_f32_16x16x32_bf16 v[116:119], v[200:203], v[138:141], v[116:119]
	v_mfma_f32_16x16x32_bf16 v[112:115], v[200:203], v[168:171], v[112:115]
	v_mfma_f32_16x16x32_bf16 v[108:111], v[208:211], v[138:141], v[108:111]
	v_mfma_f32_16x16x32_bf16 v[104:107], v[208:211], v[168:171], v[104:107]
	v_mfma_f32_16x16x32_bf16 v[96:99], v[216:219], v[168:171], v[96:99]
	v_mfma_f32_16x16x32_bf16 v[88:91], v[192:195], v[176:179], v[88:91]
	v_mfma_f32_16x16x32_bf16 v[72:75], v[192:195], v[184:187], v[72:75]
	v_mfma_f32_16x16x32_bf16 v[56:59], v[200:203], v[176:179], v[56:59]
	v_mfma_f32_16x16x32_bf16 v[48:51], v[200:203], v[184:187], v[48:51]
	v_mfma_f32_16x16x32_bf16 v[44:47], v[208:211], v[176:179], v[44:47]
	v_mfma_f32_16x16x32_bf16 v[40:43], v[208:211], v[184:187], v[40:43]
	v_mfma_f32_16x16x32_bf16 v[36:39], v[216:219], v[176:179], v[36:39]
	v_mfma_f32_16x16x32_bf16 v[32:35], v[216:219], v[184:187], v[32:35]
	v_mfma_f32_16x16x32_bf16 v[124:127], v[196:199], v[142:145], v[124:127]
	v_mfma_f32_16x16x32_bf16 v[120:123], v[196:199], v[172:175], v[120:123]
	v_mfma_f32_16x16x32_bf16 v[116:119], v[204:207], v[142:145], v[116:119]
	v_mfma_f32_16x16x32_bf16 v[112:115], v[204:207], v[172:175], v[112:115]
	v_mfma_f32_16x16x32_bf16 v[108:111], v[212:215], v[142:145], v[108:111]
	v_mfma_f32_16x16x32_bf16 v[104:107], v[212:215], v[172:175], v[104:107]
	v_mfma_f32_16x16x32_bf16 v[100:103], v[216:219], v[138:141], v[100:103]
	v_mfma_f32_16x16x32_bf16 v[96:99], v[220:223], v[172:175], v[96:99]
	v_mfma_f32_16x16x32_bf16 v[88:91], v[196:199], v[180:183], v[88:91]
	v_mfma_f32_16x16x32_bf16 v[72:75], v[196:199], v[188:191], v[72:75]
	v_mfma_f32_16x16x32_bf16 v[56:59], v[204:207], v[180:183], v[56:59]
	v_mfma_f32_16x16x32_bf16 v[48:51], v[204:207], v[188:191], v[48:51]
	v_mfma_f32_16x16x32_bf16 v[44:47], v[212:215], v[180:183], v[44:47]
	v_mfma_f32_16x16x32_bf16 v[40:43], v[212:215], v[188:191], v[40:43]
	v_mfma_f32_16x16x32_bf16 v[36:39], v[220:223], v[180:183], v[36:39]
	v_mfma_f32_16x16x32_bf16 v[32:35], v[220:223], v[188:191], v[32:35]
	v_mfma_f32_16x16x32_bf16 v[224:227], v[220:223], v[142:145], v[100:103]
	s_setprio 0
	s_barrier
	s_nop 0
	ds_read_b128 v[100:103], v148 offset:16384
	ds_read_b128 v[192:195], v148 offset:17408
	ds_read_b128 v[196:199], v148 offset:18432
	ds_read_b128 v[200:203], v148 offset:19456
	ds_read_b128 v[204:207], v148 offset:20480
	ds_read_b128 v[208:211], v148 offset:21504
	ds_read_b128 v[212:215], v148 offset:22528
	ds_read_b128 v[216:219], v148 offset:23552
	s_waitcnt vmcnt(0)
	s_waitcnt lgkmcnt(0)
	s_barrier
	s_setprio 1
	s_waitcnt lgkmcnt(0)
	v_mfma_f32_16x16x32_bf16 v[28:31], v[100:103], v[138:141], v[28:31]
	v_mfma_f32_16x16x32_bf16 v[20:23], v[196:199], v[138:141], v[20:23]
	v_mfma_f32_16x16x32_bf16 v[12:15], v[204:207], v[138:141], v[12:15]
	v_mfma_f32_16x16x32_bf16 v[4:7], v[212:215], v[138:141], v[4:7]
	v_mfma_f32_16x16x32_bf16 v[0:3], v[212:215], v[168:171], v[0:3]
	v_mfma_f32_16x16x32_bf16 v[28:31], v[192:195], v[142:145], v[28:31]
	v_mfma_f32_16x16x32_bf16 v[20:23], v[200:203], v[142:145], v[20:23]
	v_mfma_f32_16x16x32_bf16 v[220:223], v[208:211], v[142:145], v[12:15]
	v_mfma_f32_16x16x32_bf16 v[138:141], v[216:219], v[142:145], v[4:7]
	v_mfma_f32_16x16x32_bf16 v[142:145], v[216:219], v[172:175], v[0:3]
	v_mfma_f32_16x16x32_bf16 v[0:3], v[100:103], v[176:179], v[52:55]
	v_mfma_f32_16x16x32_bf16 v[24:27], v[100:103], v[168:171], v[24:27]
	v_mfma_f32_16x16x32_bf16 v[16:19], v[196:199], v[168:171], v[16:19]
	v_mfma_f32_16x16x32_bf16 v[8:11], v[204:207], v[168:171], v[8:11]
	v_mfma_f32_16x16x32_bf16 v[168:171], v[192:195], v[180:183], v[0:3]
	v_mfma_f32_16x16x32_bf16 v[0:3], v[100:103], v[184:187], v[60:63]
	v_mfma_f32_16x16x32_bf16 v[24:27], v[192:195], v[172:175], v[24:27]
	v_mfma_f32_16x16x32_bf16 v[16:19], v[200:203], v[172:175], v[16:19]
	v_mfma_f32_16x16x32_bf16 v[228:231], v[208:211], v[172:175], v[8:11]
	v_mfma_f32_16x16x32_bf16 v[172:175], v[192:195], v[188:191], v[0:3]
	v_mfma_f32_16x16x32_bf16 v[0:3], v[196:199], v[176:179], v[64:67]
	v_mfma_f32_16x16x32_bf16 v[192:195], v[200:203], v[180:183], v[0:3]
	v_mfma_f32_16x16x32_bf16 v[0:3], v[196:199], v[184:187], v[68:71]
	v_mfma_f32_16x16x32_bf16 v[196:199], v[200:203], v[188:191], v[0:3]
	v_mfma_f32_16x16x32_bf16 v[0:3], v[204:207], v[176:179], v[76:79]
	v_mfma_f32_16x16x32_bf16 v[200:203], v[208:211], v[180:183], v[0:3]
	v_mfma_f32_16x16x32_bf16 v[0:3], v[204:207], v[184:187], v[80:83]
	v_mfma_f32_16x16x32_bf16 v[204:207], v[208:211], v[188:191], v[0:3]
	v_mfma_f32_16x16x32_bf16 v[0:3], v[212:215], v[176:179], v[84:87]
	v_mfma_f32_16x16x32_bf16 v[176:179], v[216:219], v[180:183], v[0:3]
	v_mfma_f32_16x16x32_bf16 v[0:3], v[212:215], v[184:187], v[92:95]
	v_mfma_f32_16x16x32_bf16 v[180:183], v[216:219], v[188:191], v[0:3]
	s_setprio 0
	s_barrier
; #define LDA(dst, b, h) _Pragma("unroll") for (int m = 0; m < 4; ++m) _Pragma("unroll") for (int k = 0; k < 2; ++k) \
;     dst[m][k] = *reinterpret_cast<const bf16x8*>((const char*)shm + aB + (((b) * 2 + (h)) * 16384 + (m * 2 + k) * 1024))
; #define LDB(dst, b, h) _Pragma("unroll") for (int n = 0; n < 2; ++n) _Pragma("unroll") for (int k = 0; k < 2; ++k) \
;     dst[n][k] = *reinterpret_cast<const bf16x8*>((const char*)shm + bB + (((b) * 2 + (h)) * 16384 + (n * 2 + k) * 1024))
; #define WAIT_L(n) asm volatile("s_waitcnt lgkmcnt(" #n ")" ::: "memory")
; #define BAR __builtin_amdgcn_s_barrier()
; #define SCHED __builtin_amdgcn_sched_barrier(0)
; template <int MODE> ...
;     ...
;       LDB(B0, 1, 0); LDB(B1, 1, 1); LDA(At, 1, 0); WAIT_L(0); BAR; MMA2(0, 0, 0, 1); BAR; SCHED;
;       LDA(At, 1, 1); WAIT_L(0); BAR; MMA2(1, 0, 1, 1); BAR; SCHED;
;     }
;     ...
;     if (wr == 0) BAR;
	ds_read_b128 v[64:67], v149 offset:32768
	ds_read_b128 v[184:187], v149 offset:33792
	ds_read_b128 v[188:191], v149 offset:34816
	ds_read_b128 v[208:211], v149 offset:35840
	ds_read_b128 v[212:215], v149 offset:49152
	ds_read_b128 v[216:219], v149 offset:50176
	ds_read_b128 v[232:235], v149 offset:51200
	ds_read_b128 v[236:239], v149 offset:52224
	ds_read_b128 v[8:11], v148 offset:32768
	ds_read_b128 v[52:55], v148 offset:33792
	ds_read_b128 v[60:63], v148 offset:34816
	ds_read_b128 v[68:71], v148 offset:35840
	ds_read_b128 v[76:79], v148 offset:36864
	ds_read_b128 v[80:83], v148 offset:37888
	ds_read_b128 v[240:243], v148 offset:38912
	ds_read_b128 v[244:247], v148 offset:39936
	s_waitcnt lgkmcnt(0)
	s_barrier
	s_setprio 1
	s_waitcnt lgkmcnt(0)
	v_mfma_f32_16x16x32_bf16 v[12:15], v[60:63], v[64:67], v[116:119]
	v_mfma_f32_16x16x32_bf16 v[0:3], v[8:11], v[64:67], v[124:127]
	v_mfma_f32_16x16x32_bf16 v[124:127], v[68:71], v[184:187], v[12:15]
	v_mfma_f32_16x16x32_bf16 v[12:15], v[60:63], v[188:191], v[112:115]
	v_mfma_f32_16x16x32_bf16 v[116:119], v[68:71], v[208:211], v[12:15]
	v_mfma_f32_16x16x32_bf16 v[12:15], v[76:79], v[64:67], v[108:111]
	v_mfma_f32_16x16x32_bf16 v[108:111], v[80:83], v[184:187], v[12:15]
	v_mfma_f32_16x16x32_bf16 v[12:15], v[76:79], v[188:191], v[104:107]
	v_mfma_f32_16x16x32_bf16 v[100:103], v[80:83], v[208:211], v[12:15]
	v_mfma_f32_16x16x32_bf16 v[12:15], v[240:243], v[64:67], v[224:227]
	v_mfma_f32_16x16x32_bf16 v[92:95], v[244:247], v[184:187], v[12:15]
	v_mfma_f32_16x16x32_bf16 v[12:15], v[240:243], v[188:191], v[96:99]
	v_mfma_f32_16x16x32_bf16 v[4:7], v[52:55], v[184:187], v[0:3]
	v_mfma_f32_16x16x32_bf16 v[0:3], v[8:11], v[188:191], v[120:123]
	v_mfma_f32_16x16x32_bf16 v[84:87], v[244:247], v[208:211], v[12:15]
	v_mfma_f32_16x16x32_bf16 v[12:15], v[8:11], v[212:215], v[88:91]
	v_mfma_f32_16x16x32_bf16 v[8:11], v[8:11], v[232:235], v[72:75]
	v_mfma_f32_16x16x32_bf16 v[0:3], v[52:55], v[208:211], v[0:3]
	v_mfma_f32_16x16x32_bf16 v[12:15], v[52:55], v[216:219], v[12:15]
	v_mfma_f32_16x16x32_bf16 v[8:11], v[52:55], v[236:239], v[8:11]
	v_mfma_f32_16x16x32_bf16 v[52:55], v[60:63], v[212:215], v[56:59]
	v_mfma_f32_16x16x32_bf16 v[48:51], v[60:63], v[232:235], v[48:51]
	v_mfma_f32_16x16x32_bf16 v[44:47], v[76:79], v[212:215], v[44:47]
	v_mfma_f32_16x16x32_bf16 v[40:43], v[76:79], v[232:235], v[40:43]
	v_mfma_f32_16x16x32_bf16 v[36:39], v[240:243], v[212:215], v[36:39]
	v_mfma_f32_16x16x32_bf16 v[32:35], v[240:243], v[232:235], v[32:35]
	v_mfma_f32_16x16x32_bf16 v[120:123], v[68:71], v[216:219], v[52:55]
	v_mfma_f32_16x16x32_bf16 v[112:115], v[68:71], v[236:239], v[48:51]
	v_mfma_f32_16x16x32_bf16 v[104:107], v[80:83], v[216:219], v[44:47]
	v_mfma_f32_16x16x32_bf16 v[96:99], v[80:83], v[236:239], v[40:43]
	v_mfma_f32_16x16x32_bf16 v[88:91], v[244:247], v[216:219], v[36:39]
	v_mfma_f32_16x16x32_bf16 v[80:83], v[244:247], v[236:239], v[32:35]
	s_setprio 0
	s_barrier
	s_nop 0
	ds_read_b128 v[32:35], v148 offset:49152
	ds_read_b128 v[40:43], v148 offset:50176
	ds_read_b128 v[48:51], v148 offset:51200
	ds_read_b128 v[224:227], v148 offset:52224
	ds_read_b128 v[240:243], v148 offset:53248
	ds_read_b128 v[244:247], v148 offset:54272
	ds_read_b128 v[248:251], v148 offset:55296
	ds_read_b128 v[130:133], v148 offset:56320
	s_waitcnt lgkmcnt(0)
	s_barrier
	s_setprio 1
	s_waitcnt lgkmcnt(0)
	v_mfma_f32_16x16x32_bf16 v[24:27], v[32:35], v[188:191], v[24:27]
	v_mfma_f32_16x16x32_bf16 v[16:19], v[48:51], v[188:191], v[16:19]
	v_mfma_f32_16x16x32_bf16 v[68:71], v[40:43], v[208:211], v[24:27]
	v_mfma_f32_16x16x32_bf16 v[52:55], v[224:227], v[208:211], v[16:19]
	v_mfma_f32_16x16x32_bf16 v[16:19], v[240:243], v[64:67], v[220:223]
	v_mfma_f32_16x16x32_bf16 v[24:27], v[32:35], v[212:215], v[168:171]
	v_mfma_f32_16x16x32_bf16 v[44:47], v[244:247], v[184:187], v[16:19]
	v_mfma_f32_16x16x32_bf16 v[16:19], v[240:243], v[188:191], v[228:231]
	v_mfma_f32_16x16x32_bf16 v[72:75], v[40:43], v[216:219], v[24:27]
	v_mfma_f32_16x16x32_bf16 v[24:27], v[32:35], v[232:235], v[172:175]
	v_mfma_f32_16x16x32_bf16 v[28:31], v[32:35], v[64:67], v[28:31]
	v_mfma_f32_16x16x32_bf16 v[20:23], v[48:51], v[64:67], v[20:23]
	v_mfma_f32_16x16x32_bf16 v[36:39], v[244:247], v[208:211], v[16:19]
	v_mfma_f32_16x16x32_bf16 v[16:19], v[248:251], v[64:67], v[138:141]
	v_mfma_f32_16x16x32_bf16 v[64:67], v[40:43], v[236:239], v[24:27]
	v_mfma_f32_16x16x32_bf16 v[24:27], v[48:51], v[212:215], v[192:195]
	v_mfma_f32_16x16x32_bf16 v[56:59], v[224:227], v[216:219], v[24:27]
	v_mfma_f32_16x16x32_bf16 v[24:27], v[48:51], v[232:235], v[196:199]
	v_mfma_f32_16x16x32_bf16 v[48:51], v[224:227], v[236:239], v[24:27]
	v_mfma_f32_16x16x32_bf16 v[24:27], v[240:243], v[212:215], v[200:203]
	v_mfma_f32_16x16x32_bf16 v[76:79], v[40:43], v[184:187], v[28:31]
	v_mfma_f32_16x16x32_bf16 v[40:43], v[244:247], v[216:219], v[24:27]
	v_mfma_f32_16x16x32_bf16 v[24:27], v[240:243], v[232:235], v[204:207]
	v_mfma_f32_16x16x32_bf16 v[32:35], v[244:247], v[236:239], v[24:27]
	v_mfma_f32_16x16x32_bf16 v[24:27], v[248:251], v[212:215], v[176:179]
	v_mfma_f32_16x16x32_bf16 v[60:63], v[224:227], v[184:187], v[20:23]
	v_mfma_f32_16x16x32_bf16 v[20:23], v[130:133], v[184:187], v[16:19]
	v_mfma_f32_16x16x32_bf16 v[16:19], v[248:251], v[188:191], v[142:145]
	v_mfma_f32_16x16x32_bf16 v[28:31], v[130:133], v[216:219], v[24:27]
	v_mfma_f32_16x16x32_bf16 v[24:27], v[248:251], v[232:235], v[180:183]
	v_mfma_f32_16x16x32_bf16 v[16:19], v[130:133], v[208:211], v[16:19]
	v_mfma_f32_16x16x32_bf16 v[24:27], v[130:133], v[236:239], v[24:27]
	s_setprio 0
	s_barrier
	s_and_saveexec_b64 s[8:9], s[6:7]
	s_cbranch_execz .LBB0_594
	s_barrier

; #define STAGE(Pp, BASE, br, kt) do { const u16* _g = (BASE) + ((long)(br) * K + (long)(kt) * BK); \
;     __builtin_amdgcn_global_load_lds((const unsigned*)(_g + voff0), (unsigned*)((char*)(Pp) + tb16), 16, 0, 0); \
;     __builtin_amdgcn_global_load_lds((const unsigned*)(_g + voff1), (unsigned*)((char*)(Pp) + tb16 + 8192), 16, 0, 0); } while (0)
; #define LDA(dst, b, h) _Pragma("unroll") for (int m = 0; m < 4; ++m) _Pragma("unroll") for (int k = 0; k < 2; ++k) \
;     dst[m][k] = *reinterpret_cast<const bf16x8*>((const char*)shm + aB + (((b) * 2 + (h)) * 16384 + (m * 2 + k) * 1024))
; #define LDB(dst, b, h) _Pragma("unroll") for (int n = 0; n < 2; ++n) _Pragma("unroll") for (int k = 0; k < 2; ++k) \
;     dst[n][k] = *reinterpret_cast<const bf16x8*>((const char*)shm + bB + (((b) * 2 + (h)) * 16384 + (n * 2 + k) * 1024))
; #define WAIT_V(n) asm volatile("s_waitcnt vmcnt(" #n ")" ::: "memory")
; #define WAIT_L(n) asm volatile("s_waitcnt lgkmcnt(" #n ")" ::: "memory")
; #define BAR __builtin_amdgcn_s_barrier()
; #define SCHED __builtin_amdgcn_sched_barrier(0)
; template <int MODE> ...
;     ...
;     for (int t = 0; t < nt - 2; t += 2) {
;       LDB(B0, 0, 0); LDB(B1, 0, 1); LDA(At, 0, 0); STAGE(SA(1, 1), A, brow + HALF, t + 1);
;       WAIT_L(0); BAR; MMA2(0, 0, 0, 1); BAR; SCHED;
;       LDA(At, 0, 1); STAGE(SB(0, 0), Bt, bcol, t + 2); STAGE(SB(0, 1), Bt, bcol + HALF, t + 2); STAGE(SA(0, 0), A, brow, t + 2);
;       WAIT_V(6); WAIT_L(0); BAR; MMA2(1, 0, 1, 1); BAR; SCHED;
.LBB0_848:
	v_readfirstlane_b32 s64, v167
	s_mov_b32 m0, s64
	ds_read_b128 v[170:173], v151
	ds_read_b128 v[174:177], v151 offset:1024
	ds_read_b128 v[178:181], v151 offset:2048
	ds_read_b128 v[182:185], v151 offset:3072
	ds_read_b128 v[186:189], v151 offset:16384
	ds_read_b128 v[190:193], v151 offset:17408
	ds_read_b128 v[194:197], v151 offset:18432
	ds_read_b128 v[198:201], v151 offset:19456
	ds_read_b128 v[202:205], v150
	ds_read_b128 v[206:209], v150 offset:1024
	ds_read_b128 v[210:213], v150 offset:2048
	ds_read_b128 v[214:217], v150 offset:3072
	ds_read_b128 v[218:221], v150 offset:4096
	ds_read_b128 v[222:225], v150 offset:5120
	ds_read_b128 v[226:229], v150 offset:6144
	ds_read_b128 v[230:233], v150 offset:7168
	s_add_u32 s88, s62, s22
	s_addc_u32 s89, s63, s23
	global_load_lds_dwordx4 v146, s[88:89]
	v_readfirstlane_b32 s64, v168
	s_mov_b32 m0, s64
	s_nop 0
	s_add_u32 s90, s62, s22
	s_addc_u32 s91, s63, s23
	global_load_lds_dwordx4 v148, s[90:91]
	s_waitcnt lgkmcnt(0)
	s_barrier
	s_setprio 1
	s_waitcnt lgkmcnt(0)
	v_mfma_f32_16x16x32_bf16 v[124:127], v[202:205], v[170:173], v[124:127]
	v_mfma_f32_16x16x32_bf16 v[120:123], v[202:205], v[178:181], v[120:123]
	v_mfma_f32_16x16x32_bf16 v[116:119], v[210:213], v[170:173], v[116:119]
	v_mfma_f32_16x16x32_bf16 v[112:115], v[210:213], v[178:181], v[112:115]
	v_mfma_f32_16x16x32_bf16 v[108:111], v[218:221], v[170:173], v[108:111]
	v_mfma_f32_16x16x32_bf16 v[104:107], v[218:221], v[178:181], v[104:107]
	v_mfma_f32_16x16x32_bf16 v[100:103], v[226:229], v[170:173], v[100:103]
	v_mfma_f32_16x16x32_bf16 v[96:99], v[226:229], v[178:181], v[96:99]
	v_mfma_f32_16x16x32_bf16 v[92:95], v[202:205], v[186:189], v[92:95]
	v_mfma_f32_16x16x32_bf16 v[88:91], v[202:205], v[194:197], v[88:91]
	v_mfma_f32_16x16x32_bf16 v[84:87], v[210:213], v[186:189], v[84:87]
	v_mfma_f32_16x16x32_bf16 v[80:83], v[210:213], v[194:197], v[80:83]
	v_mfma_f32_16x16x32_bf16 v[76:79], v[218:221], v[186:189], v[76:79]
	v_mfma_f32_16x16x32_bf16 v[72:75], v[218:221], v[194:197], v[72:75]
	v_mfma_f32_16x16x32_bf16 v[68:71], v[226:229], v[186:189], v[68:71]
	v_mfma_f32_16x16x32_bf16 v[64:67], v[226:229], v[194:197], v[64:67]
	v_mfma_f32_16x16x32_bf16 v[124:127], v[206:209], v[174:177], v[124:127]
	v_mfma_f32_16x16x32_bf16 v[120:123], v[206:209], v[182:185], v[120:123]
	v_mfma_f32_16x16x32_bf16 v[116:119], v[214:217], v[174:177], v[116:119]
	v_mfma_f32_16x16x32_bf16 v[112:115], v[214:217], v[182:185], v[112:115]
	v_mfma_f32_16x16x32_bf16 v[108:111], v[222:225], v[174:177], v[108:111]
	v_mfma_f32_16x16x32_bf16 v[104:107], v[222:225], v[182:185], v[104:107]
	v_mfma_f32_16x16x32_bf16 v[100:103], v[230:233], v[174:177], v[100:103]
	v_mfma_f32_16x16x32_bf16 v[96:99], v[230:233], v[182:185], v[96:99]
	v_mfma_f32_16x16x32_bf16 v[92:95], v[206:209], v[190:193], v[92:95]
	v_mfma_f32_16x16x32_bf16 v[88:91], v[206:209], v[198:201], v[88:91]
	v_mfma_f32_16x16x32_bf16 v[84:87], v[214:217], v[190:193], v[84:87]
	v_mfma_f32_16x16x32_bf16 v[80:83], v[214:217], v[198:201], v[80:83]
	v_mfma_f32_16x16x32_bf16 v[76:79], v[222:225], v[190:193], v[76:79]
	v_mfma_f32_16x16x32_bf16 v[72:75], v[222:225], v[198:201], v[72:75]
	v_mfma_f32_16x16x32_bf16 v[68:71], v[230:233], v[190:193], v[68:71]
	v_mfma_f32_16x16x32_bf16 v[64:67], v[230:233], v[198:201], v[64:67]
	s_setprio 0
	s_barrier
	v_readfirstlane_b32 s64, v153
	s_mov_b32 m0, s64
	ds_read_b128 v[202:205], v150 offset:16384
	ds_read_b128 v[206:209], v150 offset:17408
	ds_read_b128 v[210:213], v150 offset:18432
	ds_read_b128 v[214:217], v150 offset:19456
	ds_read_b128 v[218:221], v150 offset:20480
	ds_read_b128 v[222:225], v150 offset:21504
	ds_read_b128 v[226:229], v150 offset:22528
	ds_read_b128 v[230:233], v150 offset:23552
	s_add_u32 s92, s62, s24
	s_addc_u32 s93, s63, s25
	global_load_lds_dwordx4 v138, s[92:93]
	v_readfirstlane_b32 s64, v154
	s_mov_b32 m0, s64
	v_readfirstlane_b32 s64, v156
	s_add_u32 s96, s62, s24
	s_addc_u32 s97, s63, s25
	global_load_lds_dwordx4 v140, s[96:97]
	s_mov_b32 m0, s64
	v_readfirstlane_b32 s64, v157
	s_add_u32 s88, s62, s26
	s_addc_u32 s89, s63, s27
	global_load_lds_dwordx4 v142, s[88:89]
	s_mov_b32 m0, s64
	v_readfirstlane_b32 s64, v152
	s_add_u32 s90, s62, s26
	s_addc_u32 s91, s63, s27
	global_load_lds_dwordx4 v144, s[90:91]
	s_mov_b32 m0, s64
	v_readfirstlane_b32 s64, v155
	s_add_u32 s92, s62, s28
	s_addc_u32 s93, s63, s29
	global_load_lds_dwordx4 v146, s[92:93]
	s_mov_b32 m0, s64
	s_nop 0
	s_add_u32 s96, s62, s28
	s_addc_u32 s97, s63, s29
	global_load_lds_dwordx4 v148, s[96:97]
	s_waitcnt vmcnt(6)
	s_waitcnt lgkmcnt(0)
	s_barrier
; #define STAGE(Pp, BASE, br, kt) do { const u16* _g = (BASE) + ((long)(br) * K + (long)(kt) * BK); \
;     __builtin_amdgcn_global_load_lds((const unsigned*)(_g + voff0), (unsigned*)((char*)(Pp) + tb16), 16, 0, 0); \
;     __builtin_amdgcn_global_load_lds((const unsigned*)(_g + voff1), (unsigned*)((char*)(Pp) + tb16 + 8192), 16, 0, 0); } while (0)
; #define LDA(dst, b, h) _Pragma("unroll") for (int m = 0; m < 4; ++m) _Pragma("unroll") for (int k = 0; k < 2; ++k) \
;     dst[m][k] = *reinterpret_cast<const bf16x8*>((const char*)shm + aB + (((b) * 2 + (h)) * 16384 + (m * 2 + k) * 1024))
; #define LDB(dst, b, h) _Pragma("unroll") for (int n = 0; n < 2; ++n) _Pragma("unroll") for (int k = 0; k < 2; ++k) \
;     dst[n][k] = *reinterpret_cast<const bf16x8*>((const char*)shm + bB + (((b) * 2 + (h)) * 16384 + (n * 2 + k) * 1024))
; #define WAIT_V(n) asm volatile("s_waitcnt vmcnt(" #n ")" ::: "memory")
; #define WAIT_L(n) asm volatile("s_waitcnt lgkmcnt(" #n ")" ::: "memory")
; #define BAR __builtin_amdgcn_s_barrier()
; #define SCHED __builtin_amdgcn_sched_barrier(0)
; template <int MODE> ...
;     ...
;       WAIT_V(6); WAIT_L(0); BAR; MMA2(1, 0, 1, 1); BAR; SCHED;
;       LDB(B0, 1, 0); LDB(B1, 1, 1); LDA(At, 1, 0); STAGE(SA(0, 1), A, brow + HALF, t + 2);
;       WAIT_L(0); BAR; MMA2(0, 0, 0, 1); BAR; SCHED;
	s_setprio 1
	s_waitcnt lgkmcnt(0)
	v_mfma_f32_16x16x32_bf16 v[60:63], v[202:205], v[170:173], v[60:63]
	v_mfma_f32_16x16x32_bf16 v[56:59], v[202:205], v[178:181], v[56:59]
	v_mfma_f32_16x16x32_bf16 v[52:55], v[210:213], v[170:173], v[52:55]
	v_mfma_f32_16x16x32_bf16 v[48:51], v[210:213], v[178:181], v[48:51]
	v_mfma_f32_16x16x32_bf16 v[44:47], v[218:221], v[170:173], v[44:47]
	v_mfma_f32_16x16x32_bf16 v[40:43], v[218:221], v[178:181], v[40:43]
	v_mfma_f32_16x16x32_bf16 v[36:39], v[226:229], v[170:173], v[36:39]
	v_mfma_f32_16x16x32_bf16 v[32:35], v[226:229], v[178:181], v[32:35]
	v_mfma_f32_16x16x32_bf16 v[28:31], v[202:205], v[186:189], v[28:31]
	v_mfma_f32_16x16x32_bf16 v[24:27], v[202:205], v[194:197], v[24:27]
	v_mfma_f32_16x16x32_bf16 v[20:23], v[210:213], v[186:189], v[20:23]
	v_mfma_f32_16x16x32_bf16 v[16:19], v[210:213], v[194:197], v[16:19]
	v_mfma_f32_16x16x32_bf16 v[12:15], v[218:221], v[186:189], v[12:15]
	v_mfma_f32_16x16x32_bf16 v[8:11], v[218:221], v[194:197], v[8:11]
	v_mfma_f32_16x16x32_bf16 v[4:7], v[226:229], v[186:189], v[4:7]
	v_mfma_f32_16x16x32_bf16 v[0:3], v[226:229], v[194:197], v[0:3]
	v_mfma_f32_16x16x32_bf16 v[60:63], v[206:209], v[174:177], v[60:63]
	v_mfma_f32_16x16x32_bf16 v[56:59], v[206:209], v[182:185], v[56:59]
	v_mfma_f32_16x16x32_bf16 v[52:55], v[214:217], v[174:177], v[52:55]
	v_mfma_f32_16x16x32_bf16 v[48:51], v[214:217], v[182:185], v[48:51]
	v_mfma_f32_16x16x32_bf16 v[44:47], v[222:225], v[174:177], v[44:47]
	v_mfma_f32_16x16x32_bf16 v[40:43], v[222:225], v[182:185], v[40:43]
	v_mfma_f32_16x16x32_bf16 v[36:39], v[230:233], v[174:177], v[36:39]
	v_mfma_f32_16x16x32_bf16 v[32:35], v[230:233], v[182:185], v[32:35]
	v_mfma_f32_16x16x32_bf16 v[28:31], v[206:209], v[190:193], v[28:31]
	v_mfma_f32_16x16x32_bf16 v[24:27], v[206:209], v[198:201], v[24:27]
	v_mfma_f32_16x16x32_bf16 v[20:23], v[214:217], v[190:193], v[20:23]
	v_mfma_f32_16x16x32_bf16 v[16:19], v[214:217], v[198:201], v[16:19]
	v_mfma_f32_16x16x32_bf16 v[12:15], v[222:225], v[190:193], v[12:15]
	v_mfma_f32_16x16x32_bf16 v[8:11], v[222:225], v[198:201], v[8:11]
	v_mfma_f32_16x16x32_bf16 v[4:7], v[230:233], v[190:193], v[4:7]
	v_mfma_f32_16x16x32_bf16 v[0:3], v[230:233], v[198:201], v[0:3]
	s_setprio 0
	s_barrier
	v_readfirstlane_b32 s64, v158
	s_mov_b32 m0, s64
	v_readfirstlane_b32 s64, v159
	ds_read_b128 v[170:173], v151 offset:32768
	ds_read_b128 v[174:177], v151 offset:33792
	ds_read_b128 v[178:181], v151 offset:34816
	ds_read_b128 v[182:185], v151 offset:35840
	ds_read_b128 v[186:189], v151 offset:49152
	ds_read_b128 v[190:193], v151 offset:50176
	ds_read_b128 v[194:197], v151 offset:51200
	ds_read_b128 v[198:201], v151 offset:52224
	ds_read_b128 v[202:205], v150 offset:32768
	ds_read_b128 v[206:209], v150 offset:33792
	ds_read_b128 v[210:213], v150 offset:34816
	ds_read_b128 v[214:217], v150 offset:35840
	ds_read_b128 v[218:221], v150 offset:36864
	ds_read_b128 v[222:225], v150 offset:37888
	ds_read_b128 v[226:229], v150 offset:38912
	ds_read_b128 v[230:233], v150 offset:39936
	s_add_u32 s88, s62, s36
	s_addc_u32 s89, s63, s37
	global_load_lds_dwordx4 v146, s[88:89]
	s_mov_b32 m0, s64
	s_nop 0
	s_add_u32 s90, s62, s36
	s_addc_u32 s91, s63, s37
	global_load_lds_dwordx4 v148, s[90:91]
	s_waitcnt lgkmcnt(0)
	s_barrier
	s_setprio 1
	s_waitcnt lgkmcnt(0)
	v_mfma_f32_16x16x32_bf16 v[124:127], v[202:205], v[170:173], v[124:127]
	v_mfma_f32_16x16x32_bf16 v[120:123], v[202:205], v[178:181], v[120:123]
	v_mfma_f32_16x16x32_bf16 v[116:119], v[210:213], v[170:173], v[116:119]
	v_mfma_f32_16x16x32_bf16 v[112:115], v[210:213], v[178:181], v[112:115]
	v_mfma_f32_16x16x32_bf16 v[108:111], v[218:221], v[170:173], v[108:111]
	v_mfma_f32_16x16x32_bf16 v[104:107], v[218:221], v[178:181], v[104:107]
	v_mfma_f32_16x16x32_bf16 v[100:103], v[226:229], v[170:173], v[100:103]
	v_mfma_f32_16x16x32_bf16 v[96:99], v[226:229], v[178:181], v[96:99]
	v_mfma_f32_16x16x32_bf16 v[92:95], v[202:205], v[186:189], v[92:95]
	v_mfma_f32_16x16x32_bf16 v[88:91], v[202:205], v[194:197], v[88:91]
	v_mfma_f32_16x16x32_bf16 v[84:87], v[210:213], v[186:189], v[84:87]
	v_mfma_f32_16x16x32_bf16 v[80:83], v[210:213], v[194:197], v[80:83]
	v_mfma_f32_16x16x32_bf16 v[76:79], v[218:221], v[186:189], v[76:79]
	v_mfma_f32_16x16x32_bf16 v[72:75], v[218:221], v[194:197], v[72:75]
	v_mfma_f32_16x16x32_bf16 v[68:71], v[226:229], v[186:189], v[68:71]
	v_mfma_f32_16x16x32_bf16 v[64:67], v[226:229], v[194:197], v[64:67]
	v_mfma_f32_16x16x32_bf16 v[124:127], v[206:209], v[174:177], v[124:127]
	v_mfma_f32_16x16x32_bf16 v[120:123], v[206:209], v[182:185], v[120:123]
	v_mfma_f32_16x16x32_bf16 v[116:119], v[214:217], v[174:177], v[116:119]
	v_mfma_f32_16x16x32_bf16 v[112:115], v[214:217], v[182:185], v[112:115]
	v_mfma_f32_16x16x32_bf16 v[108:111], v[222:225], v[174:177], v[108:111]
	v_mfma_f32_16x16x32_bf16 v[104:107], v[222:225], v[182:185], v[104:107]
	v_mfma_f32_16x16x32_bf16 v[100:103], v[230:233], v[174:177], v[100:103]
	v_mfma_f32_16x16x32_bf16 v[96:99], v[230:233], v[182:185], v[96:99]
	v_mfma_f32_16x16x32_bf16 v[92:95], v[206:209], v[190:193], v[92:95]
	v_mfma_f32_16x16x32_bf16 v[88:91], v[206:209], v[198:201], v[88:91]
	v_mfma_f32_16x16x32_bf16 v[84:87], v[214:217], v[190:193], v[84:87]
	v_mfma_f32_16x16x32_bf16 v[80:83], v[214:217], v[198:201], v[80:83]
	v_mfma_f32_16x16x32_bf16 v[76:79], v[222:225], v[190:193], v[76:79]
	v_mfma_f32_16x16x32_bf16 v[72:75], v[222:225], v[198:201], v[72:75]
	v_mfma_f32_16x16x32_bf16 v[68:71], v[230:233], v[190:193], v[68:71]
	v_mfma_f32_16x16x32_bf16 v[64:67], v[230:233], v[198:201], v[64:67]
	s_setprio 0
	s_barrier
; #define STAGE(Pp, BASE, br, kt) do { const u16* _g = (BASE) + ((long)(br) * K + (long)(kt) * BK); \
;     __builtin_amdgcn_global_load_lds((const unsigned*)(_g + voff0), (unsigned*)((char*)(Pp) + tb16), 16, 0, 0); \
;     __builtin_amdgcn_global_load_lds((const unsigned*)(_g + voff1), (unsigned*)((char*)(Pp) + tb16 + 8192), 16, 0, 0); } while (0)
; #define LDA(dst, b, h) _Pragma("unroll") for (int m = 0; m < 4; ++m) _Pragma("unroll") for (int k = 0; k < 2; ++k) \
;     dst[m][k] = *reinterpret_cast<const bf16x8*>((const char*)shm + aB + (((b) * 2 + (h)) * 16384 + (m * 2 + k) * 1024))
; #define LDB(dst, b, h) _Pragma("unroll") for (int n = 0; n < 2; ++n) _Pragma("unroll") for (int k = 0; k < 2; ++k) \
;     dst[n][k] = *reinterpret_cast<const bf16x8*>((const char*)shm + bB + (((b) * 2 + (h)) * 16384 + (n * 2 + k) * 1024))
; #define WAIT_V(n) asm volatile("s_waitcnt vmcnt(" #n ")" ::: "memory")
; #define WAIT_L(n) asm volatile("s_waitcnt lgkmcnt(" #n ")" ::: "memory")
; #define BAR __builtin_amdgcn_s_barrier()
; #define SCHED __builtin_amdgcn_sched_barrier(0)
; template <int MODE> ...
;     ...
;       LDA(At, 1, 1); STAGE(SB(1, 0), Bt, bcol, t + 3); STAGE(SB(1, 1), Bt, bcol + HALF, t + 3); STAGE(SA(1, 0), A, brow, t + 3);
;       WAIT_V(6); WAIT_L(0); BAR; MMA2(1, 0, 1, 1); BAR; SCHED;
;     }
;     {
;       LDB(B0, 0, 0); LDB(B1, 0, 1); LDA(At, 0, 0); STAGE(SA(1, 1), A, brow + HALF, nt - 1);
;       WAIT_L(0); BAR; MMA2(0, 0, 0, 1); BAR; SCHED;
	v_readfirstlane_b32 s64, v160
	s_mov_b32 m0, s64
	v_readfirstlane_b32 s64, v161
	ds_read_b128 v[202:205], v150 offset:49152
	ds_read_b128 v[206:209], v150 offset:50176
	ds_read_b128 v[210:213], v150 offset:51200
	ds_read_b128 v[214:217], v150 offset:52224
	ds_read_b128 v[218:221], v150 offset:53248
	ds_read_b128 v[222:225], v150 offset:54272
	ds_read_b128 v[226:229], v150 offset:55296
	ds_read_b128 v[230:233], v150 offset:56320
	s_add_u32 s92, s62, s38
	s_addc_u32 s93, s63, s39
	global_load_lds_dwordx4 v138, s[92:93]
	s_mov_b32 m0, s64
	v_readfirstlane_b32 s64, v165
	s_add_u32 s96, s62, s38
	s_addc_u32 s97, s63, s39
	global_load_lds_dwordx4 v140, s[96:97]
	s_mov_b32 m0, s64
	v_readfirstlane_b32 s64, v166
	s_add_u32 s88, s62, s40
	s_addc_u32 s89, s63, s41
	global_load_lds_dwordx4 v142, s[88:89]
	s_mov_b32 m0, s64
	v_readfirstlane_b32 s64, v162
	s_add_u32 s90, s62, s40
	s_addc_u32 s91, s63, s41
	global_load_lds_dwordx4 v144, s[90:91]
	s_mov_b32 m0, s64
	v_readfirstlane_b32 s64, v163
	s_add_u32 s92, s62, s42
	s_addc_u32 s93, s63, s43
	global_load_lds_dwordx4 v146, s[92:93]
	s_mov_b32 m0, s64
	s_nop 0
	s_add_u32 s96, s62, s42
	s_addc_u32 s97, s63, s43
	global_load_lds_dwordx4 v148, s[96:97]
	s_waitcnt vmcnt(6)
	s_waitcnt lgkmcnt(0)
	s_barrier
	s_setprio 1
	s_waitcnt lgkmcnt(0)
	v_mfma_f32_16x16x32_bf16 v[60:63], v[202:205], v[170:173], v[60:63]
	v_mfma_f32_16x16x32_bf16 v[56:59], v[202:205], v[178:181], v[56:59]
	v_mfma_f32_16x16x32_bf16 v[52:55], v[210:213], v[170:173], v[52:55]
	v_mfma_f32_16x16x32_bf16 v[48:51], v[210:213], v[178:181], v[48:51]
	v_mfma_f32_16x16x32_bf16 v[44:47], v[218:221], v[170:173], v[44:47]
	v_mfma_f32_16x16x32_bf16 v[40:43], v[218:221], v[178:181], v[40:43]
	v_mfma_f32_16x16x32_bf16 v[36:39], v[226:229], v[170:173], v[36:39]
	v_mfma_f32_16x16x32_bf16 v[32:35], v[226:229], v[178:181], v[32:35]
	v_mfma_f32_16x16x32_bf16 v[28:31], v[202:205], v[186:189], v[28:31]
	v_mfma_f32_16x16x32_bf16 v[24:27], v[202:205], v[194:197], v[24:27]
	v_mfma_f32_16x16x32_bf16 v[20:23], v[210:213], v[186:189], v[20:23]
	v_mfma_f32_16x16x32_bf16 v[16:19], v[210:213], v[194:197], v[16:19]
	v_mfma_f32_16x16x32_bf16 v[12:15], v[218:221], v[186:189], v[12:15]
	v_mfma_f32_16x16x32_bf16 v[8:11], v[218:221], v[194:197], v[8:11]
	v_mfma_f32_16x16x32_bf16 v[4:7], v[226:229], v[186:189], v[4:7]
	v_mfma_f32_16x16x32_bf16 v[0:3], v[226:229], v[194:197], v[0:3]
	v_mfma_f32_16x16x32_bf16 v[60:63], v[206:209], v[174:177], v[60:63]
	v_mfma_f32_16x16x32_bf16 v[56:59], v[206:209], v[182:185], v[56:59]
	v_mfma_f32_16x16x32_bf16 v[52:55], v[214:217], v[174:177], v[52:55]
	v_mfma_f32_16x16x32_bf16 v[48:51], v[214:217], v[182:185], v[48:51]
	v_mfma_f32_16x16x32_bf16 v[44:47], v[222:225], v[174:177], v[44:47]
	v_mfma_f32_16x16x32_bf16 v[40:43], v[222:225], v[182:185], v[40:43]
	v_mfma_f32_16x16x32_bf16 v[36:39], v[230:233], v[174:177], v[36:39]
	v_mfma_f32_16x16x32_bf16 v[32:35], v[230:233], v[182:185], v[32:35]
	v_mfma_f32_16x16x32_bf16 v[28:31], v[206:209], v[190:193], v[28:31]
	v_mfma_f32_16x16x32_bf16 v[24:27], v[206:209], v[198:201], v[24:27]
	v_mfma_f32_16x16x32_bf16 v[20:23], v[214:217], v[190:193], v[20:23]
	v_mfma_f32_16x16x32_bf16 v[16:19], v[214:217], v[198:201], v[16:19]
	v_mfma_f32_16x16x32_bf16 v[12:15], v[222:225], v[190:193], v[12:15]
	v_mfma_f32_16x16x32_bf16 v[8:11], v[222:225], v[198:201], v[8:11]
	v_mfma_f32_16x16x32_bf16 v[4:7], v[230:233], v[190:193], v[4:7]
	v_mfma_f32_16x16x32_bf16 v[0:3], v[230:233], v[198:201], v[0:3]
	s_setprio 0
	s_barrier
	s_add_i32 s45, s45, 2
	s_add_u32 s62, s62, 0x100
	s_addc_u32 s63, s63, 0
	s_cmpk_lt_u32 s45, 0xa8
	s_cbranch_scc1 .LBB0_848
	s_add_u32 s60, s60, 0x5580
	v_readfirstlane_b32 s45, v167
	s_addc_u32 s61, s61, 0
	s_mov_b32 m0, s45
	v_readfirstlane_b32 s45, v168
	ds_read_b128 v[138:141], v151
	ds_read_b128 v[142:145], v151 offset:1024
	ds_read_b128 v[146:149], v151 offset:2048
	ds_read_b128 v[170:173], v151 offset:3072
	ds_read_b128 v[174:177], v151 offset:16384
	ds_read_b128 v[178:181], v151 offset:17408
	ds_read_b128 v[182:185], v151 offset:18432
	ds_read_b128 v[186:189], v151 offset:19456
	ds_read_b128 v[190:193], v150
	ds_read_b128 v[194:197], v150 offset:1024
	ds_read_b128 v[198:201], v150 offset:2048
	ds_read_b128 v[202:205], v150 offset:3072
	ds_read_b128 v[206:209], v150 offset:4096
	ds_read_b128 v[210:213], v150 offset:5120
	ds_read_b128 v[214:217], v150 offset:6144
	ds_read_b128 v[218:221], v150 offset:7168
	global_load_lds_dwordx4 v134, s[60:61]
	s_mov_b32 m0, s45
	s_nop 0
	global_load_lds_dwordx4 v136, s[60:61]
	s_waitcnt lgkmcnt(0)
	s_barrier
; #define LDA(dst, b, h) _Pragma("unroll") for (int m = 0; m < 4; ++m) _Pragma("unroll") for (int k = 0; k < 2; ++k) \
;     dst[m][k] = *reinterpret_cast<const bf16x8*>((const char*)shm + aB + (((b) * 2 + (h)) * 16384 + (m * 2 + k) * 1024))
; #define WAIT_V(n) asm volatile("s_waitcnt vmcnt(" #n ")" ::: "memory")
; #define WAIT_L(n) asm volatile("s_waitcnt lgkmcnt(" #n ")" ::: "memory")
; #define BAR __builtin_amdgcn_s_barrier()
; #define SCHED __builtin_amdgcn_sched_barrier(0)
; template <int MODE> ...
;     ...
;       WAIT_L(0); BAR; MMA2(0, 0, 0, 1); BAR; SCHED;
;       LDA(At, 0, 1); WAIT_V(0); WAIT_L(0); BAR; MMA2(1, 0, 1, 1); BAR; SCHED;
	s_setprio 1
	s_waitcnt lgkmcnt(0)
	v_mfma_f32_16x16x32_bf16 v[124:127], v[190:193], v[138:141], v[124:127]
	v_mfma_f32_16x16x32_bf16 v[116:119], v[198:201], v[138:141], v[116:119]
	v_mfma_f32_16x16x32_bf16 v[108:111], v[206:209], v[138:141], v[108:111]
	v_mfma_f32_16x16x32_bf16 v[100:103], v[214:217], v[138:141], v[100:103]
	v_mfma_f32_16x16x32_bf16 v[96:99], v[214:217], v[146:149], v[96:99]
	v_mfma_f32_16x16x32_bf16 v[92:95], v[190:193], v[174:177], v[92:95]
	v_mfma_f32_16x16x32_bf16 v[88:91], v[190:193], v[182:185], v[88:91]
	v_mfma_f32_16x16x32_bf16 v[80:83], v[198:201], v[182:185], v[80:83]
	v_mfma_f32_16x16x32_bf16 v[76:79], v[206:209], v[174:177], v[76:79]
	v_mfma_f32_16x16x32_bf16 v[124:127], v[194:197], v[142:145], v[124:127]
	v_mfma_f32_16x16x32_bf16 v[120:123], v[190:193], v[146:149], v[120:123]
	v_mfma_f32_16x16x32_bf16 v[116:119], v[202:205], v[142:145], v[116:119]
	v_mfma_f32_16x16x32_bf16 v[112:115], v[198:201], v[146:149], v[112:115]
	v_mfma_f32_16x16x32_bf16 v[108:111], v[210:213], v[142:145], v[108:111]
	v_mfma_f32_16x16x32_bf16 v[104:107], v[206:209], v[146:149], v[104:107]
	v_mfma_f32_16x16x32_bf16 v[100:103], v[218:221], v[142:145], v[100:103]
	v_mfma_f32_16x16x32_bf16 v[96:99], v[218:221], v[170:173], v[96:99]
	v_mfma_f32_16x16x32_bf16 v[92:95], v[194:197], v[178:181], v[92:95]
	v_mfma_f32_16x16x32_bf16 v[88:91], v[194:197], v[186:189], v[88:91]
	v_mfma_f32_16x16x32_bf16 v[84:87], v[198:201], v[174:177], v[84:87]
	v_mfma_f32_16x16x32_bf16 v[80:83], v[202:205], v[186:189], v[80:83]
	v_mfma_f32_16x16x32_bf16 v[76:79], v[210:213], v[178:181], v[76:79]
	v_mfma_f32_16x16x32_bf16 v[72:75], v[206:209], v[182:185], v[72:75]
	v_mfma_f32_16x16x32_bf16 v[68:71], v[214:217], v[174:177], v[68:71]
	v_mfma_f32_16x16x32_bf16 v[64:67], v[214:217], v[182:185], v[64:67]
	v_mfma_f32_16x16x32_bf16 v[222:225], v[194:197], v[170:173], v[120:123]
	v_mfma_f32_16x16x32_bf16 v[226:229], v[202:205], v[170:173], v[112:115]
	v_mfma_f32_16x16x32_bf16 v[230:233], v[210:213], v[170:173], v[104:107]
	v_mfma_f32_16x16x32_bf16 v[190:193], v[202:205], v[178:181], v[84:87]
	v_mfma_f32_16x16x32_bf16 v[194:197], v[210:213], v[186:189], v[72:75]
	v_mfma_f32_16x16x32_bf16 v[198:201], v[218:221], v[178:181], v[68:71]
	v_mfma_f32_16x16x32_bf16 v[202:205], v[218:221], v[186:189], v[64:67]
	s_setprio 0
	s_barrier
	s_nop 0
	ds_read_b128 v[64:67], v150 offset:16384
	ds_read_b128 v[68:71], v150 offset:17408
	ds_read_b128 v[72:75], v150 offset:18432
	ds_read_b128 v[84:87], v150 offset:19456
	ds_read_b128 v[104:107], v150 offset:20480
	ds_read_b128 v[112:115], v150 offset:21504
	ds_read_b128 v[120:123], v150 offset:22528
	ds_read_b128 v[206:209], v150 offset:23552
	s_waitcnt vmcnt(0)
	s_waitcnt lgkmcnt(0)
	s_barrier
	s_setprio 1
	s_waitcnt lgkmcnt(0)
	v_mfma_f32_16x16x32_bf16 v[60:63], v[64:67], v[138:141], v[60:63]
	v_mfma_f32_16x16x32_bf16 v[56:59], v[64:67], v[146:149], v[56:59]
	v_mfma_f32_16x16x32_bf16 v[52:55], v[72:75], v[138:141], v[52:55]
	v_mfma_f32_16x16x32_bf16 v[48:51], v[72:75], v[146:149], v[48:51]
	v_mfma_f32_16x16x32_bf16 v[44:47], v[104:107], v[138:141], v[44:47]
	v_mfma_f32_16x16x32_bf16 v[40:43], v[104:107], v[146:149], v[40:43]
	v_mfma_f32_16x16x32_bf16 v[28:31], v[64:67], v[174:177], v[28:31]
	v_mfma_f32_16x16x32_bf16 v[24:27], v[64:67], v[182:185], v[24:27]
	v_mfma_f32_16x16x32_bf16 v[20:23], v[72:75], v[174:177], v[20:23]
	v_mfma_f32_16x16x32_bf16 v[60:63], v[68:71], v[142:145], v[60:63]
	v_mfma_f32_16x16x32_bf16 v[56:59], v[68:71], v[170:173], v[56:59]
	v_mfma_f32_16x16x32_bf16 v[52:55], v[84:87], v[142:145], v[52:55]
	v_mfma_f32_16x16x32_bf16 v[48:51], v[84:87], v[170:173], v[48:51]
	v_mfma_f32_16x16x32_bf16 v[44:47], v[112:115], v[142:145], v[44:47]
	v_mfma_f32_16x16x32_bf16 v[40:43], v[112:115], v[170:173], v[40:43]
	v_mfma_f32_16x16x32_bf16 v[36:39], v[120:123], v[138:141], v[36:39]
	v_mfma_f32_16x16x32_bf16 v[32:35], v[120:123], v[146:149], v[32:35]
	v_mfma_f32_16x16x32_bf16 v[28:31], v[68:71], v[178:181], v[28:31]
	v_mfma_f32_16x16x32_bf16 v[24:27], v[68:71], v[186:189], v[24:27]
	v_mfma_f32_16x16x32_bf16 v[20:23], v[84:87], v[178:181], v[20:23]
	v_mfma_f32_16x16x32_bf16 v[16:19], v[72:75], v[182:185], v[16:19]
	v_mfma_f32_16x16x32_bf16 v[12:15], v[104:107], v[174:177], v[12:15]
	v_mfma_f32_16x16x32_bf16 v[8:11], v[104:107], v[182:185], v[8:11]
	v_mfma_f32_16x16x32_bf16 v[4:7], v[120:123], v[174:177], v[4:7]
	v_mfma_f32_16x16x32_bf16 v[0:3], v[120:123], v[182:185], v[0:3]
	v_mfma_f32_16x16x32_bf16 v[138:141], v[206:209], v[142:145], v[36:39]
	v_mfma_f32_16x16x32_bf16 v[142:145], v[206:209], v[170:173], v[32:35]
	v_mfma_f32_16x16x32_bf16 v[146:149], v[84:87], v[186:189], v[16:19]
	v_mfma_f32_16x16x32_bf16 v[170:173], v[112:115], v[178:181], v[12:15]
	v_mfma_f32_16x16x32_bf16 v[210:213], v[112:115], v[186:189], v[8:11]
	v_mfma_f32_16x16x32_bf16 v[174:177], v[206:209], v[178:181], v[4:7]
	v_mfma_f32_16x16x32_bf16 v[178:181], v[206:209], v[186:189], v[0:3]
	s_setprio 0
	s_barrier
; #define LDA(dst, b, h) _Pragma("unroll") for (int m = 0; m < 4; ++m) _Pragma("unroll") for (int k = 0; k < 2; ++k) \
;     dst[m][k] = *reinterpret_cast<const bf16x8*>((const char*)shm + aB + (((b) * 2 + (h)) * 16384 + (m * 2 + k) * 1024))
; #define LDB(dst, b, h) _Pragma("unroll") for (int n = 0; n < 2; ++n) _Pragma("unroll") for (int k = 0; k < 2; ++k) \
;     dst[n][k] = *reinterpret_cast<const bf16x8*>((const char*)shm + bB + (((b) * 2 + (h)) * 16384 + (n * 2 + k) * 1024))
; #define WAIT_L(n) asm volatile("s_waitcnt lgkmcnt(" #n ")" ::: "memory")
; #define BAR __builtin_amdgcn_s_barrier()
; #define SCHED __builtin_amdgcn_sched_barrier(0)
; template <int MODE> ...
;     ...
;       LDB(B0, 1, 0); LDB(B1, 1, 1); LDA(At, 1, 0); WAIT_L(0); BAR; MMA2(0, 0, 0, 1); BAR; SCHED;
;       LDA(At, 1, 1); WAIT_L(0); BAR; MMA2(1, 0, 1, 1); BAR; SCHED;
;     }
;     ...
;     if (wr == 0) BAR;
	ds_read_b128 v[12:15], v151 offset:32768
	ds_read_b128 v[16:19], v151 offset:33792
	ds_read_b128 v[182:185], v151 offset:34816
	ds_read_b128 v[186:189], v151 offset:35840
	ds_read_b128 v[206:209], v151 offset:49152
	ds_read_b128 v[214:217], v151 offset:50176
	ds_read_b128 v[218:221], v151 offset:51200
	ds_read_b128 v[234:237], v151 offset:52224
	ds_read_b128 v[0:3], v150 offset:32768
	ds_read_b128 v[4:7], v150 offset:33792
	ds_read_b128 v[8:11], v150 offset:34816
	ds_read_b128 v[32:35], v150 offset:35840
	ds_read_b128 v[36:39], v150 offset:36864
	ds_read_b128 v[238:241], v150 offset:37888
	ds_read_b128 v[242:245], v150 offset:38912
	ds_read_b128 v[246:249], v150 offset:39936
	s_waitcnt lgkmcnt(0)
	s_barrier
	s_setprio 1
	s_waitcnt lgkmcnt(0)
	v_mfma_f32_16x16x32_bf16 v[64:67], v[0:3], v[12:15], v[124:127]
	v_mfma_f32_16x16x32_bf16 v[68:71], v[242:245], v[182:185], v[96:99]
	v_mfma_f32_16x16x32_bf16 v[120:123], v[4:7], v[16:19], v[64:67]
	v_mfma_f32_16x16x32_bf16 v[64:67], v[0:3], v[182:185], v[222:225]
	v_mfma_f32_16x16x32_bf16 v[84:87], v[246:249], v[186:189], v[68:71]
	v_mfma_f32_16x16x32_bf16 v[68:71], v[0:3], v[206:209], v[92:95]
	v_mfma_f32_16x16x32_bf16 v[0:3], v[0:3], v[218:221], v[88:91]
	v_mfma_f32_16x16x32_bf16 v[88:91], v[4:7], v[234:237], v[0:3]
	v_mfma_f32_16x16x32_bf16 v[0:3], v[8:11], v[206:209], v[190:193]
	v_mfma_f32_16x16x32_bf16 v[124:127], v[4:7], v[186:189], v[64:67]
	v_mfma_f32_16x16x32_bf16 v[64:67], v[8:11], v[12:15], v[116:119]
	v_mfma_f32_16x16x32_bf16 v[72:75], v[32:35], v[214:217], v[0:3]
	v_mfma_f32_16x16x32_bf16 v[0:3], v[8:11], v[218:221], v[80:83]
	v_mfma_f32_16x16x32_bf16 v[112:115], v[32:35], v[16:19], v[64:67]
	v_mfma_f32_16x16x32_bf16 v[64:67], v[8:11], v[182:185], v[226:229]
	v_mfma_f32_16x16x32_bf16 v[92:95], v[32:35], v[234:237], v[0:3]
	v_mfma_f32_16x16x32_bf16 v[0:3], v[36:39], v[206:209], v[76:79]
	v_mfma_f32_16x16x32_bf16 v[116:119], v[32:35], v[186:189], v[64:67]
	v_mfma_f32_16x16x32_bf16 v[64:67], v[36:39], v[12:15], v[108:111]
	v_mfma_f32_16x16x32_bf16 v[76:79], v[238:241], v[214:217], v[0:3]
	v_mfma_f32_16x16x32_bf16 v[0:3], v[36:39], v[218:221], v[194:197]
	v_mfma_f32_16x16x32_bf16 v[104:107], v[238:241], v[16:19], v[64:67]
	v_mfma_f32_16x16x32_bf16 v[64:67], v[36:39], v[182:185], v[230:233]
	v_mfma_f32_16x16x32_bf16 v[96:99], v[238:241], v[234:237], v[0:3]
	v_mfma_f32_16x16x32_bf16 v[0:3], v[242:245], v[206:209], v[198:201]
	v_mfma_f32_16x16x32_bf16 v[108:111], v[238:241], v[186:189], v[64:67]
	v_mfma_f32_16x16x32_bf16 v[64:67], v[242:245], v[12:15], v[100:103]
	v_mfma_f32_16x16x32_bf16 v[80:83], v[246:249], v[214:217], v[0:3]
	v_mfma_f32_16x16x32_bf16 v[0:3], v[242:245], v[218:221], v[202:205]
	v_mfma_f32_16x16x32_bf16 v[64:67], v[246:249], v[16:19], v[64:67]
	v_mfma_f32_16x16x32_bf16 v[68:71], v[4:7], v[214:217], v[68:71]
	v_mfma_f32_16x16x32_bf16 v[100:103], v[246:249], v[234:237], v[0:3]
	s_setprio 0
	s_barrier
	ds_read_b128 v[190:193], v150 offset:49152
	ds_read_b128 v[194:197], v150 offset:50176
	ds_read_b128 v[198:201], v150 offset:51200
	ds_read_b128 v[202:205], v150 offset:52224
	ds_read_b128 v[222:225], v150 offset:53248
	ds_read_b128 v[226:229], v150 offset:54272
	ds_read_b128 v[230:233], v150 offset:55296
	ds_read_b128 v[238:241], v150 offset:56320
	s_waitcnt lgkmcnt(0)
	s_barrier
	s_setprio 1
	s_waitcnt lgkmcnt(0)
	v_mfma_f32_16x16x32_bf16 v[4:7], v[190:193], v[182:185], v[56:59]
	v_mfma_f32_16x16x32_bf16 v[8:11], v[198:201], v[182:185], v[48:51]
	v_mfma_f32_16x16x32_bf16 v[0:3], v[190:193], v[12:15], v[60:63]
	v_mfma_f32_16x16x32_bf16 v[32:35], v[194:197], v[186:189], v[4:7]
	v_mfma_f32_16x16x32_bf16 v[4:7], v[198:201], v[12:15], v[52:55]
	v_mfma_f32_16x16x32_bf16 v[36:39], v[202:205], v[186:189], v[8:11]
	v_mfma_f32_16x16x32_bf16 v[8:11], v[222:225], v[12:15], v[44:47]
	v_mfma_f32_16x16x32_bf16 v[12:15], v[230:233], v[12:15], v[138:141]
	v_mfma_f32_16x16x32_bf16 v[0:3], v[194:197], v[16:19], v[0:3]
	v_mfma_f32_16x16x32_bf16 v[4:7], v[202:205], v[16:19], v[4:7]
	v_mfma_f32_16x16x32_bf16 v[8:11], v[226:229], v[16:19], v[8:11]
	v_mfma_f32_16x16x32_bf16 v[12:15], v[238:241], v[16:19], v[12:15]
	v_mfma_f32_16x16x32_bf16 v[16:19], v[230:233], v[182:185], v[142:145]
	v_mfma_f32_16x16x32_bf16 v[24:27], v[190:193], v[218:221], v[24:27]
	v_mfma_f32_16x16x32_bf16 v[44:47], v[238:241], v[186:189], v[16:19]
	v_mfma_f32_16x16x32_bf16 v[16:19], v[190:193], v[206:209], v[28:31]
	v_mfma_f32_16x16x32_bf16 v[48:51], v[194:197], v[234:237], v[24:27]
	v_mfma_f32_16x16x32_bf16 v[24:27], v[198:201], v[218:221], v[146:149]
	v_mfma_f32_16x16x32_bf16 v[28:31], v[222:225], v[218:221], v[210:213]
	v_mfma_f32_16x16x32_bf16 v[40:43], v[222:225], v[182:185], v[40:43]
	v_mfma_f32_16x16x32_bf16 v[20:23], v[198:201], v[206:209], v[20:23]
	v_mfma_f32_16x16x32_bf16 v[52:55], v[202:205], v[234:237], v[24:27]
	v_mfma_f32_16x16x32_bf16 v[24:27], v[222:225], v[206:209], v[170:173]
	v_mfma_f32_16x16x32_bf16 v[56:59], v[226:229], v[234:237], v[28:31]
	v_mfma_f32_16x16x32_bf16 v[28:31], v[230:233], v[206:209], v[174:177]
	v_mfma_f32_16x16x32_bf16 v[60:63], v[230:233], v[218:221], v[178:181]
	v_mfma_f32_16x16x32_bf16 v[40:43], v[226:229], v[186:189], v[40:43]
	v_mfma_f32_16x16x32_bf16 v[16:19], v[194:197], v[214:217], v[16:19]
	v_mfma_f32_16x16x32_bf16 v[20:23], v[202:205], v[214:217], v[20:23]
	v_mfma_f32_16x16x32_bf16 v[24:27], v[226:229], v[214:217], v[24:27]
	v_mfma_f32_16x16x32_bf16 v[28:31], v[238:241], v[214:217], v[28:31]
	v_mfma_f32_16x16x32_bf16 v[60:63], v[238:241], v[234:237], v[60:63]
	s_setprio 0
	s_barrier
	s_and_saveexec_b64 s[60:61], s[6:7]
	s_cbranch_execz .LBB0_851
	s_barrier
